# acc-chained MFMA order (same accumulator back-to-back, k inner) in the big GEMM loops (P1,P5,P6,P8,P9); structure unchanged
# speedup vs baseline: 1.0606x; 1.0042x over previous
; #define PG8_STAGE(bufoff, gbase, voff) do { _Pragma("unroll") for (int _i = 0; _i < 2; ++_i) \
;         __builtin_amdgcn_global_load_lds((const unsigned*)((const char*)(gbase) + (voff)[_i]), (PG8_LAS unsigned*)(lds + (bufoff) + ldsw + _i * 8192), 16, 0, 0); } while (0)
; #define PG8_LDA(dst, b, h) do { _Pragma("unroll") for (int m = 0; m < 4; ++m) _Pragma("unroll") for (int k = 0; k < 2; ++k) dst[m][k] = *(const PG8_LAS bf16x8*)(lds + PG8_SA(b, h) + aoff + m * 2048 + k * 1024); } while (0)
; #define PG8_LDB(dst, b, h) do { _Pragma("unroll") for (int n = 0; n < 2; ++n) _Pragma("unroll") for (int k = 0; k < 2; ++k) dst[n][k] = *(const PG8_LAS bf16x8*)(lds + PG8_SB(b, h) + boff + n * 2048 + k * 1024); } while (0)
; #define PG8_MMA(ai, bj, At, Bt) do { __builtin_amdgcn_s_setprio(1); _Pragma("unroll") for (int m = 0; m < 4; ++m) _Pragma("unroll") for (int n = 0; n < 2; ++n) _Pragma("unroll") for (int k = 0; k < 2; ++k) \
;         acc[ai][bj][m][n] = __builtin_amdgcn_mfma_f32_16x16x32_bf16(Bt[n][k], At[m][k], acc[ai][bj][m][n], 0, 0, 0); __builtin_amdgcn_s_setprio(0); } while (0)
; #define PG8_WAIT_V(n) asm volatile("s_waitcnt vmcnt(" #n ")" ::: "memory")
; template <class Epi, class Sched, bool ALIGN_EPI>
; __device__ __forceinline__ void gemm_phase(PG8_LAS unsigned char* lds, const Gemm g, const Sched& S, const Epi& E) {
;     ...
;             PG8_LDB(B0, 0, 0); PG8_LDB(B1, 0, 1); PG8_SCHED; PG8_LDA(At, 0, 0); PG8_STAGE(PG8_SA(1, 1), a1 + hstepA, voffA);
;             PG8_WAIT_V(8); PG8_WAIT_L(0); PG8_BAR; PG8_MMA(0, 0, At, B0); PG8_MMA(0, 1, At, B1); PG8_BAR; PG8_SCHED;
;             PG8_LDA(At, 0, 1); PG8_STAGE(PG8_SB(0, 0), b2, voffB); PG8_STAGE(PG8_SB(0, 1), b2 + hstepB, voffB); PG8_STAGE(PG8_SA(0, 0), a2, voffA);
;             PG8_WAIT_V(8); PG8_WAIT_L(0); PG8_BAR; PG8_MMA(1, 0, At, B0); PG8_MMA(1, 1, At, B1); PG8_BAR; PG8_SCHED;
;             PG8_LDB(B0, 1, 0); PG8_LDB(B1, 1, 1); PG8_SCHED; PG8_LDA(At, 1, 0); PG8_STAGE(PG8_SA(0, 1), a2 + hstepA, voffA);
;             PG8_WAIT_V(8); PG8_WAIT_L(0); PG8_BAR; PG8_MMA(0, 0, At, B0); PG8_MMA(0, 1, At, B1); PG8_BAR; PG8_SCHED;
;             PG8_LDA(At, 1, 1); PG8_STAGE(PG8_SB(1, 0), b3, voffB); PG8_STAGE(PG8_SB(1, 1), b3 + hstepB, voffB); PG8_STAGE(PG8_SA(1, 0), a3, voffA);
;             PG8_WAIT_V(8); PG8_WAIT_L(0); PG8_BAR; PG8_MMA(1, 0, At, B0); PG8_MMA(1, 1, At, B1); PG8_BAR; PG8_SCHED;
.LBB0_403:
	ds_read_b128 v[152:155], v166
	ds_read_b128 v[172:175], v166 offset:1024
	ds_read_b128 v[176:179], v166 offset:2048
	ds_read_b128 v[180:183], v166 offset:3072
	ds_read_b128 v[184:187], v167
	ds_read_b128 v[188:191], v167 offset:1024
	ds_read_b128 v[192:195], v167 offset:2048
	ds_read_b128 v[196:199], v167 offset:3072
	s_add_u32 s23, s24, 0xfff80080
	s_addc_u32 s26, s25, -1
	s_cmp_eq_u32 s17, 28
	s_cselect_b32 s29, s19, s26
	s_cselect_b32 s28, s18, s23
	s_cselect_b32 s27, s21, s15
	s_cselect_b32 s26, s20, s5
	v_lshl_add_u64 v[156:157], s[24:25], 0, v[140:141]
	s_add_i32 m0, s34, 0xc000
	ds_read_b128 v[200:203], v168
	ds_read_b128 v[204:207], v168 offset:1024
	ds_read_b128 v[208:211], v168 offset:2048
	ds_read_b128 v[212:215], v168 offset:3072
	ds_read_b128 v[216:219], v168 offset:4096
	ds_read_b128 v[220:223], v168 offset:5120
	ds_read_b128 v[224:227], v168 offset:6144
	ds_read_b128 v[228:231], v168 offset:7168
	global_load_lds_dwordx4 v[156:157], off
	v_lshl_add_u64 v[156:157], s[24:25], 0, v[142:143]
	s_add_i32 m0, s34, 0xe000
	s_nop 0
	global_load_lds_dwordx4 v[156:157], off
	s_waitcnt vmcnt(8)
	s_waitcnt lgkmcnt(0)
	s_barrier
	s_setprio 1
	s_waitcnt lgkmcnt(0)
	v_mfma_f32_16x16x32_bf16 v[126:129], v[152:155], v[200:203], v[126:129]
	v_mfma_f32_16x16x32_bf16 v[126:129], v[172:175], v[204:207], v[126:129]
	v_mfma_f32_16x16x32_bf16 v[122:125], v[176:179], v[200:203], v[122:125]
	v_mfma_f32_16x16x32_bf16 v[122:125], v[180:183], v[204:207], v[122:125]
	v_mfma_f32_16x16x32_bf16 v[110:113], v[152:155], v[208:211], v[110:113]
	v_mfma_f32_16x16x32_bf16 v[110:113], v[172:175], v[212:215], v[110:113]
	v_mfma_f32_16x16x32_bf16 v[106:109], v[176:179], v[208:211], v[106:109]
	v_mfma_f32_16x16x32_bf16 v[106:109], v[180:183], v[212:215], v[106:109]
	v_mfma_f32_16x16x32_bf16 v[94:97], v[152:155], v[216:219], v[94:97]
	v_mfma_f32_16x16x32_bf16 v[94:97], v[172:175], v[220:223], v[94:97]
	v_mfma_f32_16x16x32_bf16 v[90:93], v[176:179], v[216:219], v[90:93]
	v_mfma_f32_16x16x32_bf16 v[90:93], v[180:183], v[220:223], v[90:93]
	v_mfma_f32_16x16x32_bf16 v[78:81], v[152:155], v[224:227], v[78:81]
	v_mfma_f32_16x16x32_bf16 v[78:81], v[172:175], v[228:231], v[78:81]
	v_mfma_f32_16x16x32_bf16 v[74:77], v[176:179], v[224:227], v[74:77]
	v_mfma_f32_16x16x32_bf16 v[74:77], v[180:183], v[228:231], v[74:77]
	s_setprio 0
	s_setprio 1
	v_mfma_f32_16x16x32_bf16 v[118:121], v[184:187], v[200:203], v[118:121]
	v_mfma_f32_16x16x32_bf16 v[118:121], v[188:191], v[204:207], v[118:121]
	v_mfma_f32_16x16x32_bf16 v[114:117], v[192:195], v[200:203], v[114:117]
	v_mfma_f32_16x16x32_bf16 v[114:117], v[196:199], v[204:207], v[114:117]
	v_mfma_f32_16x16x32_bf16 v[102:105], v[184:187], v[208:211], v[102:105]
	v_mfma_f32_16x16x32_bf16 v[102:105], v[188:191], v[212:215], v[102:105]
	v_mfma_f32_16x16x32_bf16 v[98:101], v[192:195], v[208:211], v[98:101]
	v_mfma_f32_16x16x32_bf16 v[98:101], v[196:199], v[212:215], v[98:101]
	v_mfma_f32_16x16x32_bf16 v[86:89], v[184:187], v[216:219], v[86:89]
	v_mfma_f32_16x16x32_bf16 v[86:89], v[188:191], v[220:223], v[86:89]
	v_mfma_f32_16x16x32_bf16 v[82:85], v[192:195], v[216:219], v[82:85]
	v_mfma_f32_16x16x32_bf16 v[82:85], v[196:199], v[220:223], v[82:85]
	v_mfma_f32_16x16x32_bf16 v[70:73], v[184:187], v[224:227], v[70:73]
	v_mfma_f32_16x16x32_bf16 v[70:73], v[188:191], v[228:231], v[70:73]
	v_mfma_f32_16x16x32_bf16 v[66:69], v[192:195], v[224:227], v[66:69]
	v_mfma_f32_16x16x32_bf16 v[66:69], v[196:199], v[228:231], v[66:69]
	s_setprio 0
	s_barrier
	s_add_i32 s23, s45, s3
	v_lshl_add_u64 v[156:157], s[26:27], 0, v[134:135]
	s_mov_b32 m0, s23
	ds_read_b128 v[200:203], v168 offset:16384
	ds_read_b128 v[204:207], v168 offset:17408
	ds_read_b128 v[208:211], v168 offset:18432
	ds_read_b128 v[212:215], v168 offset:19456
	ds_read_b128 v[216:219], v168 offset:20480
	ds_read_b128 v[220:223], v168 offset:21504
	ds_read_b128 v[224:227], v168 offset:22528
	ds_read_b128 v[228:231], v168 offset:23552
	global_load_lds_dwordx4 v[156:157], off
	s_add_i32 m0, s23, 0x2000
	s_add_u32 s48, s26, 0x80000
	v_lshl_add_u64 v[232:233], s[26:27], 0, v[130:131]
	s_addc_u32 s49, s27, 0
	s_add_i32 s23, s46, s3
	global_load_lds_dwordx4 v[232:233], off
	v_lshl_add_u64 v[234:235], s[48:49], 0, v[134:135]
	s_mov_b32 m0, s23
	v_lshl_add_u64 v[236:237], s[28:29], 0, v[132:133]
	global_load_lds_dwordx4 v[234:235], off
	v_lshl_add_u64 v[234:235], s[48:49], 0, v[130:131]
	s_add_i32 m0, s23, 0x2000
	s_nop 0
	global_load_lds_dwordx4 v[234:235], off
	v_lshl_add_u64 v[234:235], s[28:29], 0, v[136:137]
	s_mov_b32 m0, s34
	s_nop 0
	global_load_lds_dwordx4 v[234:235], off
	s_mov_b32 m0, s35
	s_nop 0
	global_load_lds_dwordx4 v[236:237], off
	s_waitcnt vmcnt(8)
	s_waitcnt lgkmcnt(0)
	s_barrier
; #define PG8_STAGE(bufoff, gbase, voff) do { _Pragma("unroll") for (int _i = 0; _i < 2; ++_i) \
;         __builtin_amdgcn_global_load_lds((const unsigned*)((const char*)(gbase) + (voff)[_i]), (PG8_LAS unsigned*)(lds + (bufoff) + ldsw + _i * 8192), 16, 0, 0); } while (0)
; #define PG8_LDA(dst, b, h) do { _Pragma("unroll") for (int m = 0; m < 4; ++m) _Pragma("unroll") for (int k = 0; k < 2; ++k) dst[m][k] = *(const PG8_LAS bf16x8*)(lds + PG8_SA(b, h) + aoff + m * 2048 + k * 1024); } while (0)
; #define PG8_LDB(dst, b, h) do { _Pragma("unroll") for (int n = 0; n < 2; ++n) _Pragma("unroll") for (int k = 0; k < 2; ++k) dst[n][k] = *(const PG8_LAS bf16x8*)(lds + PG8_SB(b, h) + boff + n * 2048 + k * 1024); } while (0)
; #define PG8_MMA(ai, bj, At, Bt) do { __builtin_amdgcn_s_setprio(1); _Pragma("unroll") for (int m = 0; m < 4; ++m) _Pragma("unroll") for (int n = 0; n < 2; ++n) _Pragma("unroll") for (int k = 0; k < 2; ++k) \
;         acc[ai][bj][m][n] = __builtin_amdgcn_mfma_f32_16x16x32_bf16(Bt[n][k], At[m][k], acc[ai][bj][m][n], 0, 0, 0); __builtin_amdgcn_s_setprio(0); } while (0)
; #define PG8_WAIT_V(n) asm volatile("s_waitcnt vmcnt(" #n ")" ::: "memory")
; template <class Epi, class Sched, bool ALIGN_EPI>
; __device__ __forceinline__ void gemm_phase(PG8_LAS unsigned char* lds, const Gemm g, const Sched& S, const Epi& E) {
;     ...
;             PG8_LDB(B0, 0, 0); PG8_LDB(B1, 0, 1); PG8_SCHED; PG8_LDA(At, 0, 0); PG8_STAGE(PG8_SA(1, 1), a1 + hstepA, voffA);
;             PG8_WAIT_V(8); PG8_WAIT_L(0); PG8_BAR; PG8_MMA(0, 0, At, B0); PG8_MMA(0, 1, At, B1); PG8_BAR; PG8_SCHED;
;             PG8_LDA(At, 0, 1); PG8_STAGE(PG8_SB(0, 0), b2, voffB); PG8_STAGE(PG8_SB(0, 1), b2 + hstepB, voffB); PG8_STAGE(PG8_SA(0, 0), a2, voffA);
;             PG8_WAIT_V(8); PG8_WAIT_L(0); PG8_BAR; PG8_MMA(1, 0, At, B0); PG8_MMA(1, 1, At, B1); PG8_BAR; PG8_SCHED;
;             PG8_LDB(B0, 1, 0); PG8_LDB(B1, 1, 1); PG8_SCHED; PG8_LDA(At, 1, 0); PG8_STAGE(PG8_SA(0, 1), a2 + hstepA, voffA);
;             PG8_WAIT_V(8); PG8_WAIT_L(0); PG8_BAR; PG8_MMA(0, 0, At, B0); PG8_MMA(0, 1, At, B1); PG8_BAR; PG8_SCHED;
;             PG8_LDA(At, 1, 1); PG8_STAGE(PG8_SB(1, 0), b3, voffB); PG8_STAGE(PG8_SB(1, 1), b3 + hstepB, voffB); PG8_STAGE(PG8_SA(1, 0), a3, voffA);
;             PG8_WAIT_V(8); PG8_WAIT_L(0); PG8_BAR; PG8_MMA(1, 0, At, B0); PG8_MMA(1, 1, At, B1); PG8_BAR; PG8_SCHED;
	s_setprio 1
	s_waitcnt lgkmcnt(0)
	v_mfma_f32_16x16x32_bf16 v[62:65], v[152:155], v[200:203], v[62:65]
	v_mfma_f32_16x16x32_bf16 v[62:65], v[172:175], v[204:207], v[62:65]
	v_mfma_f32_16x16x32_bf16 v[58:61], v[176:179], v[200:203], v[58:61]
	v_mfma_f32_16x16x32_bf16 v[58:61], v[180:183], v[204:207], v[58:61]
	v_mfma_f32_16x16x32_bf16 v[46:49], v[152:155], v[208:211], v[46:49]
	v_mfma_f32_16x16x32_bf16 v[46:49], v[172:175], v[212:215], v[46:49]
	v_mfma_f32_16x16x32_bf16 v[42:45], v[176:179], v[208:211], v[42:45]
	v_mfma_f32_16x16x32_bf16 v[42:45], v[180:183], v[212:215], v[42:45]
	v_mfma_f32_16x16x32_bf16 v[30:33], v[152:155], v[216:219], v[30:33]
	v_mfma_f32_16x16x32_bf16 v[30:33], v[172:175], v[220:223], v[30:33]
	v_mfma_f32_16x16x32_bf16 v[26:29], v[176:179], v[216:219], v[26:29]
	v_mfma_f32_16x16x32_bf16 v[26:29], v[180:183], v[220:223], v[26:29]
	v_mfma_f32_16x16x32_bf16 v[14:17], v[152:155], v[224:227], v[14:17]
	v_mfma_f32_16x16x32_bf16 v[14:17], v[172:175], v[228:231], v[14:17]
	v_mfma_f32_16x16x32_bf16 v[10:13], v[176:179], v[224:227], v[10:13]
	v_mfma_f32_16x16x32_bf16 v[10:13], v[180:183], v[228:231], v[10:13]
	s_setprio 0
	s_setprio 1
	v_mfma_f32_16x16x32_bf16 v[54:57], v[184:187], v[200:203], v[54:57]
	v_mfma_f32_16x16x32_bf16 v[54:57], v[188:191], v[204:207], v[54:57]
	v_mfma_f32_16x16x32_bf16 v[50:53], v[192:195], v[200:203], v[50:53]
	v_mfma_f32_16x16x32_bf16 v[50:53], v[196:199], v[204:207], v[50:53]
	v_mfma_f32_16x16x32_bf16 v[38:41], v[184:187], v[208:211], v[38:41]
	v_mfma_f32_16x16x32_bf16 v[38:41], v[188:191], v[212:215], v[38:41]
	v_mfma_f32_16x16x32_bf16 v[34:37], v[192:195], v[208:211], v[34:37]
	v_mfma_f32_16x16x32_bf16 v[34:37], v[196:199], v[212:215], v[34:37]
	v_mfma_f32_16x16x32_bf16 v[22:25], v[184:187], v[216:219], v[22:25]
	v_mfma_f32_16x16x32_bf16 v[22:25], v[188:191], v[220:223], v[22:25]
	v_mfma_f32_16x16x32_bf16 v[18:21], v[192:195], v[216:219], v[18:21]
	v_mfma_f32_16x16x32_bf16 v[18:21], v[196:199], v[220:223], v[18:21]
	v_mfma_f32_16x16x32_bf16 v[6:9], v[184:187], v[224:227], v[6:9]
	v_mfma_f32_16x16x32_bf16 v[6:9], v[188:191], v[228:231], v[6:9]
	v_mfma_f32_16x16x32_bf16 v[2:5], v[192:195], v[224:227], v[2:5]
	v_mfma_f32_16x16x32_bf16 v[2:5], v[196:199], v[228:231], v[2:5]
	s_setprio 0
	s_barrier
	s_add_i32 s23, 0, 0x18000
	v_add_u32_e32 v149, s23, v159
	s_add_i32 s48, 0, 0x1c000
	ds_read_b128 v[152:155], v149
	ds_read_b128 v[172:175], v149 offset:1024
	ds_read_b128 v[176:179], v149 offset:2048
	ds_read_b128 v[180:183], v149 offset:3072
	v_add_u32_e32 v149, s48, v159
	ds_read_b128 v[184:187], v149
	ds_read_b128 v[188:191], v149 offset:1024
	ds_read_b128 v[192:195], v149 offset:2048
	ds_read_b128 v[196:199], v149 offset:3072
	s_add_u32 s28, s28, 0x80000
	s_addc_u32 s29, s29, 0
	s_mov_b32 m0, s36
	v_lshl_add_u64 v[238:239], s[28:29], 0, v[136:137]
	ds_read_b128 v[200:203], v168 offset:32768
	ds_read_b128 v[204:207], v168 offset:33792
	ds_read_b128 v[208:211], v168 offset:34816
	ds_read_b128 v[212:215], v168 offset:35840
	ds_read_b128 v[216:219], v168 offset:36864
	ds_read_b128 v[220:223], v168 offset:37888
	ds_read_b128 v[224:227], v168 offset:38912
	ds_read_b128 v[228:231], v168 offset:39936
	global_load_lds_dwordx4 v[238:239], off
	v_lshl_add_u64 v[238:239], s[28:29], 0, v[132:133]
	s_mov_b32 m0, s37
	s_nop 0
	global_load_lds_dwordx4 v[238:239], off
	s_waitcnt vmcnt(8)
	s_waitcnt lgkmcnt(0)
	s_barrier
	s_setprio 1
	s_waitcnt lgkmcnt(0)
	v_mfma_f32_16x16x32_bf16 v[126:129], v[152:155], v[200:203], v[126:129]
	v_mfma_f32_16x16x32_bf16 v[126:129], v[172:175], v[204:207], v[126:129]
	v_mfma_f32_16x16x32_bf16 v[122:125], v[176:179], v[200:203], v[122:125]
	v_mfma_f32_16x16x32_bf16 v[122:125], v[180:183], v[204:207], v[122:125]
	v_mfma_f32_16x16x32_bf16 v[110:113], v[152:155], v[208:211], v[110:113]
	v_mfma_f32_16x16x32_bf16 v[110:113], v[172:175], v[212:215], v[110:113]
	v_mfma_f32_16x16x32_bf16 v[106:109], v[176:179], v[208:211], v[106:109]
	v_mfma_f32_16x16x32_bf16 v[106:109], v[180:183], v[212:215], v[106:109]
	v_mfma_f32_16x16x32_bf16 v[94:97], v[152:155], v[216:219], v[94:97]
	v_mfma_f32_16x16x32_bf16 v[94:97], v[172:175], v[220:223], v[94:97]
	v_mfma_f32_16x16x32_bf16 v[90:93], v[176:179], v[216:219], v[90:93]
	v_mfma_f32_16x16x32_bf16 v[90:93], v[180:183], v[220:223], v[90:93]
	v_mfma_f32_16x16x32_bf16 v[78:81], v[152:155], v[224:227], v[78:81]
	v_mfma_f32_16x16x32_bf16 v[78:81], v[172:175], v[228:231], v[78:81]
	v_mfma_f32_16x16x32_bf16 v[74:77], v[176:179], v[224:227], v[74:77]
	v_mfma_f32_16x16x32_bf16 v[74:77], v[180:183], v[228:231], v[74:77]
	s_setprio 0
	s_setprio 1
	v_mfma_f32_16x16x32_bf16 v[118:121], v[184:187], v[200:203], v[118:121]
	v_mfma_f32_16x16x32_bf16 v[118:121], v[188:191], v[204:207], v[118:121]
	v_mfma_f32_16x16x32_bf16 v[114:117], v[192:195], v[200:203], v[114:117]
	v_mfma_f32_16x16x32_bf16 v[114:117], v[196:199], v[204:207], v[114:117]
	v_mfma_f32_16x16x32_bf16 v[102:105], v[184:187], v[208:211], v[102:105]
	v_mfma_f32_16x16x32_bf16 v[102:105], v[188:191], v[212:215], v[102:105]
	v_mfma_f32_16x16x32_bf16 v[98:101], v[192:195], v[208:211], v[98:101]
	v_mfma_f32_16x16x32_bf16 v[98:101], v[196:199], v[212:215], v[98:101]
	v_mfma_f32_16x16x32_bf16 v[86:89], v[184:187], v[216:219], v[86:89]
	v_mfma_f32_16x16x32_bf16 v[86:89], v[188:191], v[220:223], v[86:89]
	v_mfma_f32_16x16x32_bf16 v[82:85], v[192:195], v[216:219], v[82:85]
	v_mfma_f32_16x16x32_bf16 v[82:85], v[196:199], v[220:223], v[82:85]
	v_mfma_f32_16x16x32_bf16 v[70:73], v[184:187], v[224:227], v[70:73]
	v_mfma_f32_16x16x32_bf16 v[70:73], v[188:191], v[228:231], v[70:73]
	v_mfma_f32_16x16x32_bf16 v[66:69], v[192:195], v[224:227], v[66:69]
	v_mfma_f32_16x16x32_bf16 v[66:69], v[196:199], v[228:231], v[66:69]
	s_setprio 0
	s_barrier
; #define PG8_STAGE(bufoff, gbase, voff) do { _Pragma("unroll") for (int _i = 0; _i < 2; ++_i) \
;         __builtin_amdgcn_global_load_lds((const unsigned*)((const char*)(gbase) + (voff)[_i]), (PG8_LAS unsigned*)(lds + (bufoff) + ldsw + _i * 8192), 16, 0, 0); } while (0)
; #define PG8_LDA(dst, b, h) do { _Pragma("unroll") for (int m = 0; m < 4; ++m) _Pragma("unroll") for (int k = 0; k < 2; ++k) dst[m][k] = *(const PG8_LAS bf16x8*)(lds + PG8_SA(b, h) + aoff + m * 2048 + k * 1024); } while (0)
; #define PG8_LDB(dst, b, h) do { _Pragma("unroll") for (int n = 0; n < 2; ++n) _Pragma("unroll") for (int k = 0; k < 2; ++k) dst[n][k] = *(const PG8_LAS bf16x8*)(lds + PG8_SB(b, h) + boff + n * 2048 + k * 1024); } while (0)
; #define PG8_MMA(ai, bj, At, Bt) do { __builtin_amdgcn_s_setprio(1); _Pragma("unroll") for (int m = 0; m < 4; ++m) _Pragma("unroll") for (int n = 0; n < 2; ++n) _Pragma("unroll") for (int k = 0; k < 2; ++k) \
;         acc[ai][bj][m][n] = __builtin_amdgcn_mfma_f32_16x16x32_bf16(Bt[n][k], At[m][k], acc[ai][bj][m][n], 0, 0, 0); __builtin_amdgcn_s_setprio(0); } while (0)
; #define PG8_WAIT_V(n) asm volatile("s_waitcnt vmcnt(" #n ")" ::: "memory")
; template <class Epi, class Sched, bool ALIGN_EPI>
; __device__ __forceinline__ void gemm_phase(PG8_LAS unsigned char* lds, const Gemm g, const Sched& S, const Epi& E) {
;     ...
;             PG8_LDB(B0, 0, 0); PG8_LDB(B1, 0, 1); PG8_SCHED; PG8_LDA(At, 0, 0); PG8_STAGE(PG8_SA(1, 1), a1 + hstepA, voffA);
;             PG8_WAIT_V(8); PG8_WAIT_L(0); PG8_BAR; PG8_MMA(0, 0, At, B0); PG8_MMA(0, 1, At, B1); PG8_BAR; PG8_SCHED;
;             PG8_LDA(At, 0, 1); PG8_STAGE(PG8_SB(0, 0), b2, voffB); PG8_STAGE(PG8_SB(0, 1), b2 + hstepB, voffB); PG8_STAGE(PG8_SA(0, 0), a2, voffA);
;             PG8_WAIT_V(8); PG8_WAIT_L(0); PG8_BAR; PG8_MMA(1, 0, At, B0); PG8_MMA(1, 1, At, B1); PG8_BAR; PG8_SCHED;
;             PG8_LDB(B0, 1, 0); PG8_LDB(B1, 1, 1); PG8_SCHED; PG8_LDA(At, 1, 0); PG8_STAGE(PG8_SA(0, 1), a2 + hstepA, voffA);
;             PG8_WAIT_V(8); PG8_WAIT_L(0); PG8_BAR; PG8_MMA(0, 0, At, B0); PG8_MMA(0, 1, At, B1); PG8_BAR; PG8_SCHED;
;             PG8_LDA(At, 1, 1); PG8_STAGE(PG8_SB(1, 0), b3, voffB); PG8_STAGE(PG8_SB(1, 1), b3 + hstepB, voffB); PG8_STAGE(PG8_SA(1, 0), a3, voffA);
;             PG8_WAIT_V(8); PG8_WAIT_L(0); PG8_BAR; PG8_MMA(1, 0, At, B0); PG8_MMA(1, 1, At, B1); PG8_BAR; PG8_SCHED;
	s_add_i32 s23, s23, s3
	v_lshl_add_u64 v[156:157], v[156:157], 0, s[8:9]
	s_mov_b32 m0, s23
	ds_read_b128 v[200:203], v168 offset:49152
	ds_read_b128 v[204:207], v168 offset:50176
	ds_read_b128 v[208:211], v168 offset:51200
	ds_read_b128 v[212:215], v168 offset:52224
	ds_read_b128 v[216:219], v168 offset:53248
	ds_read_b128 v[220:223], v168 offset:54272
	ds_read_b128 v[224:227], v168 offset:55296
	ds_read_b128 v[228:231], v168 offset:56320
	global_load_lds_dwordx4 v[156:157], off
	s_add_i32 m0, s23, 0x2000
	s_add_u32 s26, s26, 0x80080
	v_lshl_add_u64 v[156:157], v[232:233], 0, s[8:9]
	s_addc_u32 s27, s27, 0
	s_add_i32 s23, s48, s3
	global_load_lds_dwordx4 v[156:157], off
	v_lshl_add_u64 v[156:157], s[26:27], 0, v[134:135]
	s_mov_b32 m0, s23
	s_nop 0
	global_load_lds_dwordx4 v[156:157], off
	v_lshl_add_u64 v[156:157], s[26:27], 0, v[130:131]
	s_add_i32 m0, s23, 0x2000
	s_nop 0
	global_load_lds_dwordx4 v[156:157], off
	v_lshl_add_u64 v[156:157], v[234:235], 0, s[8:9]
	s_mov_b32 m0, s42
	s_nop 0
	global_load_lds_dwordx4 v[156:157], off
	v_lshl_add_u64 v[156:157], v[236:237], 0, s[8:9]
	s_mov_b32 m0, s43
	s_nop 0
	global_load_lds_dwordx4 v[156:157], off
	s_waitcnt vmcnt(8)
	s_waitcnt lgkmcnt(0)
	s_barrier
	s_setprio 1
	s_waitcnt lgkmcnt(0)
	v_mfma_f32_16x16x32_bf16 v[62:65], v[152:155], v[200:203], v[62:65]
	v_mfma_f32_16x16x32_bf16 v[62:65], v[172:175], v[204:207], v[62:65]
	v_mfma_f32_16x16x32_bf16 v[58:61], v[176:179], v[200:203], v[58:61]
	v_mfma_f32_16x16x32_bf16 v[58:61], v[180:183], v[204:207], v[58:61]
	v_mfma_f32_16x16x32_bf16 v[46:49], v[152:155], v[208:211], v[46:49]
	v_mfma_f32_16x16x32_bf16 v[46:49], v[172:175], v[212:215], v[46:49]
	v_mfma_f32_16x16x32_bf16 v[42:45], v[176:179], v[208:211], v[42:45]
	v_mfma_f32_16x16x32_bf16 v[42:45], v[180:183], v[212:215], v[42:45]
	v_mfma_f32_16x16x32_bf16 v[30:33], v[152:155], v[216:219], v[30:33]
	v_mfma_f32_16x16x32_bf16 v[30:33], v[172:175], v[220:223], v[30:33]
	v_mfma_f32_16x16x32_bf16 v[26:29], v[176:179], v[216:219], v[26:29]
	v_mfma_f32_16x16x32_bf16 v[26:29], v[180:183], v[220:223], v[26:29]
	v_mfma_f32_16x16x32_bf16 v[14:17], v[152:155], v[224:227], v[14:17]
	v_mfma_f32_16x16x32_bf16 v[14:17], v[172:175], v[228:231], v[14:17]
	v_mfma_f32_16x16x32_bf16 v[10:13], v[176:179], v[224:227], v[10:13]
	v_mfma_f32_16x16x32_bf16 v[10:13], v[180:183], v[228:231], v[10:13]
	s_setprio 0
	s_setprio 1
	v_mfma_f32_16x16x32_bf16 v[54:57], v[184:187], v[200:203], v[54:57]
	v_mfma_f32_16x16x32_bf16 v[54:57], v[188:191], v[204:207], v[54:57]
	v_mfma_f32_16x16x32_bf16 v[50:53], v[192:195], v[200:203], v[50:53]
	v_mfma_f32_16x16x32_bf16 v[50:53], v[196:199], v[204:207], v[50:53]
	v_mfma_f32_16x16x32_bf16 v[38:41], v[184:187], v[208:211], v[38:41]
	v_mfma_f32_16x16x32_bf16 v[38:41], v[188:191], v[212:215], v[38:41]
	v_mfma_f32_16x16x32_bf16 v[34:37], v[192:195], v[208:211], v[34:37]
	v_mfma_f32_16x16x32_bf16 v[34:37], v[196:199], v[212:215], v[34:37]
	v_mfma_f32_16x16x32_bf16 v[22:25], v[184:187], v[216:219], v[22:25]
	v_mfma_f32_16x16x32_bf16 v[22:25], v[188:191], v[220:223], v[22:25]
	v_mfma_f32_16x16x32_bf16 v[18:21], v[192:195], v[216:219], v[18:21]
	v_mfma_f32_16x16x32_bf16 v[18:21], v[196:199], v[220:223], v[18:21]
	v_mfma_f32_16x16x32_bf16 v[6:9], v[184:187], v[224:227], v[6:9]
	v_mfma_f32_16x16x32_bf16 v[6:9], v[188:191], v[228:231], v[6:9]
	v_mfma_f32_16x16x32_bf16 v[2:5], v[192:195], v[224:227], v[2:5]
	v_mfma_f32_16x16x32_bf16 v[2:5], v[196:199], v[228:231], v[2:5]
	s_setprio 0
	s_barrier
	s_add_i32 s17, s17, 2
	s_add_u32 s24, s24, 0x100
	s_addc_u32 s25, s25, 0
	s_add_u32 s5, s5, 0x100
	s_addc_u32 s15, s15, 0
	s_cmp_gt_u32 s17, 29
	s_cbranch_scc0 .LBB0_403
	s_and_b64 vcc, exec, s[10:11]
	s_cbranch_vccz .LBB0_406
	s_barrier

; #define PG8_STAGE(bufoff, gbase, voff) do { _Pragma("unroll") for (int _i = 0; _i < 2; ++_i) \
;         __builtin_amdgcn_global_load_lds((const unsigned*)((const char*)(gbase) + (voff)[_i]), (PG8_LAS unsigned*)(lds + (bufoff) + ldsw + _i * 8192), 16, 0, 0); } while (0)
; #define PG8_LDA(dst, b, h) do { _Pragma("unroll") for (int m = 0; m < 4; ++m) _Pragma("unroll") for (int k = 0; k < 2; ++k) dst[m][k] = *(const PG8_LAS bf16x8*)(lds + PG8_SA(b, h) + aoff + m * 2048 + k * 1024); } while (0)
; #define PG8_LDB(dst, b, h) do { _Pragma("unroll") for (int n = 0; n < 2; ++n) _Pragma("unroll") for (int k = 0; k < 2; ++k) dst[n][k] = *(const PG8_LAS bf16x8*)(lds + PG8_SB(b, h) + boff + n * 2048 + k * 1024); } while (0)
; #define PG8_MMA(ai, bj, At, Bt) do { __builtin_amdgcn_s_setprio(1); _Pragma("unroll") for (int m = 0; m < 4; ++m) _Pragma("unroll") for (int n = 0; n < 2; ++n) _Pragma("unroll") for (int k = 0; k < 2; ++k) \
;         acc[ai][bj][m][n] = __builtin_amdgcn_mfma_f32_16x16x32_bf16(Bt[n][k], At[m][k], acc[ai][bj][m][n], 0, 0, 0); __builtin_amdgcn_s_setprio(0); } while (0)
; #define PG8_WAIT_V(n) asm volatile("s_waitcnt vmcnt(" #n ")" ::: "memory")
; #define PG8_WAIT_L(n) asm volatile("s_waitcnt lgkmcnt(" #n ")" ::: "memory")
; #define PG8_BAR __builtin_amdgcn_s_barrier()
; #define PG8_SCHED __builtin_amdgcn_sched_barrier(0)
; template <class Epi, class Sched, bool ALIGN_EPI>
; __device__ __forceinline__ void gemm_phase(PG8_LAS unsigned char* lds, const Gemm g, const Sched& S, const Epi& E) {
;     ...
;             const bool last = (t == nt - 2);
;             const char* a1 = cA + (size_t)(t + 1) * kstepA;
;             const char* a2 = last ? nA : cA + (size_t)(t + 2) * kstepA; const char* b2 = last ? nB : cB + (size_t)(t + 2) * kstep;
;             const char* a3 = a2 + kstepA; const char* b3 = b2 + kstep;
;             PG8_LDB(B0, 0, 0); PG8_LDB(B1, 0, 1); PG8_SCHED; PG8_LDA(At, 0, 0); PG8_STAGE(PG8_SA(1, 1), a1 + hstepA, voffA);
;             PG8_WAIT_V(8); PG8_WAIT_L(0); PG8_BAR; PG8_MMA(0, 0, At, B0); PG8_MMA(0, 1, At, B1); PG8_BAR; PG8_SCHED;
;             PG8_LDA(At, 0, 1); PG8_STAGE(PG8_SB(0, 0), b2, voffB); PG8_STAGE(PG8_SB(0, 1), b2 + hstepB, voffB); PG8_STAGE(PG8_SA(0, 0), a2, voffA);
;             PG8_WAIT_V(8); PG8_WAIT_L(0); PG8_BAR; PG8_MMA(1, 0, At, B0); PG8_MMA(1, 1, At, B1); PG8_BAR; PG8_SCHED;
.LBB0_431:
	ds_read_b128 v[150:153], v147
	ds_read_b128 v[154:157], v147 offset:1024
	ds_read_b128 v[158:161], v147 offset:2048
	ds_read_b128 v[162:165], v147 offset:3072
	ds_read_b128 v[166:169], v148
	ds_read_b128 v[170:173], v148 offset:1024
	ds_read_b128 v[174:177], v148 offset:2048
	ds_read_b128 v[178:181], v148 offset:3072
	s_add_u32 s34, s30, 0xfff80080
	s_addc_u32 s35, s31, -1
	s_cmp_eq_u32 s54, 28
	s_cselect_b32 s37, s25, s35
	s_cselect_b32 s36, s24, s34
	s_cselect_b32 s35, s27, s23
	s_cselect_b32 s34, s26, s21
	v_lshl_add_u64 v[142:143], s[30:31], 0, v[138:139]
	s_add_i32 m0, s29, 0xc000
	ds_read_b128 v[182:185], v149
	ds_read_b128 v[186:189], v149 offset:1024
	ds_read_b128 v[190:193], v149 offset:2048
	ds_read_b128 v[194:197], v149 offset:3072
	ds_read_b128 v[198:201], v149 offset:4096
	ds_read_b128 v[202:205], v149 offset:5120
	ds_read_b128 v[206:209], v149 offset:6144
	ds_read_b128 v[210:213], v149 offset:7168
	global_load_lds_dwordx4 v[142:143], off
	v_lshl_add_u64 v[142:143], s[30:31], 0, v[140:141]
	s_add_i32 m0, s29, 0xe000
	s_nop 0
	global_load_lds_dwordx4 v[142:143], off
	s_waitcnt vmcnt(8)
	s_waitcnt lgkmcnt(0)
	s_barrier
	s_setprio 1
	s_waitcnt lgkmcnt(0)
	v_mfma_f32_16x16x32_bf16 v[126:129], v[150:153], v[182:185], v[126:129]
	v_mfma_f32_16x16x32_bf16 v[126:129], v[154:157], v[186:189], v[126:129]
	v_mfma_f32_16x16x32_bf16 v[122:125], v[158:161], v[182:185], v[122:125]
	v_mfma_f32_16x16x32_bf16 v[122:125], v[162:165], v[186:189], v[122:125]
	v_mfma_f32_16x16x32_bf16 v[118:121], v[150:153], v[190:193], v[118:121]
	v_mfma_f32_16x16x32_bf16 v[118:121], v[154:157], v[194:197], v[118:121]
	v_mfma_f32_16x16x32_bf16 v[110:113], v[158:161], v[190:193], v[110:113]
	v_mfma_f32_16x16x32_bf16 v[110:113], v[162:165], v[194:197], v[110:113]
	v_mfma_f32_16x16x32_bf16 v[102:105], v[150:153], v[198:201], v[102:105]
	v_mfma_f32_16x16x32_bf16 v[102:105], v[154:157], v[202:205], v[102:105]
	v_mfma_f32_16x16x32_bf16 v[94:97], v[158:161], v[198:201], v[94:97]
	v_mfma_f32_16x16x32_bf16 v[94:97], v[162:165], v[202:205], v[94:97]
	v_mfma_f32_16x16x32_bf16 v[86:89], v[150:153], v[206:209], v[86:89]
	v_mfma_f32_16x16x32_bf16 v[86:89], v[154:157], v[210:213], v[86:89]
	v_mfma_f32_16x16x32_bf16 v[78:81], v[158:161], v[206:209], v[78:81]
	v_mfma_f32_16x16x32_bf16 v[78:81], v[162:165], v[210:213], v[78:81]
	s_setprio 0
	s_setprio 1
	v_mfma_f32_16x16x32_bf16 v[114:117], v[166:169], v[182:185], v[114:117]
	v_mfma_f32_16x16x32_bf16 v[114:117], v[170:173], v[186:189], v[114:117]
	v_mfma_f32_16x16x32_bf16 v[106:109], v[174:177], v[182:185], v[106:109]
	v_mfma_f32_16x16x32_bf16 v[106:109], v[178:181], v[186:189], v[106:109]
	v_mfma_f32_16x16x32_bf16 v[98:101], v[166:169], v[190:193], v[98:101]
	v_mfma_f32_16x16x32_bf16 v[98:101], v[170:173], v[194:197], v[98:101]
	v_mfma_f32_16x16x32_bf16 v[90:93], v[174:177], v[190:193], v[90:93]
	v_mfma_f32_16x16x32_bf16 v[90:93], v[178:181], v[194:197], v[90:93]
	v_mfma_f32_16x16x32_bf16 v[82:85], v[166:169], v[198:201], v[82:85]
	v_mfma_f32_16x16x32_bf16 v[82:85], v[170:173], v[202:205], v[82:85]
	v_mfma_f32_16x16x32_bf16 v[74:77], v[174:177], v[198:201], v[74:77]
	v_mfma_f32_16x16x32_bf16 v[74:77], v[178:181], v[202:205], v[74:77]
	v_mfma_f32_16x16x32_bf16 v[70:73], v[166:169], v[206:209], v[70:73]
	v_mfma_f32_16x16x32_bf16 v[70:73], v[170:173], v[210:213], v[70:73]
	v_mfma_f32_16x16x32_bf16 v[66:69], v[174:177], v[206:209], v[66:69]
	v_mfma_f32_16x16x32_bf16 v[66:69], v[178:181], v[210:213], v[66:69]
	s_setprio 0
	s_barrier
	s_add_i32 s55, s47, s39
	v_lshl_add_u64 v[142:143], s[34:35], 0, v[132:133]
	s_mov_b32 m0, s55
	ds_read_b128 v[182:185], v149 offset:16384
	ds_read_b128 v[186:189], v149 offset:17408
	ds_read_b128 v[190:193], v149 offset:18432
	ds_read_b128 v[194:197], v149 offset:19456
	ds_read_b128 v[198:201], v149 offset:20480
	ds_read_b128 v[202:205], v149 offset:21504
	ds_read_b128 v[206:209], v149 offset:22528
	ds_read_b128 v[210:213], v149 offset:23552
	global_load_lds_dwordx4 v[142:143], off
	s_add_i32 m0, s55, 0x2000
	s_add_u32 s56, s34, 0x80000
	v_lshl_add_u64 v[214:215], s[34:35], 0, v[136:137]
	s_addc_u32 s57, s35, 0
	s_add_i32 s55, s48, s39
	global_load_lds_dwordx4 v[214:215], off
	v_lshl_add_u64 v[216:217], s[56:57], 0, v[132:133]
	s_mov_b32 m0, s55
	v_lshl_add_u64 v[218:219], s[36:37], 0, v[134:135]
	global_load_lds_dwordx4 v[216:217], off
	v_lshl_add_u64 v[216:217], s[56:57], 0, v[136:137]
	s_add_i32 m0, s55, 0x2000
	s_nop 0
	global_load_lds_dwordx4 v[216:217], off
	v_lshl_add_u64 v[216:217], s[36:37], 0, v[130:131]
	s_mov_b32 m0, s29
	s_nop 0
	global_load_lds_dwordx4 v[216:217], off
	s_mov_b32 m0, s40
	s_nop 0
	global_load_lds_dwordx4 v[218:219], off
	s_waitcnt vmcnt(8)
	s_waitcnt lgkmcnt(0)
	s_barrier
; #define PG8_STAGE(bufoff, gbase, voff) do { _Pragma("unroll") for (int _i = 0; _i < 2; ++_i) \
;         __builtin_amdgcn_global_load_lds((const unsigned*)((const char*)(gbase) + (voff)[_i]), (PG8_LAS unsigned*)(lds + (bufoff) + ldsw + _i * 8192), 16, 0, 0); } while (0)
; #define PG8_LDA(dst, b, h) do { _Pragma("unroll") for (int m = 0; m < 4; ++m) _Pragma("unroll") for (int k = 0; k < 2; ++k) dst[m][k] = *(const PG8_LAS bf16x8*)(lds + PG8_SA(b, h) + aoff + m * 2048 + k * 1024); } while (0)
; #define PG8_LDB(dst, b, h) do { _Pragma("unroll") for (int n = 0; n < 2; ++n) _Pragma("unroll") for (int k = 0; k < 2; ++k) dst[n][k] = *(const PG8_LAS bf16x8*)(lds + PG8_SB(b, h) + boff + n * 2048 + k * 1024); } while (0)
; #define PG8_MMA(ai, bj, At, Bt) do { __builtin_amdgcn_s_setprio(1); _Pragma("unroll") for (int m = 0; m < 4; ++m) _Pragma("unroll") for (int n = 0; n < 2; ++n) _Pragma("unroll") for (int k = 0; k < 2; ++k) \
;         acc[ai][bj][m][n] = __builtin_amdgcn_mfma_f32_16x16x32_bf16(Bt[n][k], At[m][k], acc[ai][bj][m][n], 0, 0, 0); __builtin_amdgcn_s_setprio(0); } while (0)
; #define PG8_WAIT_V(n) asm volatile("s_waitcnt vmcnt(" #n ")" ::: "memory")
; #define PG8_WAIT_L(n) asm volatile("s_waitcnt lgkmcnt(" #n ")" ::: "memory")
; #define PG8_BAR __builtin_amdgcn_s_barrier()
; #define PG8_SCHED __builtin_amdgcn_sched_barrier(0)
; template <class Epi, class Sched, bool ALIGN_EPI>
; __device__ __forceinline__ void gemm_phase(PG8_LAS unsigned char* lds, const Gemm g, const Sched& S, const Epi& E) {
;     ...
;             PG8_WAIT_V(8); PG8_WAIT_L(0); PG8_BAR; PG8_MMA(1, 0, At, B0); PG8_MMA(1, 1, At, B1); PG8_BAR; PG8_SCHED;
;             PG8_LDB(B0, 1, 0); PG8_LDB(B1, 1, 1); PG8_SCHED; PG8_LDA(At, 1, 0); PG8_STAGE(PG8_SA(0, 1), a2 + hstepA, voffA);
;             PG8_WAIT_V(8); PG8_WAIT_L(0); PG8_BAR; PG8_MMA(0, 0, At, B0); PG8_MMA(0, 1, At, B1); PG8_BAR; PG8_SCHED;
	s_setprio 1
	s_waitcnt lgkmcnt(0)
	v_mfma_f32_16x16x32_bf16 v[62:65], v[150:153], v[182:185], v[62:65]
	v_mfma_f32_16x16x32_bf16 v[62:65], v[154:157], v[186:189], v[62:65]
	v_mfma_f32_16x16x32_bf16 v[58:61], v[158:161], v[182:185], v[58:61]
	v_mfma_f32_16x16x32_bf16 v[58:61], v[162:165], v[186:189], v[58:61]
	v_mfma_f32_16x16x32_bf16 v[54:57], v[150:153], v[190:193], v[54:57]
	v_mfma_f32_16x16x32_bf16 v[54:57], v[154:157], v[194:197], v[54:57]
	v_mfma_f32_16x16x32_bf16 v[46:49], v[158:161], v[190:193], v[46:49]
	v_mfma_f32_16x16x32_bf16 v[46:49], v[162:165], v[194:197], v[46:49]
	v_mfma_f32_16x16x32_bf16 v[38:41], v[150:153], v[198:201], v[38:41]
	v_mfma_f32_16x16x32_bf16 v[38:41], v[154:157], v[202:205], v[38:41]
	v_mfma_f32_16x16x32_bf16 v[30:33], v[158:161], v[198:201], v[30:33]
	v_mfma_f32_16x16x32_bf16 v[30:33], v[162:165], v[202:205], v[30:33]
	v_mfma_f32_16x16x32_bf16 v[22:25], v[150:153], v[206:209], v[22:25]
	v_mfma_f32_16x16x32_bf16 v[22:25], v[154:157], v[210:213], v[22:25]
	v_mfma_f32_16x16x32_bf16 v[14:17], v[158:161], v[206:209], v[14:17]
	v_mfma_f32_16x16x32_bf16 v[14:17], v[162:165], v[210:213], v[14:17]
	s_setprio 0
	s_setprio 1
	v_mfma_f32_16x16x32_bf16 v[50:53], v[166:169], v[182:185], v[50:53]
	v_mfma_f32_16x16x32_bf16 v[50:53], v[170:173], v[186:189], v[50:53]
	v_mfma_f32_16x16x32_bf16 v[42:45], v[174:177], v[182:185], v[42:45]
	v_mfma_f32_16x16x32_bf16 v[42:45], v[178:181], v[186:189], v[42:45]
	v_mfma_f32_16x16x32_bf16 v[34:37], v[166:169], v[190:193], v[34:37]
	v_mfma_f32_16x16x32_bf16 v[34:37], v[170:173], v[194:197], v[34:37]
	v_mfma_f32_16x16x32_bf16 v[26:29], v[174:177], v[190:193], v[26:29]
	v_mfma_f32_16x16x32_bf16 v[26:29], v[178:181], v[194:197], v[26:29]
	v_mfma_f32_16x16x32_bf16 v[18:21], v[166:169], v[198:201], v[18:21]
	v_mfma_f32_16x16x32_bf16 v[18:21], v[170:173], v[202:205], v[18:21]
	v_mfma_f32_16x16x32_bf16 v[10:13], v[174:177], v[198:201], v[10:13]
	v_mfma_f32_16x16x32_bf16 v[10:13], v[178:181], v[202:205], v[10:13]
	v_mfma_f32_16x16x32_bf16 v[6:9], v[166:169], v[206:209], v[6:9]
	v_mfma_f32_16x16x32_bf16 v[6:9], v[170:173], v[210:213], v[6:9]
	v_mfma_f32_16x16x32_bf16 v[2:5], v[174:177], v[206:209], v[2:5]
	v_mfma_f32_16x16x32_bf16 v[2:5], v[178:181], v[210:213], v[2:5]
	s_setprio 0
	s_barrier
	s_add_i32 s55, 0, 0x18000
	s_add_i32 s56, 0, 0x1c000
	v_add_u32_e32 v162, s55, v145
	v_add_u32_e32 v178, s56, v145
	ds_read_b128 v[150:153], v162
	ds_read_b128 v[154:157], v162 offset:1024
	ds_read_b128 v[158:161], v162 offset:2048
	ds_read_b128 v[162:165], v162 offset:3072
	ds_read_b128 v[166:169], v178
	ds_read_b128 v[170:173], v178 offset:1024
	ds_read_b128 v[174:177], v178 offset:2048
	ds_read_b128 v[178:181], v178 offset:3072
	s_add_u32 s36, s36, 0x80000
	s_addc_u32 s37, s37, 0
	s_mov_b32 m0, s41
	v_lshl_add_u64 v[220:221], s[36:37], 0, v[130:131]
	ds_read_b128 v[182:185], v149 offset:32768
	ds_read_b128 v[186:189], v149 offset:33792
	ds_read_b128 v[190:193], v149 offset:34816
	ds_read_b128 v[194:197], v149 offset:35840
	ds_read_b128 v[198:201], v149 offset:36864
	ds_read_b128 v[202:205], v149 offset:37888
	ds_read_b128 v[206:209], v149 offset:38912
	ds_read_b128 v[210:213], v149 offset:39936
	global_load_lds_dwordx4 v[220:221], off
	v_lshl_add_u64 v[220:221], s[36:37], 0, v[134:135]
	s_mov_b32 m0, s42
	s_nop 0
	global_load_lds_dwordx4 v[220:221], off
	s_waitcnt vmcnt(8)
	s_waitcnt lgkmcnt(0)
	s_barrier
	s_setprio 1
	s_waitcnt lgkmcnt(0)
	v_mfma_f32_16x16x32_bf16 v[126:129], v[150:153], v[182:185], v[126:129]
	v_mfma_f32_16x16x32_bf16 v[126:129], v[154:157], v[186:189], v[126:129]
	v_mfma_f32_16x16x32_bf16 v[122:125], v[158:161], v[182:185], v[122:125]
	v_mfma_f32_16x16x32_bf16 v[122:125], v[162:165], v[186:189], v[122:125]
	v_mfma_f32_16x16x32_bf16 v[118:121], v[150:153], v[190:193], v[118:121]
	v_mfma_f32_16x16x32_bf16 v[118:121], v[154:157], v[194:197], v[118:121]
	v_mfma_f32_16x16x32_bf16 v[110:113], v[158:161], v[190:193], v[110:113]
	v_mfma_f32_16x16x32_bf16 v[110:113], v[162:165], v[194:197], v[110:113]
	v_mfma_f32_16x16x32_bf16 v[102:105], v[150:153], v[198:201], v[102:105]
	v_mfma_f32_16x16x32_bf16 v[102:105], v[154:157], v[202:205], v[102:105]
	v_mfma_f32_16x16x32_bf16 v[94:97], v[158:161], v[198:201], v[94:97]
	v_mfma_f32_16x16x32_bf16 v[94:97], v[162:165], v[202:205], v[94:97]
	v_mfma_f32_16x16x32_bf16 v[86:89], v[150:153], v[206:209], v[86:89]
	v_mfma_f32_16x16x32_bf16 v[86:89], v[154:157], v[210:213], v[86:89]
	v_mfma_f32_16x16x32_bf16 v[78:81], v[158:161], v[206:209], v[78:81]
	v_mfma_f32_16x16x32_bf16 v[78:81], v[162:165], v[210:213], v[78:81]
	s_setprio 0
	s_setprio 1
	v_mfma_f32_16x16x32_bf16 v[114:117], v[166:169], v[182:185], v[114:117]
	v_mfma_f32_16x16x32_bf16 v[114:117], v[170:173], v[186:189], v[114:117]
	v_mfma_f32_16x16x32_bf16 v[106:109], v[174:177], v[182:185], v[106:109]
	v_mfma_f32_16x16x32_bf16 v[106:109], v[178:181], v[186:189], v[106:109]
	v_mfma_f32_16x16x32_bf16 v[98:101], v[166:169], v[190:193], v[98:101]
	v_mfma_f32_16x16x32_bf16 v[98:101], v[170:173], v[194:197], v[98:101]
	v_mfma_f32_16x16x32_bf16 v[90:93], v[174:177], v[190:193], v[90:93]
	v_mfma_f32_16x16x32_bf16 v[90:93], v[178:181], v[194:197], v[90:93]
	v_mfma_f32_16x16x32_bf16 v[82:85], v[166:169], v[198:201], v[82:85]
	v_mfma_f32_16x16x32_bf16 v[82:85], v[170:173], v[202:205], v[82:85]
	v_mfma_f32_16x16x32_bf16 v[74:77], v[174:177], v[198:201], v[74:77]
	v_mfma_f32_16x16x32_bf16 v[74:77], v[178:181], v[202:205], v[74:77]
	v_mfma_f32_16x16x32_bf16 v[70:73], v[166:169], v[206:209], v[70:73]
	v_mfma_f32_16x16x32_bf16 v[70:73], v[170:173], v[210:213], v[70:73]
	v_mfma_f32_16x16x32_bf16 v[66:69], v[174:177], v[206:209], v[66:69]
	v_mfma_f32_16x16x32_bf16 v[66:69], v[178:181], v[210:213], v[66:69]
	s_setprio 0
	s_barrier
; #define PG8_STAGE(bufoff, gbase, voff) do { _Pragma("unroll") for (int _i = 0; _i < 2; ++_i) \
;         __builtin_amdgcn_global_load_lds((const unsigned*)((const char*)(gbase) + (voff)[_i]), (PG8_LAS unsigned*)(lds + (bufoff) + ldsw + _i * 8192), 16, 0, 0); } while (0)
; #define PG8_LDA(dst, b, h) do { _Pragma("unroll") for (int m = 0; m < 4; ++m) _Pragma("unroll") for (int k = 0; k < 2; ++k) dst[m][k] = *(const PG8_LAS bf16x8*)(lds + PG8_SA(b, h) + aoff + m * 2048 + k * 1024); } while (0)
; #define PG8_MMA(ai, bj, At, Bt) do { __builtin_amdgcn_s_setprio(1); _Pragma("unroll") for (int m = 0; m < 4; ++m) _Pragma("unroll") for (int n = 0; n < 2; ++n) _Pragma("unroll") for (int k = 0; k < 2; ++k) \
;         acc[ai][bj][m][n] = __builtin_amdgcn_mfma_f32_16x16x32_bf16(Bt[n][k], At[m][k], acc[ai][bj][m][n], 0, 0, 0); __builtin_amdgcn_s_setprio(0); } while (0)
; #define PG8_WAIT_V(n) asm volatile("s_waitcnt vmcnt(" #n ")" ::: "memory")
; #define PG8_WAIT_L(n) asm volatile("s_waitcnt lgkmcnt(" #n ")" ::: "memory")
; #define PG8_BAR __builtin_amdgcn_s_barrier()
; #define PG8_SCHED __builtin_amdgcn_sched_barrier(0)
; template <class Epi, class Sched, bool ALIGN_EPI>
; __device__ __forceinline__ void gemm_phase(PG8_LAS unsigned char* lds, const Gemm g, const Sched& S, const Epi& E) {
;     ...
;             PG8_LDA(At, 1, 1); PG8_STAGE(PG8_SB(1, 0), b3, voffB); PG8_STAGE(PG8_SB(1, 1), b3 + hstepB, voffB); PG8_STAGE(PG8_SA(1, 0), a3, voffA);
;             PG8_WAIT_V(8); PG8_WAIT_L(0); PG8_BAR; PG8_MMA(1, 0, At, B0); PG8_MMA(1, 1, At, B1); PG8_BAR; PG8_SCHED;
;         }
;         if constexpr (ALIGN_EPI) { if (wr == 0) PG8_BAR; }
	s_add_i32 s36, s55, s39
	v_lshl_add_u64 v[142:143], v[142:143], 0, s[8:9]
	s_mov_b32 m0, s36
	ds_read_b128 v[182:185], v149 offset:49152
	ds_read_b128 v[186:189], v149 offset:50176
	ds_read_b128 v[190:193], v149 offset:51200
	ds_read_b128 v[194:197], v149 offset:52224
	ds_read_b128 v[198:201], v149 offset:53248
	ds_read_b128 v[202:205], v149 offset:54272
	ds_read_b128 v[206:209], v149 offset:55296
	ds_read_b128 v[210:213], v149 offset:56320
	global_load_lds_dwordx4 v[142:143], off
	s_add_i32 m0, s36, 0x2000
	s_add_u32 s34, s34, 0x80080
	v_lshl_add_u64 v[142:143], v[214:215], 0, s[8:9]
	s_addc_u32 s35, s35, 0
	s_add_i32 s36, s56, s39
	global_load_lds_dwordx4 v[142:143], off
	v_lshl_add_u64 v[142:143], s[34:35], 0, v[132:133]
	s_mov_b32 m0, s36
	s_nop 0
	global_load_lds_dwordx4 v[142:143], off
	v_lshl_add_u64 v[142:143], s[34:35], 0, v[136:137]
	s_add_i32 m0, s36, 0x2000
	s_nop 0
	global_load_lds_dwordx4 v[142:143], off
	v_lshl_add_u64 v[142:143], v[216:217], 0, s[8:9]
	s_mov_b32 m0, s44
	s_nop 0
	global_load_lds_dwordx4 v[142:143], off
	v_lshl_add_u64 v[142:143], v[218:219], 0, s[8:9]
	s_mov_b32 m0, s45
	s_nop 0
	global_load_lds_dwordx4 v[142:143], off
	s_waitcnt vmcnt(8)
	s_waitcnt lgkmcnt(0)
	s_barrier
	s_setprio 1
	s_waitcnt lgkmcnt(0)
	v_mfma_f32_16x16x32_bf16 v[62:65], v[150:153], v[182:185], v[62:65]
	v_mfma_f32_16x16x32_bf16 v[62:65], v[154:157], v[186:189], v[62:65]
	v_mfma_f32_16x16x32_bf16 v[58:61], v[158:161], v[182:185], v[58:61]
	v_mfma_f32_16x16x32_bf16 v[58:61], v[162:165], v[186:189], v[58:61]
	v_mfma_f32_16x16x32_bf16 v[54:57], v[150:153], v[190:193], v[54:57]
	v_mfma_f32_16x16x32_bf16 v[54:57], v[154:157], v[194:197], v[54:57]
	v_mfma_f32_16x16x32_bf16 v[46:49], v[158:161], v[190:193], v[46:49]
	v_mfma_f32_16x16x32_bf16 v[46:49], v[162:165], v[194:197], v[46:49]
	v_mfma_f32_16x16x32_bf16 v[38:41], v[150:153], v[198:201], v[38:41]
	v_mfma_f32_16x16x32_bf16 v[38:41], v[154:157], v[202:205], v[38:41]
	v_mfma_f32_16x16x32_bf16 v[30:33], v[158:161], v[198:201], v[30:33]
	v_mfma_f32_16x16x32_bf16 v[30:33], v[162:165], v[202:205], v[30:33]
	v_mfma_f32_16x16x32_bf16 v[22:25], v[150:153], v[206:209], v[22:25]
	v_mfma_f32_16x16x32_bf16 v[22:25], v[154:157], v[210:213], v[22:25]
	v_mfma_f32_16x16x32_bf16 v[14:17], v[158:161], v[206:209], v[14:17]
	v_mfma_f32_16x16x32_bf16 v[14:17], v[162:165], v[210:213], v[14:17]
	s_setprio 0
	s_setprio 1
	v_mfma_f32_16x16x32_bf16 v[50:53], v[166:169], v[182:185], v[50:53]
	v_mfma_f32_16x16x32_bf16 v[50:53], v[170:173], v[186:189], v[50:53]
	v_mfma_f32_16x16x32_bf16 v[42:45], v[174:177], v[182:185], v[42:45]
	v_mfma_f32_16x16x32_bf16 v[42:45], v[178:181], v[186:189], v[42:45]
	v_mfma_f32_16x16x32_bf16 v[34:37], v[166:169], v[190:193], v[34:37]
	v_mfma_f32_16x16x32_bf16 v[34:37], v[170:173], v[194:197], v[34:37]
	v_mfma_f32_16x16x32_bf16 v[26:29], v[174:177], v[190:193], v[26:29]
	v_mfma_f32_16x16x32_bf16 v[26:29], v[178:181], v[194:197], v[26:29]
	v_mfma_f32_16x16x32_bf16 v[18:21], v[166:169], v[198:201], v[18:21]
	v_mfma_f32_16x16x32_bf16 v[18:21], v[170:173], v[202:205], v[18:21]
	v_mfma_f32_16x16x32_bf16 v[10:13], v[174:177], v[198:201], v[10:13]
	v_mfma_f32_16x16x32_bf16 v[10:13], v[178:181], v[202:205], v[10:13]
	v_mfma_f32_16x16x32_bf16 v[6:9], v[166:169], v[206:209], v[6:9]
	v_mfma_f32_16x16x32_bf16 v[6:9], v[170:173], v[210:213], v[6:9]
	v_mfma_f32_16x16x32_bf16 v[2:5], v[174:177], v[206:209], v[2:5]
	v_mfma_f32_16x16x32_bf16 v[2:5], v[178:181], v[210:213], v[2:5]
	s_setprio 0
	s_barrier
	s_add_i32 s54, s54, 2
	s_add_u32 s30, s30, 0x100
	s_addc_u32 s31, s31, 0
	s_add_u32 s21, s21, 0x100
	s_addc_u32 s23, s23, 0
	s_cmp_gt_u32 s54, 29
	s_cbranch_scc0 .LBB0_431
	s_and_b64 vcc, exec, s[10:11]
	s_cbranch_vccz .LBB0_434
	s_barrier

;     __host__ __device__ bool next(int i, Unit& u) const { const int L = i * G + c; if (L >= n) return false; u.pm = L; u.pn = L >> 2; return true; }
; #define PG8_STAGE(bufoff, gbase, voff) do { _Pragma("unroll") for (int _i = 0; _i < 2; ++_i) \
;         __builtin_amdgcn_global_load_lds((const unsigned*)((const char*)(gbase) + (voff)[_i]), (PG8_LAS unsigned*)(lds + (bufoff) + ldsw + _i * 8192), 16, 0, 0); } while (0)
; #define PG8_LDA(dst, b, h) do { _Pragma("unroll") for (int m = 0; m < 4; ++m) _Pragma("unroll") for (int k = 0; k < 2; ++k) dst[m][k] = *(const PG8_LAS bf16x8*)(lds + PG8_SA(b, h) + aoff + m * 2048 + k * 1024); } while (0)
; #define PG8_WAIT_V(n) asm volatile("s_waitcnt vmcnt(" #n ")" ::: "memory")
; #define PG8_WAIT_L(n) asm volatile("s_waitcnt lgkmcnt(" #n ")" ::: "memory")
; template <class Epi, class Sched, bool ALIGN_EPI>
; __device__ __forceinline__ void gemm_phase(PG8_LAS unsigned char* lds, const Gemm g, const Sched& S, const Epi& E) {
;     ...
;         const bool has_next = S.next(ui + 1, nxt);
;         const size_t tail_ = has_next ? 0 : tailoff; const char* nA = (has_next ? (const char*)g.A + (size_t)nxt.pm * tstepA : cA) + (has_next ? 0 : tailoffA); const char* nB = (has_next ? (const char*)g.Bt + (size_t)nxt.pn * tstepB : cB) + tail_;
;         for (int t = 0; t < nt; t += 2) {
;             if constexpr (Epi::MIDK) { if (t == (nt >> 1)) E.midk(acc, cur, wr, fr); }
;             const bool last = (t == nt - 2);
;             const char* a1 = cA + (size_t)(t + 1) * kstepA;
;             const char* a2 = last ? nA : cA + (size_t)(t + 2) * kstepA; const char* b2 = last ? nB : cB + (size_t)(t + 2) * kstep;
;             const char* a3 = a2 + kstepA; const char* b3 = b2 + kstep;
;             PG8_LDB(B0, 0, 0); PG8_LDB(B1, 0, 1); PG8_SCHED; PG8_LDA(At, 0, 0); PG8_STAGE(PG8_SA(1, 1), a1 + hstepA, voffA);
;             PG8_WAIT_V(8); PG8_WAIT_L(0); PG8_BAR; PG8_MMA(0, 0, At, B0); PG8_MMA(0, 1, At, B1); PG8_BAR; PG8_SCHED;
;             PG8_LDA(At, 0, 1); PG8_STAGE(PG8_SB(0, 0), b2, voffB); PG8_STAGE(PG8_SB(0, 1), b2 + hstepB, voffB); PG8_STAGE(PG8_SA(0, 0), a2, voffA);
;             PG8_WAIT_V(8); PG8_WAIT_L(0); PG8_BAR; PG8_MMA(1, 0, At, B0); PG8_MMA(1, 1, At, B1); PG8_BAR; PG8_SCHED;
;             PG8_LDB(B0, 1, 0); PG8_LDB(B1, 1, 1); PG8_SCHED; PG8_LDA(At, 1, 0); PG8_STAGE(PG8_SA(0, 1), a2 + hstepA, voffA);
.LBB0_628:
	s_ashr_i32 s54, s48, 2
	s_and_b64 s[56:57], s[24:25], exec
	s_cselect_b32 s56, s54, s55
	s_cselect_b32 s55, 0, 0x100
	s_add_u32 s20, s22, s20
	s_addc_u32 s21, s23, s21
	s_ashr_i32 s57, s56, 31
	s_lshl_b64 s[22:23], s[56:57], 17
	ds_read_b128 v[2:5], v79
	ds_read_b128 v[6:9], v79 offset:1024
	ds_read_b128 v[10:13], v79 offset:2048
	ds_read_b128 v[14:17], v79 offset:3072
	s_add_u32 s56, s31, s22
	s_addc_u32 s57, s34, s23
	s_and_b64 s[22:23], s[24:25], exec
	s_cselect_b32 s22, s56, s28
	s_cselect_b32 s23, s57, s29
	s_add_u32 s22, s22, s55
	s_addc_u32 s23, s23, 0
	s_add_u32 s56, s26, 0x18080
	s_addc_u32 s57, s27, 0
	s_mov_b32 m0, s47
	v_lshl_add_u64 v[50:51], s[56:57], 0, v[72:73]
	ds_read_b128 v[18:21], v80
	ds_read_b128 v[22:25], v80 offset:1024
	ds_read_b128 v[26:29], v80 offset:2048
	ds_read_b128 v[30:33], v80 offset:3072
	ds_read_b128 v[34:37], v80 offset:4096
	ds_read_b128 v[38:41], v80 offset:5120
	ds_read_b128 v[42:45], v80 offset:6144
	ds_read_b128 v[46:49], v80 offset:7168
	global_load_lds_dwordx4 v[50:51], off
	v_lshl_add_u64 v[50:51], s[56:57], 0, v[68:69]
	s_mov_b32 m0, s49
	s_nop 0
	global_load_lds_dwordx4 v[50:51], off
	s_waitcnt vmcnt(8)
	s_waitcnt lgkmcnt(0)
	s_barrier
	s_setprio 1
	s_waitcnt lgkmcnt(0)
	v_mfma_f32_16x16x32_bf16 v[50:53], v[2:5], v[18:21], 0
	v_mfma_f32_16x16x32_bf16 v[18:21], v[10:13], v[18:21], 0
	v_mfma_f32_16x16x32_bf16 v[50:53], v[6:9], v[22:25], v[50:53]
	v_mfma_f32_16x16x32_bf16 v[18:21], v[14:17], v[22:25], v[18:21]
	v_mfma_f32_16x16x32_bf16 v[22:25], v[2:5], v[26:29], 0
	v_mfma_f32_16x16x32_bf16 v[26:29], v[10:13], v[26:29], 0
	v_mfma_f32_16x16x32_bf16 v[22:25], v[6:9], v[30:33], v[22:25]
	v_mfma_f32_16x16x32_bf16 v[26:29], v[14:17], v[30:33], v[26:29]
	v_mfma_f32_16x16x32_bf16 v[30:33], v[2:5], v[34:37], 0
	v_mfma_f32_16x16x32_bf16 v[34:37], v[10:13], v[34:37], 0
	v_mfma_f32_16x16x32_bf16 v[30:33], v[6:9], v[38:41], v[30:33]
	v_mfma_f32_16x16x32_bf16 v[34:37], v[14:17], v[38:41], v[34:37]
	v_mfma_f32_16x16x32_bf16 v[38:41], v[2:5], v[42:45], 0
	v_mfma_f32_16x16x32_bf16 v[42:45], v[10:13], v[42:45], 0
	v_mfma_f32_16x16x32_bf16 v[38:41], v[6:9], v[46:49], v[38:41]
	v_mfma_f32_16x16x32_bf16 v[42:45], v[14:17], v[46:49], v[42:45]
	s_setprio 0
	s_setprio 1
	s_setprio 0
	s_barrier
	v_lshl_add_u64 v[130:131], s[28:29], 0, v[70:71]
	s_mov_b32 m0, s50
	v_lshl_add_u64 v[98:99], v[130:131], 0, s[16:17]
	v_lshl_add_u64 v[132:133], s[28:29], 0, v[66:67]
	s_add_u32 s56, s28, 0x10100
	ds_read_b128 v[46:49], v80 offset:16384
	ds_read_b128 v[54:57], v80 offset:17408
	ds_read_b128 v[58:61], v80 offset:18432
	ds_read_b128 v[62:65], v80 offset:19456
	ds_read_b128 v[82:85], v80 offset:20480
	ds_read_b128 v[86:89], v80 offset:21504
	ds_read_b128 v[90:93], v80 offset:22528
	ds_read_b128 v[94:97], v80 offset:23552
	global_load_lds_dwordx4 v[98:99], off
	v_lshl_add_u64 v[98:99], v[132:133], 0, s[16:17]
	s_mov_b32 m0, s51
	s_addc_u32 s57, s29, 0
	global_load_lds_dwordx4 v[98:99], off
	v_lshl_add_u64 v[98:99], s[56:57], 0, v[70:71]
	s_mov_b32 m0, s36
	v_lshl_add_u64 v[134:135], s[26:27], 0, v[72:73]
	global_load_lds_dwordx4 v[98:99], off
	v_lshl_add_u64 v[98:99], s[56:57], 0, v[66:67]
	s_mov_b32 m0, s37
	v_lshl_add_u64 v[136:137], s[26:27], 0, v[68:69]
	global_load_lds_dwordx4 v[98:99], off
	v_lshl_add_u64 v[98:99], v[134:135], 0, s[16:17]
	s_mov_b32 m0, s35
	s_nop 0
	global_load_lds_dwordx4 v[98:99], off
	v_lshl_add_u64 v[98:99], v[136:137], 0, s[16:17]
	s_mov_b32 m0, s39
	s_nop 0
	global_load_lds_dwordx4 v[98:99], off
	s_waitcnt vmcnt(8)
	s_waitcnt lgkmcnt(0)
	s_barrier
	s_setprio 1
	s_waitcnt lgkmcnt(0)
	v_mfma_f32_16x16x32_bf16 v[98:101], v[2:5], v[46:49], 0
	v_mfma_f32_16x16x32_bf16 v[46:49], v[10:13], v[46:49], 0
	v_mfma_f32_16x16x32_bf16 v[98:101], v[6:9], v[54:57], v[98:101]
	v_mfma_f32_16x16x32_bf16 v[46:49], v[14:17], v[54:57], v[46:49]
	v_mfma_f32_16x16x32_bf16 v[54:57], v[2:5], v[58:61], 0
	v_mfma_f32_16x16x32_bf16 v[58:61], v[10:13], v[58:61], 0
	v_mfma_f32_16x16x32_bf16 v[54:57], v[6:9], v[62:65], v[54:57]
	v_mfma_f32_16x16x32_bf16 v[58:61], v[14:17], v[62:65], v[58:61]
	v_mfma_f32_16x16x32_bf16 v[62:65], v[2:5], v[82:85], 0
	v_mfma_f32_16x16x32_bf16 v[2:5], v[2:5], v[90:93], 0
	v_mfma_f32_16x16x32_bf16 v[62:65], v[6:9], v[86:89], v[62:65]
	v_mfma_f32_16x16x32_bf16 v[2:5], v[6:9], v[94:97], v[2:5]
	v_mfma_f32_16x16x32_bf16 v[6:9], v[10:13], v[90:93], 0
	v_mfma_f32_16x16x32_bf16 v[82:85], v[10:13], v[82:85], 0
	v_mfma_f32_16x16x32_bf16 v[6:9], v[14:17], v[94:97], v[6:9]
	v_mfma_f32_16x16x32_bf16 v[82:85], v[14:17], v[86:89], v[82:85]
	s_setprio 0
	s_setprio 1
	s_setprio 0
	s_barrier
	ds_read_b128 v[10:13], v81
	ds_read_b128 v[14:17], v81 offset:1024
	ds_read_b128 v[86:89], v81 offset:2048
	ds_read_b128 v[90:93], v81 offset:3072
	s_add_u32 s56, s26, 0x18100
	s_addc_u32 s57, s27, 0
	s_mov_b32 m0, s40
	v_lshl_add_u64 v[138:139], s[56:57], 0, v[72:73]
	ds_read_b128 v[94:97], v80 offset:32768
	ds_read_b128 v[102:105], v80 offset:33792
	ds_read_b128 v[106:109], v80 offset:34816
	ds_read_b128 v[110:113], v80 offset:35840
	ds_read_b128 v[114:117], v80 offset:36864
	ds_read_b128 v[118:121], v80 offset:37888
	ds_read_b128 v[122:125], v80 offset:38912
	ds_read_b128 v[126:129], v80 offset:39936
	global_load_lds_dwordx4 v[138:139], off
	v_lshl_add_u64 v[138:139], s[56:57], 0, v[68:69]
	s_mov_b32 m0, s41
	s_nop 0
	global_load_lds_dwordx4 v[138:139], off
	s_waitcnt vmcnt(8)
	s_waitcnt lgkmcnt(0)
	s_barrier
; #define PG8_STAGE(bufoff, gbase, voff) do { _Pragma("unroll") for (int _i = 0; _i < 2; ++_i) \
;         __builtin_amdgcn_global_load_lds((const unsigned*)((const char*)(gbase) + (voff)[_i]), (PG8_LAS unsigned*)(lds + (bufoff) + ldsw + _i * 8192), 16, 0, 0); } while (0)
; #define PG8_LDA(dst, b, h) do { _Pragma("unroll") for (int m = 0; m < 4; ++m) _Pragma("unroll") for (int k = 0; k < 2; ++k) dst[m][k] = *(const PG8_LAS bf16x8*)(lds + PG8_SA(b, h) + aoff + m * 2048 + k * 1024); } while (0)
; #define PG8_LDB(dst, b, h) do { _Pragma("unroll") for (int n = 0; n < 2; ++n) _Pragma("unroll") for (int k = 0; k < 2; ++k) dst[n][k] = *(const PG8_LAS bf16x8*)(lds + PG8_SB(b, h) + boff + n * 2048 + k * 1024); } while (0)
; #define PG8_MMA(ai, bj, At, Bt) do { __builtin_amdgcn_s_setprio(1); _Pragma("unroll") for (int m = 0; m < 4; ++m) _Pragma("unroll") for (int n = 0; n < 2; ++n) _Pragma("unroll") for (int k = 0; k < 2; ++k) \
;         acc[ai][bj][m][n] = __builtin_amdgcn_mfma_f32_16x16x32_bf16(Bt[n][k], At[m][k], acc[ai][bj][m][n], 0, 0, 0); __builtin_amdgcn_s_setprio(0); } while (0)
; #define PG8_WAIT_V(n) asm volatile("s_waitcnt vmcnt(" #n ")" ::: "memory")
; #define PG8_WAIT_L(n) asm volatile("s_waitcnt lgkmcnt(" #n ")" ::: "memory")
; #define PG8_BAR __builtin_amdgcn_s_barrier()
; #define PG8_SCHED __builtin_amdgcn_sched_barrier(0)
; template <class Epi, class Sched, bool ALIGN_EPI>
; __device__ __forceinline__ void gemm_phase(PG8_LAS unsigned char* lds, const Gemm g, const Sched& S, const Epi& E) {
;     ...
;             PG8_LDB(B0, 0, 0); PG8_LDB(B1, 0, 1); PG8_SCHED; PG8_LDA(At, 0, 0); PG8_STAGE(PG8_SA(1, 1), a1 + hstepA, voffA);
;             PG8_WAIT_V(8); PG8_WAIT_L(0); PG8_BAR; PG8_MMA(0, 0, At, B0); PG8_MMA(0, 1, At, B1); PG8_BAR; PG8_SCHED;
;     ...
;             PG8_WAIT_V(8); PG8_WAIT_L(0); PG8_BAR; PG8_MMA(0, 0, At, B0); PG8_MMA(0, 1, At, B1); PG8_BAR; PG8_SCHED;
;             PG8_LDA(At, 1, 1); PG8_STAGE(PG8_SB(1, 0), b3, voffB); PG8_STAGE(PG8_SB(1, 1), b3 + hstepB, voffB); PG8_STAGE(PG8_SA(1, 0), a3, voffA);
;             PG8_WAIT_V(8); PG8_WAIT_L(0); PG8_BAR; PG8_MMA(1, 0, At, B0); PG8_MMA(1, 1, At, B1); PG8_BAR; PG8_SCHED;
	s_setprio 1
	s_waitcnt lgkmcnt(0)
	v_mfma_f32_16x16x32_bf16 v[50:53], v[10:13], v[94:97], v[50:53]
	v_mfma_f32_16x16x32_bf16 v[50:53], v[14:17], v[102:105], v[50:53]
	v_mfma_f32_16x16x32_bf16 v[18:21], v[86:89], v[94:97], v[18:21]
	v_mfma_f32_16x16x32_bf16 v[18:21], v[90:93], v[102:105], v[18:21]
	v_mfma_f32_16x16x32_bf16 v[22:25], v[10:13], v[106:109], v[22:25]
	v_mfma_f32_16x16x32_bf16 v[22:25], v[14:17], v[110:113], v[22:25]
	v_mfma_f32_16x16x32_bf16 v[26:29], v[86:89], v[106:109], v[26:29]
	v_mfma_f32_16x16x32_bf16 v[26:29], v[90:93], v[110:113], v[26:29]
	v_mfma_f32_16x16x32_bf16 v[30:33], v[10:13], v[114:117], v[30:33]
	v_mfma_f32_16x16x32_bf16 v[30:33], v[14:17], v[118:121], v[30:33]
	v_mfma_f32_16x16x32_bf16 v[34:37], v[86:89], v[114:117], v[34:37]
	v_mfma_f32_16x16x32_bf16 v[34:37], v[90:93], v[118:121], v[34:37]
	v_mfma_f32_16x16x32_bf16 v[38:41], v[10:13], v[122:125], v[38:41]
	v_mfma_f32_16x16x32_bf16 v[38:41], v[14:17], v[126:129], v[38:41]
	v_mfma_f32_16x16x32_bf16 v[42:45], v[86:89], v[122:125], v[42:45]
	v_mfma_f32_16x16x32_bf16 v[42:45], v[90:93], v[126:129], v[42:45]
	s_setprio 0
	s_setprio 1
	s_setprio 0
	s_barrier
	s_mov_b32 m0, s52
	v_lshl_add_u64 v[130:131], v[130:131], 0, s[18:19]
	s_add_u32 s28, s28, 0x10180
	ds_read_b128 v[94:97], v80 offset:49152
	ds_read_b128 v[102:105], v80 offset:50176
	ds_read_b128 v[106:109], v80 offset:51200
	ds_read_b128 v[110:113], v80 offset:52224
	ds_read_b128 v[114:117], v80 offset:53248
	ds_read_b128 v[118:121], v80 offset:54272
	ds_read_b128 v[122:125], v80 offset:55296
	ds_read_b128 v[126:129], v80 offset:56320
	global_load_lds_dwordx4 v[130:131], off
	v_lshl_add_u64 v[130:131], v[132:133], 0, s[18:19]
	s_mov_b32 m0, s53
	s_addc_u32 s29, s29, 0
	global_load_lds_dwordx4 v[130:131], off
	v_lshl_add_u64 v[130:131], s[28:29], 0, v[70:71]
	s_mov_b32 m0, s44
	s_nop 0
	global_load_lds_dwordx4 v[130:131], off
	v_lshl_add_u64 v[130:131], s[28:29], 0, v[66:67]
	s_mov_b32 m0, s45
	s_nop 0
	global_load_lds_dwordx4 v[130:131], off
	v_lshl_add_u64 v[130:131], v[134:135], 0, s[18:19]
	s_mov_b32 m0, s42
	s_nop 0
	global_load_lds_dwordx4 v[130:131], off
	v_lshl_add_u64 v[130:131], v[136:137], 0, s[18:19]
	s_mov_b32 m0, s43
	s_nop 0
	global_load_lds_dwordx4 v[130:131], off
	s_waitcnt vmcnt(8)
	s_waitcnt lgkmcnt(0)
	s_barrier
	s_setprio 1
	s_waitcnt lgkmcnt(0)
	v_mfma_f32_16x16x32_bf16 v[46:49], v[86:89], v[94:97], v[46:49]
	v_mfma_f32_16x16x32_bf16 v[46:49], v[90:93], v[102:105], v[46:49]
	v_mfma_f32_16x16x32_bf16 v[54:57], v[10:13], v[106:109], v[54:57]
	v_mfma_f32_16x16x32_bf16 v[54:57], v[14:17], v[110:113], v[54:57]
	v_mfma_f32_16x16x32_bf16 v[58:61], v[86:89], v[106:109], v[58:61]
	v_mfma_f32_16x16x32_bf16 v[58:61], v[90:93], v[110:113], v[58:61]
	v_mfma_f32_16x16x32_bf16 v[62:65], v[10:13], v[114:117], v[62:65]
	v_mfma_f32_16x16x32_bf16 v[62:65], v[14:17], v[118:121], v[62:65]
	v_mfma_f32_16x16x32_bf16 v[2:5], v[10:13], v[122:125], v[2:5]
	v_mfma_f32_16x16x32_bf16 v[2:5], v[14:17], v[126:129], v[2:5]
	v_mfma_f32_16x16x32_bf16 v[6:9], v[86:89], v[122:125], v[6:9]
	v_mfma_f32_16x16x32_bf16 v[6:9], v[90:93], v[126:129], v[6:9]
	v_mfma_f32_16x16x32_bf16 v[98:101], v[10:13], v[94:97], v[98:101]
	v_mfma_f32_16x16x32_bf16 v[98:101], v[14:17], v[102:105], v[98:101]
	v_mfma_f32_16x16x32_bf16 v[82:85], v[86:89], v[114:117], v[82:85]
	v_mfma_f32_16x16x32_bf16 v[82:85], v[90:93], v[118:121], v[82:85]
	s_setprio 0
	s_setprio 1
	s_setprio 0
	s_barrier
	ds_read_b128 v[10:13], v79
	ds_read_b128 v[14:17], v79 offset:1024
	ds_read_b128 v[86:89], v79 offset:2048
	ds_read_b128 v[90:93], v79 offset:3072
	s_add_u32 s26, s26, 0x18180
	s_addc_u32 s27, s27, 0
	s_mov_b32 m0, s47
	v_lshl_add_u64 v[130:131], s[26:27], 0, v[72:73]
	ds_read_b128 v[94:97], v80
	ds_read_b128 v[102:105], v80 offset:1024
	ds_read_b128 v[106:109], v80 offset:2048
	ds_read_b128 v[110:113], v80 offset:3072
	ds_read_b128 v[114:117], v80 offset:4096
	ds_read_b128 v[118:121], v80 offset:5120
	ds_read_b128 v[122:125], v80 offset:6144
	ds_read_b128 v[126:129], v80 offset:7168
	global_load_lds_dwordx4 v[130:131], off
	v_lshl_add_u64 v[130:131], s[26:27], 0, v[68:69]
	s_mov_b32 m0, s49
	s_nop 0
	global_load_lds_dwordx4 v[130:131], off
	s_waitcnt vmcnt(8)
	s_waitcnt lgkmcnt(0)
	s_barrier
	s_setprio 1
	s_waitcnt lgkmcnt(0)
	v_mfma_f32_16x16x32_bf16 v[26:29], v[86:89], v[106:109], v[26:29]
	v_mfma_f32_16x16x32_bf16 v[50:53], v[10:13], v[94:97], v[50:53]
	v_mfma_f32_16x16x32_bf16 v[18:21], v[86:89], v[94:97], v[18:21]
	v_mfma_f32_16x16x32_bf16 v[94:97], v[90:93], v[110:113], v[26:29]
	v_mfma_f32_16x16x32_bf16 v[26:29], v[10:13], v[114:117], v[30:33]
	v_mfma_f32_16x16x32_bf16 v[50:53], v[14:17], v[102:105], v[50:53]
	v_mfma_f32_16x16x32_bf16 v[18:21], v[90:93], v[102:105], v[18:21]
	v_mfma_f32_16x16x32_bf16 v[102:105], v[14:17], v[118:121], v[26:29]
	v_mfma_f32_16x16x32_bf16 v[26:29], v[86:89], v[114:117], v[34:37]
	v_mfma_f32_16x16x32_bf16 v[34:37], v[90:93], v[118:121], v[26:29]
	v_mfma_f32_16x16x32_bf16 v[26:29], v[10:13], v[122:125], v[38:41]
	v_mfma_f32_16x16x32_bf16 v[22:25], v[10:13], v[106:109], v[22:25]
	v_mfma_f32_16x16x32_bf16 v[38:41], v[14:17], v[126:129], v[26:29]
	v_mfma_f32_16x16x32_bf16 v[26:29], v[86:89], v[122:125], v[42:45]
	v_mfma_f32_16x16x32_bf16 v[22:25], v[14:17], v[110:113], v[22:25]
	v_mfma_f32_16x16x32_bf16 v[42:45], v[90:93], v[126:129], v[26:29]
	s_setprio 0
	s_setprio 1
	s_setprio 0
	s_barrier
; #define PG8_STAGE(bufoff, gbase, voff) do { _Pragma("unroll") for (int _i = 0; _i < 2; ++_i) \
;         __builtin_amdgcn_global_load_lds((const unsigned*)((const char*)(gbase) + (voff)[_i]), (PG8_LAS unsigned*)(lds + (bufoff) + ldsw + _i * 8192), 16, 0, 0); } while (0)
; #define PG8_LDA(dst, b, h) do { _Pragma("unroll") for (int m = 0; m < 4; ++m) _Pragma("unroll") for (int k = 0; k < 2; ++k) dst[m][k] = *(const PG8_LAS bf16x8*)(lds + PG8_SA(b, h) + aoff + m * 2048 + k * 1024); } while (0)
; #define PG8_LDB(dst, b, h) do { _Pragma("unroll") for (int n = 0; n < 2; ++n) _Pragma("unroll") for (int k = 0; k < 2; ++k) dst[n][k] = *(const PG8_LAS bf16x8*)(lds + PG8_SB(b, h) + boff + n * 2048 + k * 1024); } while (0)
; #define PG8_MMA(ai, bj, At, Bt) do { __builtin_amdgcn_s_setprio(1); _Pragma("unroll") for (int m = 0; m < 4; ++m) _Pragma("unroll") for (int n = 0; n < 2; ++n) _Pragma("unroll") for (int k = 0; k < 2; ++k) \
;         acc[ai][bj][m][n] = __builtin_amdgcn_mfma_f32_16x16x32_bf16(Bt[n][k], At[m][k], acc[ai][bj][m][n], 0, 0, 0); __builtin_amdgcn_s_setprio(0); } while (0)
; #define PG8_WAIT_V(n) asm volatile("s_waitcnt vmcnt(" #n ")" ::: "memory")
; #define PG8_WAIT_L(n) asm volatile("s_waitcnt lgkmcnt(" #n ")" ::: "memory")
; #define PG8_BAR __builtin_amdgcn_s_barrier()
; #define PG8_SCHED __builtin_amdgcn_sched_barrier(0)
; template <class Epi, class Sched, bool ALIGN_EPI>
; __device__ __forceinline__ void gemm_phase(PG8_LAS unsigned char* lds, const Gemm g, const Sched& S, const Epi& E) {
;     ...
;             PG8_LDA(At, 0, 1); PG8_STAGE(PG8_SB(0, 0), b2, voffB); PG8_STAGE(PG8_SB(0, 1), b2 + hstepB, voffB); PG8_STAGE(PG8_SA(0, 0), a2, voffA);
;             PG8_WAIT_V(8); PG8_WAIT_L(0); PG8_BAR; PG8_MMA(1, 0, At, B0); PG8_MMA(1, 1, At, B1); PG8_BAR; PG8_SCHED;
;             PG8_LDB(B0, 1, 0); PG8_LDB(B1, 1, 1); PG8_SCHED; PG8_LDA(At, 1, 0); PG8_STAGE(PG8_SA(0, 1), a2 + hstepA, voffA);
;             PG8_WAIT_V(8); PG8_WAIT_L(0); PG8_BAR; PG8_MMA(0, 0, At, B0); PG8_MMA(0, 1, At, B1); PG8_BAR; PG8_SCHED;
;             PG8_LDA(At, 1, 1); PG8_STAGE(PG8_SB(1, 0), b3, voffB); PG8_STAGE(PG8_SB(1, 1), b3 + hstepB, voffB); PG8_STAGE(PG8_SA(1, 0), a3, voffA);
;             PG8_WAIT_V(8); PG8_WAIT_L(0); PG8_BAR; PG8_MMA(1, 0, At, B0); PG8_MMA(1, 1, At, B1); PG8_BAR; PG8_SCHED;
;         }
;         if constexpr (ALIGN_EPI) { if (wr == 0) PG8_BAR; }
	s_mov_b32 m0, s50
	v_lshl_add_u64 v[142:143], s[22:23], 0, v[70:71]
	s_add_u32 s26, s22, 0x10000
	ds_read_b128 v[26:29], v80 offset:16384
	ds_read_b128 v[30:33], v80 offset:17408
	ds_read_b128 v[106:109], v80 offset:18432
	ds_read_b128 v[110:113], v80 offset:19456
	ds_read_b128 v[114:117], v80 offset:20480
	ds_read_b128 v[118:121], v80 offset:21504
	ds_read_b128 v[122:125], v80 offset:22528
	ds_read_b128 v[126:129], v80 offset:23552
	global_load_lds_dwordx4 v[142:143], off
	v_lshl_add_u64 v[144:145], s[22:23], 0, v[66:67]
	s_mov_b32 m0, s51
	s_addc_u32 s27, s23, 0
	global_load_lds_dwordx4 v[144:145], off
	v_lshl_add_u64 v[130:131], s[26:27], 0, v[70:71]
	s_mov_b32 m0, s36
	v_lshl_add_u64 v[146:147], s[20:21], 0, v[72:73]
	global_load_lds_dwordx4 v[130:131], off
	v_lshl_add_u64 v[130:131], s[26:27], 0, v[66:67]
	s_mov_b32 m0, s37
	v_lshl_add_u64 v[148:149], s[20:21], 0, v[68:69]
	global_load_lds_dwordx4 v[130:131], off
	s_mov_b32 m0, s35
	s_nop 0
	global_load_lds_dwordx4 v[146:147], off
	s_mov_b32 m0, s39
	s_nop 0
	global_load_lds_dwordx4 v[148:149], off
	s_waitcnt vmcnt(8)
	s_waitcnt lgkmcnt(0)
	s_barrier
	s_setprio 1
	s_waitcnt lgkmcnt(0)
	v_mfma_f32_16x16x32_bf16 v[98:101], v[10:13], v[26:29], v[98:101]
	v_mfma_f32_16x16x32_bf16 v[26:29], v[86:89], v[26:29], v[46:49]
	v_mfma_f32_16x16x32_bf16 v[46:49], v[90:93], v[30:33], v[26:29]
	v_mfma_f32_16x16x32_bf16 v[26:29], v[10:13], v[106:109], v[54:57]
	v_mfma_f32_16x16x32_bf16 v[54:57], v[14:17], v[110:113], v[26:29]
	v_mfma_f32_16x16x32_bf16 v[26:29], v[86:89], v[106:109], v[58:61]
	v_mfma_f32_16x16x32_bf16 v[106:109], v[90:93], v[110:113], v[26:29]
	v_mfma_f32_16x16x32_bf16 v[26:29], v[10:13], v[114:117], v[62:65]
	v_mfma_f32_16x16x32_bf16 v[2:5], v[10:13], v[122:125], v[2:5]
	v_mfma_f32_16x16x32_bf16 v[110:113], v[14:17], v[118:121], v[26:29]
	v_mfma_f32_16x16x32_bf16 v[26:29], v[86:89], v[114:117], v[82:85]
	v_mfma_f32_16x16x32_bf16 v[114:117], v[14:17], v[126:129], v[2:5]
	v_mfma_f32_16x16x32_bf16 v[2:5], v[86:89], v[122:125], v[6:9]
	v_mfma_f32_16x16x32_bf16 v[98:101], v[14:17], v[30:33], v[98:101]
	v_mfma_f32_16x16x32_bf16 v[82:85], v[90:93], v[118:121], v[26:29]
	v_mfma_f32_16x16x32_bf16 v[86:89], v[90:93], v[126:129], v[2:5]
	s_setprio 0
	s_setprio 1
	s_setprio 0
	s_barrier
	ds_read_b128 v[90:93], v81
	ds_read_b128 v[118:121], v81 offset:1024
	ds_read_b128 v[122:125], v81 offset:2048
	ds_read_b128 v[126:129], v81 offset:3072
	s_add_u32 s26, s20, 0x18000
	s_addc_u32 s27, s21, 0
	s_mov_b32 m0, s40
	v_lshl_add_u64 v[26:27], s[26:27], 0, v[72:73]
	ds_read_b128 v[2:5], v80 offset:32768
	ds_read_b128 v[6:9], v80 offset:33792
	ds_read_b128 v[10:13], v80 offset:34816
	ds_read_b128 v[14:17], v80 offset:35840
	ds_read_b128 v[58:61], v80 offset:36864
	ds_read_b128 v[62:65], v80 offset:37888
	ds_read_b128 v[130:133], v80 offset:38912
	ds_read_b128 v[134:137], v80 offset:39936
	global_load_lds_dwordx4 v[26:27], off
	v_lshl_add_u64 v[26:27], s[26:27], 0, v[68:69]
	s_mov_b32 m0, s41
	s_nop 0
	global_load_lds_dwordx4 v[26:27], off
	s_waitcnt vmcnt(8)
	s_waitcnt lgkmcnt(0)
	s_barrier
	s_setprio 1
	s_waitcnt lgkmcnt(0)
	v_mfma_f32_16x16x32_bf16 v[26:29], v[90:93], v[2:5], v[50:53]
	v_mfma_f32_16x16x32_bf16 v[2:5], v[122:125], v[2:5], v[18:21]
	v_mfma_f32_16x16x32_bf16 v[30:33], v[126:129], v[6:9], v[2:5]
	v_mfma_f32_16x16x32_bf16 v[2:5], v[90:93], v[10:13], v[22:25]
	v_mfma_f32_16x16x32_bf16 v[18:21], v[118:121], v[14:17], v[2:5]
	v_mfma_f32_16x16x32_bf16 v[2:5], v[122:125], v[10:13], v[94:97]
	v_mfma_f32_16x16x32_bf16 v[22:25], v[126:129], v[14:17], v[2:5]
	v_mfma_f32_16x16x32_bf16 v[2:5], v[90:93], v[58:61], v[102:105]
	v_mfma_f32_16x16x32_bf16 v[10:13], v[118:121], v[62:65], v[2:5]
	v_mfma_f32_16x16x32_bf16 v[2:5], v[122:125], v[58:61], v[34:37]
	v_mfma_f32_16x16x32_bf16 v[26:29], v[118:121], v[6:9], v[26:29]
	v_mfma_f32_16x16x32_bf16 v[14:17], v[126:129], v[62:65], v[2:5]
	v_mfma_f32_16x16x32_bf16 v[2:5], v[90:93], v[130:133], v[38:41]
	v_mfma_f32_16x16x32_bf16 v[6:9], v[122:125], v[130:133], v[42:45]
	v_mfma_f32_16x16x32_bf16 v[2:5], v[118:121], v[134:137], v[2:5]
	v_mfma_f32_16x16x32_bf16 v[6:9], v[126:129], v[134:137], v[6:9]
	s_setprio 0
	s_setprio 1
	s_setprio 0
	s_barrier
	s_mov_b32 m0, s52
	v_lshl_add_u64 v[50:51], v[142:143], 0, s[12:13]
	s_add_u32 s26, s22, 0x10080
	ds_read_b128 v[34:37], v80 offset:49152
	ds_read_b128 v[38:41], v80 offset:50176
	ds_read_b128 v[42:45], v80 offset:51200
	ds_read_b128 v[94:97], v80 offset:52224
	ds_read_b128 v[102:105], v80 offset:53248
	ds_read_b128 v[130:133], v80 offset:54272
	ds_read_b128 v[134:137], v80 offset:55296
	ds_read_b128 v[138:141], v80 offset:56320
	global_load_lds_dwordx4 v[50:51], off
	v_lshl_add_u64 v[50:51], v[144:145], 0, s[12:13]
	s_mov_b32 m0, s53
	s_addc_u32 s27, s23, 0
	global_load_lds_dwordx4 v[50:51], off
	v_lshl_add_u64 v[50:51], s[26:27], 0, v[70:71]
	s_mov_b32 m0, s44
	s_nop 0
	global_load_lds_dwordx4 v[50:51], off
	v_lshl_add_u64 v[50:51], s[26:27], 0, v[66:67]
	s_mov_b32 m0, s45
	s_nop 0
	global_load_lds_dwordx4 v[50:51], off
	v_lshl_add_u64 v[50:51], v[146:147], 0, s[12:13]
	s_mov_b32 m0, s42
	s_nop 0
	global_load_lds_dwordx4 v[50:51], off
	v_lshl_add_u64 v[50:51], v[148:149], 0, s[12:13]
	s_mov_b32 m0, s43
	s_nop 0
	global_load_lds_dwordx4 v[50:51], off
	s_waitcnt vmcnt(8)
	s_waitcnt lgkmcnt(0)
	s_barrier
	s_setprio 1
	s_waitcnt lgkmcnt(0)
	v_mfma_f32_16x16x32_bf16 v[50:53], v[90:93], v[34:37], v[98:101]
	v_mfma_f32_16x16x32_bf16 v[34:37], v[122:125], v[34:37], v[46:49]
	v_mfma_f32_16x16x32_bf16 v[62:65], v[126:129], v[38:41], v[34:37]
	v_mfma_f32_16x16x32_bf16 v[34:37], v[90:93], v[42:45], v[54:57]
	v_mfma_f32_16x16x32_bf16 v[58:61], v[118:121], v[38:41], v[50:53]
	v_mfma_f32_16x16x32_bf16 v[50:53], v[118:121], v[94:97], v[34:37]
	v_mfma_f32_16x16x32_bf16 v[34:37], v[122:125], v[42:45], v[106:109]
	v_mfma_f32_16x16x32_bf16 v[54:57], v[126:129], v[94:97], v[34:37]
	v_mfma_f32_16x16x32_bf16 v[34:37], v[90:93], v[102:105], v[110:113]
	v_mfma_f32_16x16x32_bf16 v[42:45], v[118:121], v[130:133], v[34:37]
	v_mfma_f32_16x16x32_bf16 v[34:37], v[122:125], v[102:105], v[82:85]
	v_mfma_f32_16x16x32_bf16 v[46:49], v[126:129], v[130:133], v[34:37]
	v_mfma_f32_16x16x32_bf16 v[34:37], v[90:93], v[134:137], v[114:117]
	v_mfma_f32_16x16x32_bf16 v[38:41], v[122:125], v[134:137], v[86:89]
	v_mfma_f32_16x16x32_bf16 v[34:37], v[118:121], v[138:141], v[34:37]
	v_mfma_f32_16x16x32_bf16 v[38:41], v[126:129], v[138:141], v[38:41]
	s_setprio 0
	s_setprio 1
	s_setprio 0
	s_barrier
	s_and_b64 vcc, exec, s[0:1]
	s_cbranch_vccnz .LBB0_630
	s_barrier

;     __host__ __device__ bool next(int i, Unit& u) const { const int L = i * G + c; if (L >= n) return false; u.pm = L; u.pn = L >> 2; return true; }
; #define PG8_STAGE(bufoff, gbase, voff) do { _Pragma("unroll") for (int _i = 0; _i < 2; ++_i) \
;         __builtin_amdgcn_global_load_lds((const unsigned*)((const char*)(gbase) + (voff)[_i]), (PG8_LAS unsigned*)(lds + (bufoff) + ldsw + _i * 8192), 16, 0, 0); } while (0)
; #define PG8_LDA(dst, b, h) do { _Pragma("unroll") for (int m = 0; m < 4; ++m) _Pragma("unroll") for (int k = 0; k < 2; ++k) dst[m][k] = *(const PG8_LAS bf16x8*)(lds + PG8_SA(b, h) + aoff + m * 2048 + k * 1024); } while (0)
; #define PG8_LDB(dst, b, h) do { _Pragma("unroll") for (int n = 0; n < 2; ++n) _Pragma("unroll") for (int k = 0; k < 2; ++k) dst[n][k] = *(const PG8_LAS bf16x8*)(lds + PG8_SB(b, h) + boff + n * 2048 + k * 1024); } while (0)
; #define PG8_WAIT_V(n) asm volatile("s_waitcnt vmcnt(" #n ")" ::: "memory")
; template <class Epi, class Sched, bool ALIGN_EPI>
; __device__ __forceinline__ void gemm_phase(PG8_LAS unsigned char* lds, const Gemm g, const Sched& S, const Epi& E) {
;     ...
;         const bool has_next = S.next(ui + 1, nxt);
;         const size_t tail_ = has_next ? 0 : tailoff; const char* nA = (has_next ? (const char*)g.A + (size_t)nxt.pm * tstepA : cA) + (has_next ? 0 : tailoffA); const char* nB = (has_next ? (const char*)g.Bt + (size_t)nxt.pn * tstepB : cB) + tail_;
;         for (int t = 0; t < nt; t += 2) {
;             if constexpr (Epi::MIDK) { if (t == (nt >> 1)) E.midk(acc, cur, wr, fr); }
;             const bool last = (t == nt - 2);
;             const char* a1 = cA + (size_t)(t + 1) * kstepA;
;             const char* a2 = last ? nA : cA + (size_t)(t + 2) * kstepA; const char* b2 = last ? nB : cB + (size_t)(t + 2) * kstep;
;             const char* a3 = a2 + kstepA; const char* b3 = b2 + kstep;
;             PG8_LDB(B0, 0, 0); PG8_LDB(B1, 0, 1); PG8_SCHED; PG8_LDA(At, 0, 0); PG8_STAGE(PG8_SA(1, 1), a1 + hstepA, voffA);
;             PG8_WAIT_V(8); PG8_WAIT_L(0); PG8_BAR; PG8_MMA(0, 0, At, B0); PG8_MMA(0, 1, At, B1); PG8_BAR; PG8_SCHED;
;             PG8_LDA(At, 0, 1); PG8_STAGE(PG8_SB(0, 0), b2, voffB); PG8_STAGE(PG8_SB(0, 1), b2 + hstepB, voffB); PG8_STAGE(PG8_SA(0, 0), a2, voffA);
;             PG8_WAIT_V(8); PG8_WAIT_L(0); PG8_BAR; PG8_MMA(1, 0, At, B0); PG8_MMA(1, 1, At, B1); PG8_BAR; PG8_SCHED;
.LBB0_648:
	ds_read_b128 v[12:15], v146
	ds_read_b128 v[16:19], v146 offset:1024
	ds_read_b128 v[20:23], v146 offset:2048
	ds_read_b128 v[24:27], v146 offset:3072
	ds_read_b128 v[28:31], v147
	ds_read_b128 v[32:35], v147 offset:1024
	ds_read_b128 v[36:39], v147 offset:2048
	ds_read_b128 v[40:43], v147 offset:3072
	s_add_u32 s24, s36, s24
	s_addc_u32 s25, s37, s25
	s_and_b64 s[4:5], s[26:27], exec
	s_cselect_b32 s4, 0, 0x200
	s_add_u32 s26, s34, s4
	s_addc_u32 s27, s35, 0
	s_add_u32 s4, s28, 0x18080
	s_addc_u32 s5, s29, 0
	s_mov_b32 m0, s51
	v_lshl_add_u64 v[68:69], s[4:5], 0, v[138:139]
	ds_read_b128 v[4:7], v3
	ds_read_b128 v[8:11], v3 offset:1024
	ds_read_b128 v[44:47], v3 offset:2048
	ds_read_b128 v[48:51], v3 offset:3072
	ds_read_b128 v[52:55], v3 offset:4096
	ds_read_b128 v[56:59], v3 offset:5120
	ds_read_b128 v[60:63], v3 offset:6144
	ds_read_b128 v[64:67], v3 offset:7168
	global_load_lds_dwordx4 v[68:69], off
	v_lshl_add_u64 v[68:69], s[4:5], 0, v[134:135]
	s_mov_b32 m0, s52
	s_nop 0
	global_load_lds_dwordx4 v[68:69], off
	s_waitcnt vmcnt(8)
	s_waitcnt lgkmcnt(0)
	s_barrier
	s_setprio 1
	s_waitcnt lgkmcnt(0)
	v_mfma_f32_16x16x32_bf16 v[68:71], v[12:15], v[4:7], 0
	v_mfma_f32_16x16x32_bf16 v[72:75], v[20:23], v[4:7], 0
	v_mfma_f32_16x16x32_bf16 v[76:79], v[12:15], v[44:47], 0
	v_mfma_f32_16x16x32_bf16 v[80:83], v[20:23], v[44:47], 0
	v_mfma_f32_16x16x32_bf16 v[84:87], v[12:15], v[52:55], 0
	v_mfma_f32_16x16x32_bf16 v[88:91], v[20:23], v[52:55], 0
	v_mfma_f32_16x16x32_bf16 v[92:95], v[12:15], v[60:63], 0
	v_mfma_f32_16x16x32_bf16 v[96:99], v[20:23], v[60:63], 0
	v_mfma_f32_16x16x32_bf16 v[68:71], v[16:19], v[8:11], v[68:71]
	v_mfma_f32_16x16x32_bf16 v[72:75], v[24:27], v[8:11], v[72:75]
	v_mfma_f32_16x16x32_bf16 v[76:79], v[16:19], v[48:51], v[76:79]
	v_mfma_f32_16x16x32_bf16 v[80:83], v[24:27], v[48:51], v[80:83]
	v_mfma_f32_16x16x32_bf16 v[84:87], v[16:19], v[56:59], v[84:87]
	v_mfma_f32_16x16x32_bf16 v[88:91], v[24:27], v[56:59], v[88:91]
	v_mfma_f32_16x16x32_bf16 v[92:95], v[16:19], v[64:67], v[92:95]
	v_mfma_f32_16x16x32_bf16 v[96:99], v[24:27], v[64:67], v[96:99]
	s_setprio 0
	s_setprio 1
	v_mfma_f32_16x16x32_bf16 v[100:103], v[28:31], v[4:7], 0
	v_mfma_f32_16x16x32_bf16 v[4:7], v[36:39], v[4:7], 0
	v_mfma_f32_16x16x32_bf16 v[104:107], v[40:43], v[8:11], v[4:7]
	v_mfma_f32_16x16x32_bf16 v[4:7], v[28:31], v[44:47], 0
	v_mfma_f32_16x16x32_bf16 v[108:111], v[32:35], v[48:51], v[4:7]
	v_mfma_f32_16x16x32_bf16 v[4:7], v[36:39], v[44:47], 0
	v_mfma_f32_16x16x32_bf16 v[44:47], v[40:43], v[48:51], v[4:7]
	v_mfma_f32_16x16x32_bf16 v[4:7], v[28:31], v[52:55], 0
	v_mfma_f32_16x16x32_bf16 v[48:51], v[32:35], v[56:59], v[4:7]
	v_mfma_f32_16x16x32_bf16 v[4:7], v[36:39], v[52:55], 0
	v_mfma_f32_16x16x32_bf16 v[52:55], v[40:43], v[56:59], v[4:7]
	v_mfma_f32_16x16x32_bf16 v[4:7], v[28:31], v[60:63], 0
	v_mfma_f32_16x16x32_bf16 v[56:59], v[32:35], v[64:67], v[4:7]
	v_mfma_f32_16x16x32_bf16 v[4:7], v[36:39], v[60:63], 0
	v_mfma_f32_16x16x32_bf16 v[100:103], v[32:35], v[8:11], v[100:103]
	v_mfma_f32_16x16x32_bf16 v[60:63], v[40:43], v[64:67], v[4:7]
	s_setprio 0
	s_barrier
	s_nop 3
	v_lshl_add_u64 v[4:5], s[30:31], 0, v[136:137]
	s_mov_b32 m0, s53
	v_lshl_add_u64 v[6:7], v[4:5], 0, s[16:17]
	ds_read_b128 v[64:67], v3 offset:16384
	ds_read_b128 v[112:115], v3 offset:17408
	ds_read_b128 v[116:119], v3 offset:18432
	ds_read_b128 v[120:123], v3 offset:19456
	ds_read_b128 v[124:127], v3 offset:20480
	ds_read_b128 v[128:131], v3 offset:21504
	ds_read_b128 v[150:153], v3 offset:22528
	ds_read_b128 v[154:157], v3 offset:23552
	global_load_lds_dwordx4 v[6:7], off
	v_lshl_add_u64 v[6:7], s[30:31], 0, v[132:133]
	s_add_u32 s4, s30, 0x18100
	v_lshl_add_u64 v[8:9], v[6:7], 0, s[16:17]
	s_mov_b32 m0, s57
	s_addc_u32 s5, s31, 0
	global_load_lds_dwordx4 v[8:9], off
	v_lshl_add_u64 v[8:9], s[4:5], 0, v[136:137]
	s_mov_b32 m0, s58
	s_nop 0
	global_load_lds_dwordx4 v[8:9], off
	v_lshl_add_u64 v[8:9], s[4:5], 0, v[132:133]
	s_mov_b32 m0, s59
	s_nop 0
	global_load_lds_dwordx4 v[8:9], off
	v_lshl_add_u64 v[8:9], s[28:29], 0, v[138:139]
	v_lshl_add_u64 v[10:11], v[8:9], 0, s[16:17]
	s_mov_b32 m0, s42
	s_nop 0
	global_load_lds_dwordx4 v[10:11], off
	v_lshl_add_u64 v[10:11], s[28:29], 0, v[134:135]
	v_lshl_add_u64 v[158:159], v[10:11], 0, s[16:17]
	s_mov_b32 m0, s43
	s_nop 0
	global_load_lds_dwordx4 v[158:159], off
	s_waitcnt vmcnt(8)
	s_waitcnt lgkmcnt(0)
	s_barrier
	s_setprio 1
	s_waitcnt lgkmcnt(0)
	v_mfma_f32_16x16x32_bf16 v[158:161], v[12:15], v[64:67], 0
	v_mfma_f32_16x16x32_bf16 v[166:169], v[12:15], v[116:119], 0
	v_mfma_f32_16x16x32_bf16 v[174:177], v[12:15], v[124:127], 0
	v_mfma_f32_16x16x32_bf16 v[12:15], v[12:15], v[150:153], 0
	v_mfma_f32_16x16x32_bf16 v[158:161], v[16:19], v[112:115], v[158:161]
	v_mfma_f32_16x16x32_bf16 v[166:169], v[16:19], v[120:123], v[166:169]
	v_mfma_f32_16x16x32_bf16 v[174:177], v[16:19], v[128:131], v[174:177]
	v_mfma_f32_16x16x32_bf16 v[12:15], v[16:19], v[154:157], v[12:15]
	v_mfma_f32_16x16x32_bf16 v[16:19], v[20:23], v[150:153], 0
	v_mfma_f32_16x16x32_bf16 v[162:165], v[20:23], v[64:67], 0
	v_mfma_f32_16x16x32_bf16 v[170:173], v[20:23], v[116:119], 0
	v_mfma_f32_16x16x32_bf16 v[178:181], v[20:23], v[124:127], 0
	v_mfma_f32_16x16x32_bf16 v[16:19], v[24:27], v[154:157], v[16:19]
	v_mfma_f32_16x16x32_bf16 v[162:165], v[24:27], v[112:115], v[162:165]
	v_mfma_f32_16x16x32_bf16 v[170:173], v[24:27], v[120:123], v[170:173]
	v_mfma_f32_16x16x32_bf16 v[178:181], v[24:27], v[128:131], v[178:181]
	s_setprio 0
	s_setprio 1
	v_mfma_f32_16x16x32_bf16 v[20:23], v[28:31], v[64:67], 0
	v_mfma_f32_16x16x32_bf16 v[24:27], v[36:39], v[64:67], 0
	v_mfma_f32_16x16x32_bf16 v[20:23], v[32:35], v[112:115], v[20:23]
	v_mfma_f32_16x16x32_bf16 v[24:27], v[40:43], v[112:115], v[24:27]
	v_mfma_f32_16x16x32_bf16 v[64:67], v[28:31], v[116:119], 0
	v_mfma_f32_16x16x32_bf16 v[112:115], v[36:39], v[116:119], 0
	v_mfma_f32_16x16x32_bf16 v[116:119], v[28:31], v[124:127], 0
	v_mfma_f32_16x16x32_bf16 v[28:31], v[28:31], v[150:153], 0
	v_mfma_f32_16x16x32_bf16 v[64:67], v[32:35], v[120:123], v[64:67]
	v_mfma_f32_16x16x32_bf16 v[112:115], v[40:43], v[120:123], v[112:115]
	v_mfma_f32_16x16x32_bf16 v[116:119], v[32:35], v[128:131], v[116:119]
	v_mfma_f32_16x16x32_bf16 v[120:123], v[36:39], v[124:127], 0
	v_mfma_f32_16x16x32_bf16 v[28:31], v[32:35], v[154:157], v[28:31]
	v_mfma_f32_16x16x32_bf16 v[32:35], v[36:39], v[150:153], 0
	v_mfma_f32_16x16x32_bf16 v[120:123], v[40:43], v[128:131], v[120:123]
	v_mfma_f32_16x16x32_bf16 v[32:35], v[40:43], v[154:157], v[32:35]
	s_setprio 0
	s_barrier
; #define PG8_STAGE(bufoff, gbase, voff) do { _Pragma("unroll") for (int _i = 0; _i < 2; ++_i) \
;         __builtin_amdgcn_global_load_lds((const unsigned*)((const char*)(gbase) + (voff)[_i]), (PG8_LAS unsigned*)(lds + (bufoff) + ldsw + _i * 8192), 16, 0, 0); } while (0)
; #define PG8_LDA(dst, b, h) do { _Pragma("unroll") for (int m = 0; m < 4; ++m) _Pragma("unroll") for (int k = 0; k < 2; ++k) dst[m][k] = *(const PG8_LAS bf16x8*)(lds + PG8_SA(b, h) + aoff + m * 2048 + k * 1024); } while (0)
; #define PG8_LDB(dst, b, h) do { _Pragma("unroll") for (int n = 0; n < 2; ++n) _Pragma("unroll") for (int k = 0; k < 2; ++k) dst[n][k] = *(const PG8_LAS bf16x8*)(lds + PG8_SB(b, h) + boff + n * 2048 + k * 1024); } while (0)
; #define PG8_MMA(ai, bj, At, Bt) do { __builtin_amdgcn_s_setprio(1); _Pragma("unroll") for (int m = 0; m < 4; ++m) _Pragma("unroll") for (int n = 0; n < 2; ++n) _Pragma("unroll") for (int k = 0; k < 2; ++k) \
;         acc[ai][bj][m][n] = __builtin_amdgcn_mfma_f32_16x16x32_bf16(Bt[n][k], At[m][k], acc[ai][bj][m][n], 0, 0, 0); __builtin_amdgcn_s_setprio(0); } while (0)
; #define PG8_WAIT_V(n) asm volatile("s_waitcnt vmcnt(" #n ")" ::: "memory")
; #define PG8_WAIT_L(n) asm volatile("s_waitcnt lgkmcnt(" #n ")" ::: "memory")
; #define PG8_BAR __builtin_amdgcn_s_barrier()
; #define PG8_SCHED __builtin_amdgcn_sched_barrier(0)
; template <class Epi, class Sched, bool ALIGN_EPI>
; __device__ __forceinline__ void gemm_phase(PG8_LAS unsigned char* lds, const Gemm g, const Sched& S, const Epi& E) {
;     ...
;             PG8_LDB(B0, 1, 0); PG8_LDB(B1, 1, 1); PG8_SCHED; PG8_LDA(At, 1, 0); PG8_STAGE(PG8_SA(0, 1), a2 + hstepA, voffA);
;             PG8_WAIT_V(8); PG8_WAIT_L(0); PG8_BAR; PG8_MMA(0, 0, At, B0); PG8_MMA(0, 1, At, B1); PG8_BAR; PG8_SCHED;
;             PG8_LDA(At, 1, 1); PG8_STAGE(PG8_SB(1, 0), b3, voffB); PG8_STAGE(PG8_SB(1, 1), b3 + hstepB, voffB); PG8_STAGE(PG8_SA(1, 0), a3, voffA);
	ds_read_b128 v[36:39], v148
	ds_read_b128 v[40:43], v148 offset:1024
	ds_read_b128 v[124:127], v148 offset:2048
	ds_read_b128 v[128:131], v148 offset:3072
	ds_read_b128 v[150:153], v149
	ds_read_b128 v[154:157], v149 offset:1024
	ds_read_b128 v[182:185], v149 offset:2048
	ds_read_b128 v[186:189], v149 offset:3072
	s_add_u32 s4, s28, 0x18100
	s_addc_u32 s5, s29, 0
	s_mov_b32 m0, s44
	v_lshl_add_u64 v[222:223], s[4:5], 0, v[138:139]
	ds_read_b128 v[190:193], v3 offset:32768
	ds_read_b128 v[194:197], v3 offset:33792
	ds_read_b128 v[198:201], v3 offset:34816
	ds_read_b128 v[202:205], v3 offset:35840
	ds_read_b128 v[206:209], v3 offset:36864
	ds_read_b128 v[210:213], v3 offset:37888
	ds_read_b128 v[214:217], v3 offset:38912
	ds_read_b128 v[218:221], v3 offset:39936
	global_load_lds_dwordx4 v[222:223], off
	v_lshl_add_u64 v[222:223], s[4:5], 0, v[134:135]
	s_mov_b32 m0, s45
	s_nop 0
	global_load_lds_dwordx4 v[222:223], off
	s_waitcnt vmcnt(8)
	s_waitcnt lgkmcnt(0)
	s_barrier
	s_setprio 1
	s_waitcnt lgkmcnt(0)
	v_mfma_f32_16x16x32_bf16 v[68:71], v[36:39], v[190:193], v[68:71]
	v_mfma_f32_16x16x32_bf16 v[68:71], v[40:43], v[194:197], v[68:71]
	v_mfma_f32_16x16x32_bf16 v[72:75], v[124:127], v[190:193], v[72:75]
	v_mfma_f32_16x16x32_bf16 v[72:75], v[128:131], v[194:197], v[72:75]
	v_mfma_f32_16x16x32_bf16 v[76:79], v[36:39], v[198:201], v[76:79]
	v_mfma_f32_16x16x32_bf16 v[76:79], v[40:43], v[202:205], v[76:79]
	v_mfma_f32_16x16x32_bf16 v[80:83], v[124:127], v[198:201], v[80:83]
	v_mfma_f32_16x16x32_bf16 v[80:83], v[128:131], v[202:205], v[80:83]
	v_mfma_f32_16x16x32_bf16 v[84:87], v[36:39], v[206:209], v[84:87]
	v_mfma_f32_16x16x32_bf16 v[84:87], v[40:43], v[210:213], v[84:87]
	v_mfma_f32_16x16x32_bf16 v[88:91], v[124:127], v[206:209], v[88:91]
	v_mfma_f32_16x16x32_bf16 v[88:91], v[128:131], v[210:213], v[88:91]
	v_mfma_f32_16x16x32_bf16 v[92:95], v[36:39], v[214:217], v[92:95]
	v_mfma_f32_16x16x32_bf16 v[92:95], v[40:43], v[218:221], v[92:95]
	v_mfma_f32_16x16x32_bf16 v[96:99], v[124:127], v[214:217], v[96:99]
	v_mfma_f32_16x16x32_bf16 v[96:99], v[128:131], v[218:221], v[96:99]
	s_setprio 0
	s_setprio 1
	v_mfma_f32_16x16x32_bf16 v[100:103], v[150:153], v[190:193], v[100:103]
	v_mfma_f32_16x16x32_bf16 v[100:103], v[154:157], v[194:197], v[100:103]
	v_mfma_f32_16x16x32_bf16 v[104:107], v[182:185], v[190:193], v[104:107]
	v_mfma_f32_16x16x32_bf16 v[104:107], v[186:189], v[194:197], v[104:107]
	v_mfma_f32_16x16x32_bf16 v[108:111], v[150:153], v[198:201], v[108:111]
	v_mfma_f32_16x16x32_bf16 v[108:111], v[154:157], v[202:205], v[108:111]
	v_mfma_f32_16x16x32_bf16 v[44:47], v[182:185], v[198:201], v[44:47]
	v_mfma_f32_16x16x32_bf16 v[44:47], v[186:189], v[202:205], v[44:47]
	v_mfma_f32_16x16x32_bf16 v[48:51], v[150:153], v[206:209], v[48:51]
	v_mfma_f32_16x16x32_bf16 v[48:51], v[154:157], v[210:213], v[48:51]
	v_mfma_f32_16x16x32_bf16 v[52:55], v[182:185], v[206:209], v[52:55]
	v_mfma_f32_16x16x32_bf16 v[52:55], v[186:189], v[210:213], v[52:55]
	v_mfma_f32_16x16x32_bf16 v[56:59], v[150:153], v[214:217], v[56:59]
	v_mfma_f32_16x16x32_bf16 v[56:59], v[154:157], v[218:221], v[56:59]
	v_mfma_f32_16x16x32_bf16 v[60:63], v[182:185], v[214:217], v[60:63]
	v_mfma_f32_16x16x32_bf16 v[60:63], v[186:189], v[218:221], v[60:63]
	s_setprio 0
	s_barrier
	s_add_i32 s4, s61, 0x2000
	s_mov_b32 m0, s61
	v_lshl_add_u64 v[222:223], v[4:5], 0, s[18:19]
	s_add_u32 s34, s30, 0x18180
	ds_read_b128 v[190:193], v3 offset:49152
	ds_read_b128 v[194:197], v3 offset:50176
	ds_read_b128 v[198:201], v3 offset:51200
	ds_read_b128 v[202:205], v3 offset:52224
	ds_read_b128 v[206:209], v3 offset:53248
	ds_read_b128 v[210:213], v3 offset:54272
	ds_read_b128 v[214:217], v3 offset:55296
	ds_read_b128 v[218:221], v3 offset:56320
	global_load_lds_dwordx4 v[222:223], off
	v_lshl_add_u64 v[222:223], v[6:7], 0, s[18:19]
	s_mov_b32 m0, s4
	s_addc_u32 s35, s31, 0
	s_add_i32 s5, s60, s41
	global_load_lds_dwordx4 v[222:223], off
	v_lshl_add_u64 v[222:223], s[34:35], 0, v[136:137]
	s_mov_b32 m0, s5
	s_add_i32 s7, s5, 0x2000
	global_load_lds_dwordx4 v[222:223], off
	v_lshl_add_u64 v[222:223], s[34:35], 0, v[132:133]
	s_mov_b32 m0, s7
	s_nop 0
	global_load_lds_dwordx4 v[222:223], off
	v_lshl_add_u64 v[222:223], v[8:9], 0, s[18:19]
	s_mov_b32 m0, s47
	s_nop 0
	global_load_lds_dwordx4 v[222:223], off
	v_lshl_add_u64 v[222:223], v[10:11], 0, s[18:19]
	s_mov_b32 m0, s48
	s_nop 0
	global_load_lds_dwordx4 v[222:223], off
	s_waitcnt vmcnt(8)
	s_waitcnt lgkmcnt(0)
	s_barrier
; #define PG8_STAGE(bufoff, gbase, voff) do { _Pragma("unroll") for (int _i = 0; _i < 2; ++_i) \
;         __builtin_amdgcn_global_load_lds((const unsigned*)((const char*)(gbase) + (voff)[_i]), (PG8_LAS unsigned*)(lds + (bufoff) + ldsw + _i * 8192), 16, 0, 0); } while (0)
; #define PG8_LDA(dst, b, h) do { _Pragma("unroll") for (int m = 0; m < 4; ++m) _Pragma("unroll") for (int k = 0; k < 2; ++k) dst[m][k] = *(const PG8_LAS bf16x8*)(lds + PG8_SA(b, h) + aoff + m * 2048 + k * 1024); } while (0)
; #define PG8_LDB(dst, b, h) do { _Pragma("unroll") for (int n = 0; n < 2; ++n) _Pragma("unroll") for (int k = 0; k < 2; ++k) dst[n][k] = *(const PG8_LAS bf16x8*)(lds + PG8_SB(b, h) + boff + n * 2048 + k * 1024); } while (0)
; #define PG8_MMA(ai, bj, At, Bt) do { __builtin_amdgcn_s_setprio(1); _Pragma("unroll") for (int m = 0; m < 4; ++m) _Pragma("unroll") for (int n = 0; n < 2; ++n) _Pragma("unroll") for (int k = 0; k < 2; ++k) \
;         acc[ai][bj][m][n] = __builtin_amdgcn_mfma_f32_16x16x32_bf16(Bt[n][k], At[m][k], acc[ai][bj][m][n], 0, 0, 0); __builtin_amdgcn_s_setprio(0); } while (0)
; #define PG8_WAIT_V(n) asm volatile("s_waitcnt vmcnt(" #n ")" ::: "memory")
; #define PG8_WAIT_L(n) asm volatile("s_waitcnt lgkmcnt(" #n ")" ::: "memory")
; #define PG8_BAR __builtin_amdgcn_s_barrier()
; #define PG8_SCHED __builtin_amdgcn_sched_barrier(0)
; template <class Epi, class Sched, bool ALIGN_EPI>
; __device__ __forceinline__ void gemm_phase(PG8_LAS unsigned char* lds, const Gemm g, const Sched& S, const Epi& E) {
;     ...
;             PG8_LDB(B0, 0, 0); PG8_LDB(B1, 0, 1); PG8_SCHED; PG8_LDA(At, 0, 0); PG8_STAGE(PG8_SA(1, 1), a1 + hstepA, voffA);
;             PG8_WAIT_V(8); PG8_WAIT_L(0); PG8_BAR; PG8_MMA(0, 0, At, B0); PG8_MMA(0, 1, At, B1); PG8_BAR; PG8_SCHED;
;     ...
;             PG8_WAIT_V(8); PG8_WAIT_L(0); PG8_BAR; PG8_MMA(1, 0, At, B0); PG8_MMA(1, 1, At, B1); PG8_BAR; PG8_SCHED;
	s_setprio 1
	s_waitcnt lgkmcnt(0)
	v_mfma_f32_16x16x32_bf16 v[12:15], v[36:39], v[214:217], v[12:15]
	v_mfma_f32_16x16x32_bf16 v[12:15], v[40:43], v[218:221], v[12:15]
	v_mfma_f32_16x16x32_bf16 v[16:19], v[124:127], v[214:217], v[16:19]
	v_mfma_f32_16x16x32_bf16 v[16:19], v[128:131], v[218:221], v[16:19]
	v_mfma_f32_16x16x32_bf16 v[158:161], v[36:39], v[190:193], v[158:161]
	v_mfma_f32_16x16x32_bf16 v[158:161], v[40:43], v[194:197], v[158:161]
	v_mfma_f32_16x16x32_bf16 v[162:165], v[124:127], v[190:193], v[162:165]
	v_mfma_f32_16x16x32_bf16 v[162:165], v[128:131], v[194:197], v[162:165]
	v_mfma_f32_16x16x32_bf16 v[166:169], v[36:39], v[198:201], v[166:169]
	v_mfma_f32_16x16x32_bf16 v[166:169], v[40:43], v[202:205], v[166:169]
	v_mfma_f32_16x16x32_bf16 v[170:173], v[124:127], v[198:201], v[170:173]
	v_mfma_f32_16x16x32_bf16 v[170:173], v[128:131], v[202:205], v[170:173]
	v_mfma_f32_16x16x32_bf16 v[174:177], v[36:39], v[206:209], v[174:177]
	v_mfma_f32_16x16x32_bf16 v[174:177], v[40:43], v[210:213], v[174:177]
	v_mfma_f32_16x16x32_bf16 v[178:181], v[124:127], v[206:209], v[178:181]
	v_mfma_f32_16x16x32_bf16 v[178:181], v[128:131], v[210:213], v[178:181]
	s_setprio 0
	s_setprio 1
	v_mfma_f32_16x16x32_bf16 v[20:23], v[150:153], v[190:193], v[20:23]
	v_mfma_f32_16x16x32_bf16 v[24:27], v[182:185], v[190:193], v[24:27]
	v_mfma_f32_16x16x32_bf16 v[36:39], v[150:153], v[198:201], v[64:67]
	v_mfma_f32_16x16x32_bf16 v[40:43], v[182:185], v[198:201], v[112:115]
	v_mfma_f32_16x16x32_bf16 v[64:67], v[150:153], v[206:209], v[116:119]
	v_mfma_f32_16x16x32_bf16 v[112:115], v[182:185], v[206:209], v[120:123]
	v_mfma_f32_16x16x32_bf16 v[28:31], v[150:153], v[214:217], v[28:31]
	v_mfma_f32_16x16x32_bf16 v[32:35], v[182:185], v[214:217], v[32:35]
	v_mfma_f32_16x16x32_bf16 v[20:23], v[154:157], v[194:197], v[20:23]
	v_mfma_f32_16x16x32_bf16 v[24:27], v[186:189], v[194:197], v[24:27]
	v_mfma_f32_16x16x32_bf16 v[36:39], v[154:157], v[202:205], v[36:39]
	v_mfma_f32_16x16x32_bf16 v[40:43], v[186:189], v[202:205], v[40:43]
	v_mfma_f32_16x16x32_bf16 v[64:67], v[154:157], v[210:213], v[64:67]
	v_mfma_f32_16x16x32_bf16 v[112:115], v[186:189], v[210:213], v[112:115]
	v_mfma_f32_16x16x32_bf16 v[28:31], v[154:157], v[218:221], v[28:31]
	v_mfma_f32_16x16x32_bf16 v[32:35], v[186:189], v[218:221], v[32:35]
	s_setprio 0
	s_barrier
	ds_read_b128 v[116:119], v146
	ds_read_b128 v[120:123], v146 offset:1024
	ds_read_b128 v[124:127], v146 offset:2048
	ds_read_b128 v[128:131], v146 offset:3072
	ds_read_b128 v[150:153], v147
	ds_read_b128 v[154:157], v147 offset:1024
	ds_read_b128 v[182:185], v147 offset:2048
	ds_read_b128 v[186:189], v147 offset:3072
	s_add_u32 s34, s28, 0x18180
	s_addc_u32 s35, s29, 0
	s_mov_b32 m0, s51
	v_lshl_add_u64 v[222:223], s[34:35], 0, v[138:139]
	ds_read_b128 v[190:193], v3
	ds_read_b128 v[194:197], v3 offset:1024
	ds_read_b128 v[198:201], v3 offset:2048
	ds_read_b128 v[202:205], v3 offset:3072
	ds_read_b128 v[206:209], v3 offset:4096
	ds_read_b128 v[210:213], v3 offset:5120
	ds_read_b128 v[214:217], v3 offset:6144
	ds_read_b128 v[218:221], v3 offset:7168
	global_load_lds_dwordx4 v[222:223], off
	v_lshl_add_u64 v[222:223], s[34:35], 0, v[134:135]
	s_mov_b32 m0, s52
	s_nop 0
	global_load_lds_dwordx4 v[222:223], off
	s_waitcnt vmcnt(8)
	s_waitcnt lgkmcnt(0)
	s_barrier
	s_setprio 1
	s_waitcnt lgkmcnt(0)
	v_mfma_f32_16x16x32_bf16 v[68:71], v[116:119], v[190:193], v[68:71]
	v_mfma_f32_16x16x32_bf16 v[68:71], v[120:123], v[194:197], v[68:71]
	v_mfma_f32_16x16x32_bf16 v[72:75], v[124:127], v[190:193], v[72:75]
	v_mfma_f32_16x16x32_bf16 v[72:75], v[128:131], v[194:197], v[72:75]
	v_mfma_f32_16x16x32_bf16 v[76:79], v[116:119], v[198:201], v[76:79]
	v_mfma_f32_16x16x32_bf16 v[76:79], v[120:123], v[202:205], v[76:79]
	v_mfma_f32_16x16x32_bf16 v[80:83], v[124:127], v[198:201], v[80:83]
	v_mfma_f32_16x16x32_bf16 v[80:83], v[128:131], v[202:205], v[80:83]
	v_mfma_f32_16x16x32_bf16 v[84:87], v[116:119], v[206:209], v[84:87]
	v_mfma_f32_16x16x32_bf16 v[84:87], v[120:123], v[210:213], v[84:87]
	v_mfma_f32_16x16x32_bf16 v[88:91], v[124:127], v[206:209], v[88:91]
	v_mfma_f32_16x16x32_bf16 v[88:91], v[128:131], v[210:213], v[88:91]
	v_mfma_f32_16x16x32_bf16 v[92:95], v[116:119], v[214:217], v[92:95]
	v_mfma_f32_16x16x32_bf16 v[92:95], v[120:123], v[218:221], v[92:95]
	v_mfma_f32_16x16x32_bf16 v[96:99], v[124:127], v[214:217], v[96:99]
	v_mfma_f32_16x16x32_bf16 v[96:99], v[128:131], v[218:221], v[96:99]
	s_setprio 0
	s_setprio 1
	v_mfma_f32_16x16x32_bf16 v[100:103], v[150:153], v[190:193], v[100:103]
	v_mfma_f32_16x16x32_bf16 v[100:103], v[154:157], v[194:197], v[100:103]
	v_mfma_f32_16x16x32_bf16 v[104:107], v[182:185], v[190:193], v[104:107]
	v_mfma_f32_16x16x32_bf16 v[104:107], v[186:189], v[194:197], v[104:107]
	v_mfma_f32_16x16x32_bf16 v[108:111], v[150:153], v[198:201], v[108:111]
	v_mfma_f32_16x16x32_bf16 v[108:111], v[154:157], v[202:205], v[108:111]
	v_mfma_f32_16x16x32_bf16 v[44:47], v[182:185], v[198:201], v[44:47]
	v_mfma_f32_16x16x32_bf16 v[44:47], v[186:189], v[202:205], v[44:47]
	v_mfma_f32_16x16x32_bf16 v[48:51], v[150:153], v[206:209], v[48:51]
	v_mfma_f32_16x16x32_bf16 v[48:51], v[154:157], v[210:213], v[48:51]
	v_mfma_f32_16x16x32_bf16 v[52:55], v[182:185], v[206:209], v[52:55]
	v_mfma_f32_16x16x32_bf16 v[52:55], v[186:189], v[210:213], v[52:55]
	v_mfma_f32_16x16x32_bf16 v[56:59], v[150:153], v[214:217], v[56:59]
	v_mfma_f32_16x16x32_bf16 v[56:59], v[154:157], v[218:221], v[56:59]
	v_mfma_f32_16x16x32_bf16 v[60:63], v[182:185], v[214:217], v[60:63]
	v_mfma_f32_16x16x32_bf16 v[60:63], v[186:189], v[218:221], v[60:63]
	s_setprio 0
	s_barrier
; #define PG8_STAGE(bufoff, gbase, voff) do { _Pragma("unroll") for (int _i = 0; _i < 2; ++_i) \
;         __builtin_amdgcn_global_load_lds((const unsigned*)((const char*)(gbase) + (voff)[_i]), (PG8_LAS unsigned*)(lds + (bufoff) + ldsw + _i * 8192), 16, 0, 0); } while (0)
; #define PG8_LDA(dst, b, h) do { _Pragma("unroll") for (int m = 0; m < 4; ++m) _Pragma("unroll") for (int k = 0; k < 2; ++k) dst[m][k] = *(const PG8_LAS bf16x8*)(lds + PG8_SA(b, h) + aoff + m * 2048 + k * 1024); } while (0)
; #define PG8_LDB(dst, b, h) do { _Pragma("unroll") for (int n = 0; n < 2; ++n) _Pragma("unroll") for (int k = 0; k < 2; ++k) dst[n][k] = *(const PG8_LAS bf16x8*)(lds + PG8_SB(b, h) + boff + n * 2048 + k * 1024); } while (0)
; #define PG8_MMA(ai, bj, At, Bt) do { __builtin_amdgcn_s_setprio(1); _Pragma("unroll") for (int m = 0; m < 4; ++m) _Pragma("unroll") for (int n = 0; n < 2; ++n) _Pragma("unroll") for (int k = 0; k < 2; ++k) \
;         acc[ai][bj][m][n] = __builtin_amdgcn_mfma_f32_16x16x32_bf16(Bt[n][k], At[m][k], acc[ai][bj][m][n], 0, 0, 0); __builtin_amdgcn_s_setprio(0); } while (0)
; #define PG8_WAIT_V(n) asm volatile("s_waitcnt vmcnt(" #n ")" ::: "memory")
; #define PG8_WAIT_L(n) asm volatile("s_waitcnt lgkmcnt(" #n ")" ::: "memory")
; #define PG8_BAR __builtin_amdgcn_s_barrier()
; #define PG8_SCHED __builtin_amdgcn_sched_barrier(0)
; template <class Epi, class Sched, bool ALIGN_EPI>
; __device__ __forceinline__ void gemm_phase(PG8_LAS unsigned char* lds, const Gemm g, const Sched& S, const Epi& E) {
;     ...
;             PG8_LDA(At, 0, 1); PG8_STAGE(PG8_SB(0, 0), b2, voffB); PG8_STAGE(PG8_SB(0, 1), b2 + hstepB, voffB); PG8_STAGE(PG8_SA(0, 0), a2, voffA);
;             PG8_WAIT_V(8); PG8_WAIT_L(0); PG8_BAR; PG8_MMA(1, 0, At, B0); PG8_MMA(1, 1, At, B1); PG8_BAR; PG8_SCHED;
;             PG8_LDB(B0, 1, 0); PG8_LDB(B1, 1, 1); PG8_SCHED; PG8_LDA(At, 1, 0); PG8_STAGE(PG8_SA(0, 1), a2 + hstepA, voffA);
;             PG8_WAIT_V(8); PG8_WAIT_L(0); PG8_BAR; PG8_MMA(0, 0, At, B0); PG8_MMA(0, 1, At, B1); PG8_BAR; PG8_SCHED;
	s_mov_b32 m0, s53
	v_lshl_add_u64 v[222:223], v[4:5], 0, s[20:21]
	s_add_u32 s34, s30, 0x18200
	ds_read_b128 v[190:193], v3 offset:16384
	ds_read_b128 v[194:197], v3 offset:17408
	ds_read_b128 v[198:201], v3 offset:18432
	ds_read_b128 v[202:205], v3 offset:19456
	ds_read_b128 v[206:209], v3 offset:20480
	ds_read_b128 v[210:213], v3 offset:21504
	ds_read_b128 v[214:217], v3 offset:22528
	ds_read_b128 v[218:221], v3 offset:23552
	global_load_lds_dwordx4 v[222:223], off
	v_lshl_add_u64 v[222:223], v[6:7], 0, s[20:21]
	s_mov_b32 m0, s57
	s_addc_u32 s35, s31, 0
	global_load_lds_dwordx4 v[222:223], off
	v_lshl_add_u64 v[222:223], s[34:35], 0, v[136:137]
	s_mov_b32 m0, s58
	s_nop 0
	global_load_lds_dwordx4 v[222:223], off
	v_lshl_add_u64 v[222:223], s[34:35], 0, v[132:133]
	s_mov_b32 m0, s59
	s_nop 0
	global_load_lds_dwordx4 v[222:223], off
	v_lshl_add_u64 v[222:223], v[8:9], 0, s[20:21]
	s_mov_b32 m0, s42
	s_nop 0
	global_load_lds_dwordx4 v[222:223], off
	v_lshl_add_u64 v[222:223], v[10:11], 0, s[20:21]
	s_mov_b32 m0, s43
	s_nop 0
	global_load_lds_dwordx4 v[222:223], off
	s_waitcnt vmcnt(8)
	s_waitcnt lgkmcnt(0)
	s_barrier
	s_setprio 1
	s_waitcnt lgkmcnt(0)
	v_mfma_f32_16x16x32_bf16 v[12:15], v[116:119], v[214:217], v[12:15]
	v_mfma_f32_16x16x32_bf16 v[12:15], v[120:123], v[218:221], v[12:15]
	v_mfma_f32_16x16x32_bf16 v[16:19], v[124:127], v[214:217], v[16:19]
	v_mfma_f32_16x16x32_bf16 v[16:19], v[128:131], v[218:221], v[16:19]
	v_mfma_f32_16x16x32_bf16 v[158:161], v[116:119], v[190:193], v[158:161]
	v_mfma_f32_16x16x32_bf16 v[158:161], v[120:123], v[194:197], v[158:161]
	v_mfma_f32_16x16x32_bf16 v[162:165], v[124:127], v[190:193], v[162:165]
	v_mfma_f32_16x16x32_bf16 v[162:165], v[128:131], v[194:197], v[162:165]
	v_mfma_f32_16x16x32_bf16 v[166:169], v[116:119], v[198:201], v[166:169]
	v_mfma_f32_16x16x32_bf16 v[166:169], v[120:123], v[202:205], v[166:169]
	v_mfma_f32_16x16x32_bf16 v[170:173], v[124:127], v[198:201], v[170:173]
	v_mfma_f32_16x16x32_bf16 v[170:173], v[128:131], v[202:205], v[170:173]
	v_mfma_f32_16x16x32_bf16 v[174:177], v[116:119], v[206:209], v[174:177]
	v_mfma_f32_16x16x32_bf16 v[174:177], v[120:123], v[210:213], v[174:177]
	v_mfma_f32_16x16x32_bf16 v[178:181], v[124:127], v[206:209], v[178:181]
	v_mfma_f32_16x16x32_bf16 v[178:181], v[128:131], v[210:213], v[178:181]
	s_setprio 0
	s_setprio 1
	v_mfma_f32_16x16x32_bf16 v[20:23], v[150:153], v[190:193], v[20:23]
	v_mfma_f32_16x16x32_bf16 v[20:23], v[154:157], v[194:197], v[20:23]
	v_mfma_f32_16x16x32_bf16 v[24:27], v[182:185], v[190:193], v[24:27]
	v_mfma_f32_16x16x32_bf16 v[24:27], v[186:189], v[194:197], v[24:27]
	v_mfma_f32_16x16x32_bf16 v[36:39], v[150:153], v[198:201], v[36:39]
	v_mfma_f32_16x16x32_bf16 v[36:39], v[154:157], v[202:205], v[36:39]
	v_mfma_f32_16x16x32_bf16 v[40:43], v[182:185], v[198:201], v[40:43]
	v_mfma_f32_16x16x32_bf16 v[40:43], v[186:189], v[202:205], v[40:43]
	v_mfma_f32_16x16x32_bf16 v[64:67], v[150:153], v[206:209], v[64:67]
	v_mfma_f32_16x16x32_bf16 v[64:67], v[154:157], v[210:213], v[64:67]
	v_mfma_f32_16x16x32_bf16 v[112:115], v[182:185], v[206:209], v[112:115]
	v_mfma_f32_16x16x32_bf16 v[112:115], v[186:189], v[210:213], v[112:115]
	v_mfma_f32_16x16x32_bf16 v[28:31], v[150:153], v[214:217], v[28:31]
	v_mfma_f32_16x16x32_bf16 v[28:31], v[154:157], v[218:221], v[28:31]
	v_mfma_f32_16x16x32_bf16 v[32:35], v[182:185], v[214:217], v[32:35]
	v_mfma_f32_16x16x32_bf16 v[32:35], v[186:189], v[218:221], v[32:35]
	s_setprio 0
	s_barrier
	ds_read_b128 v[116:119], v148
	ds_read_b128 v[120:123], v148 offset:1024
	ds_read_b128 v[124:127], v148 offset:2048
	ds_read_b128 v[128:131], v148 offset:3072
	ds_read_b128 v[150:153], v149
	ds_read_b128 v[154:157], v149 offset:1024
	ds_read_b128 v[182:185], v149 offset:2048
	ds_read_b128 v[186:189], v149 offset:3072
	s_add_u32 s34, s28, 0x18200
	s_addc_u32 s35, s29, 0
	s_mov_b32 m0, s44
	v_lshl_add_u64 v[222:223], s[34:35], 0, v[138:139]
	ds_read_b128 v[190:193], v3 offset:32768
	ds_read_b128 v[194:197], v3 offset:33792
	ds_read_b128 v[198:201], v3 offset:34816
	ds_read_b128 v[202:205], v3 offset:35840
	ds_read_b128 v[206:209], v3 offset:36864
	ds_read_b128 v[210:213], v3 offset:37888
	ds_read_b128 v[214:217], v3 offset:38912
	ds_read_b128 v[218:221], v3 offset:39936
	global_load_lds_dwordx4 v[222:223], off
	v_lshl_add_u64 v[222:223], s[34:35], 0, v[134:135]
	s_mov_b32 m0, s45
	s_nop 0
	global_load_lds_dwordx4 v[222:223], off
	s_waitcnt vmcnt(8)
	s_waitcnt lgkmcnt(0)
	s_barrier
	s_setprio 1
	s_waitcnt lgkmcnt(0)
	v_mfma_f32_16x16x32_bf16 v[68:71], v[116:119], v[190:193], v[68:71]
	v_mfma_f32_16x16x32_bf16 v[68:71], v[120:123], v[194:197], v[68:71]
	v_mfma_f32_16x16x32_bf16 v[72:75], v[124:127], v[190:193], v[72:75]
	v_mfma_f32_16x16x32_bf16 v[72:75], v[128:131], v[194:197], v[72:75]
	v_mfma_f32_16x16x32_bf16 v[76:79], v[116:119], v[198:201], v[76:79]
	v_mfma_f32_16x16x32_bf16 v[76:79], v[120:123], v[202:205], v[76:79]
	v_mfma_f32_16x16x32_bf16 v[80:83], v[124:127], v[198:201], v[80:83]
	v_mfma_f32_16x16x32_bf16 v[80:83], v[128:131], v[202:205], v[80:83]
	v_mfma_f32_16x16x32_bf16 v[84:87], v[116:119], v[206:209], v[84:87]
	v_mfma_f32_16x16x32_bf16 v[84:87], v[120:123], v[210:213], v[84:87]
	v_mfma_f32_16x16x32_bf16 v[88:91], v[124:127], v[206:209], v[88:91]
	v_mfma_f32_16x16x32_bf16 v[88:91], v[128:131], v[210:213], v[88:91]
	v_mfma_f32_16x16x32_bf16 v[92:95], v[116:119], v[214:217], v[92:95]
	v_mfma_f32_16x16x32_bf16 v[92:95], v[120:123], v[218:221], v[92:95]
	v_mfma_f32_16x16x32_bf16 v[96:99], v[124:127], v[214:217], v[96:99]
	v_mfma_f32_16x16x32_bf16 v[96:99], v[128:131], v[218:221], v[96:99]
	s_setprio 0
	s_setprio 1
	v_mfma_f32_16x16x32_bf16 v[100:103], v[150:153], v[190:193], v[100:103]
	v_mfma_f32_16x16x32_bf16 v[100:103], v[154:157], v[194:197], v[100:103]
	v_mfma_f32_16x16x32_bf16 v[104:107], v[182:185], v[190:193], v[104:107]
	v_mfma_f32_16x16x32_bf16 v[104:107], v[186:189], v[194:197], v[104:107]
	v_mfma_f32_16x16x32_bf16 v[108:111], v[150:153], v[198:201], v[108:111]
	v_mfma_f32_16x16x32_bf16 v[108:111], v[154:157], v[202:205], v[108:111]
	v_mfma_f32_16x16x32_bf16 v[44:47], v[182:185], v[198:201], v[44:47]
	v_mfma_f32_16x16x32_bf16 v[44:47], v[186:189], v[202:205], v[44:47]
	v_mfma_f32_16x16x32_bf16 v[48:51], v[150:153], v[206:209], v[48:51]
	v_mfma_f32_16x16x32_bf16 v[48:51], v[154:157], v[210:213], v[48:51]
	v_mfma_f32_16x16x32_bf16 v[52:55], v[182:185], v[206:209], v[52:55]
	v_mfma_f32_16x16x32_bf16 v[52:55], v[186:189], v[210:213], v[52:55]
	v_mfma_f32_16x16x32_bf16 v[56:59], v[150:153], v[214:217], v[56:59]
	v_mfma_f32_16x16x32_bf16 v[56:59], v[154:157], v[218:221], v[56:59]
	v_mfma_f32_16x16x32_bf16 v[60:63], v[182:185], v[214:217], v[60:63]
	v_mfma_f32_16x16x32_bf16 v[60:63], v[186:189], v[218:221], v[60:63]
	s_setprio 0
	s_barrier
; #define PG8_STAGE(bufoff, gbase, voff) do { _Pragma("unroll") for (int _i = 0; _i < 2; ++_i) \
;         __builtin_amdgcn_global_load_lds((const unsigned*)((const char*)(gbase) + (voff)[_i]), (PG8_LAS unsigned*)(lds + (bufoff) + ldsw + _i * 8192), 16, 0, 0); } while (0)
; #define PG8_LDA(dst, b, h) do { _Pragma("unroll") for (int m = 0; m < 4; ++m) _Pragma("unroll") for (int k = 0; k < 2; ++k) dst[m][k] = *(const PG8_LAS bf16x8*)(lds + PG8_SA(b, h) + aoff + m * 2048 + k * 1024); } while (0)
; #define PG8_LDB(dst, b, h) do { _Pragma("unroll") for (int n = 0; n < 2; ++n) _Pragma("unroll") for (int k = 0; k < 2; ++k) dst[n][k] = *(const PG8_LAS bf16x8*)(lds + PG8_SB(b, h) + boff + n * 2048 + k * 1024); } while (0)
; #define PG8_MMA(ai, bj, At, Bt) do { __builtin_amdgcn_s_setprio(1); _Pragma("unroll") for (int m = 0; m < 4; ++m) _Pragma("unroll") for (int n = 0; n < 2; ++n) _Pragma("unroll") for (int k = 0; k < 2; ++k) \
;         acc[ai][bj][m][n] = __builtin_amdgcn_mfma_f32_16x16x32_bf16(Bt[n][k], At[m][k], acc[ai][bj][m][n], 0, 0, 0); __builtin_amdgcn_s_setprio(0); } while (0)
; #define PG8_WAIT_V(n) asm volatile("s_waitcnt vmcnt(" #n ")" ::: "memory")
; #define PG8_WAIT_L(n) asm volatile("s_waitcnt lgkmcnt(" #n ")" ::: "memory")
; #define PG8_BAR __builtin_amdgcn_s_barrier()
; #define PG8_SCHED __builtin_amdgcn_sched_barrier(0)
; template <class Epi, class Sched, bool ALIGN_EPI>
; __device__ __forceinline__ void gemm_phase(PG8_LAS unsigned char* lds, const Gemm g, const Sched& S, const Epi& E) {
;     ...
;             PG8_LDB(B0, 0, 0); PG8_LDB(B1, 0, 1); PG8_SCHED; PG8_LDA(At, 0, 0); PG8_STAGE(PG8_SA(1, 1), a1 + hstepA, voffA);
;             PG8_WAIT_V(8); PG8_WAIT_L(0); PG8_BAR; PG8_MMA(0, 0, At, B0); PG8_MMA(0, 1, At, B1); PG8_BAR; PG8_SCHED;
;     ...
;             PG8_LDA(At, 1, 1); PG8_STAGE(PG8_SB(1, 0), b3, voffB); PG8_STAGE(PG8_SB(1, 1), b3 + hstepB, voffB); PG8_STAGE(PG8_SA(1, 0), a3, voffA);
;             PG8_WAIT_V(8); PG8_WAIT_L(0); PG8_BAR; PG8_MMA(1, 0, At, B0); PG8_MMA(1, 1, At, B1); PG8_BAR; PG8_SCHED;
	s_mov_b32 m0, s61
	v_lshl_add_u64 v[4:5], v[4:5], 0, s[22:23]
	s_add_u32 s30, s30, 0x18280
	ds_read_b128 v[190:193], v3 offset:49152
	ds_read_b128 v[194:197], v3 offset:50176
	ds_read_b128 v[198:201], v3 offset:51200
	ds_read_b128 v[202:205], v3 offset:52224
	ds_read_b128 v[206:209], v3 offset:53248
	ds_read_b128 v[210:213], v3 offset:54272
	ds_read_b128 v[214:217], v3 offset:55296
	ds_read_b128 v[218:221], v3 offset:56320
	global_load_lds_dwordx4 v[4:5], off
	v_lshl_add_u64 v[4:5], v[6:7], 0, s[22:23]
	s_mov_b32 m0, s4
	s_addc_u32 s31, s31, 0
	global_load_lds_dwordx4 v[4:5], off
	v_lshl_add_u64 v[4:5], s[30:31], 0, v[136:137]
	s_mov_b32 m0, s5
	s_nop 0
	global_load_lds_dwordx4 v[4:5], off
	v_lshl_add_u64 v[4:5], s[30:31], 0, v[132:133]
	s_mov_b32 m0, s7
	s_nop 0
	global_load_lds_dwordx4 v[4:5], off
	v_lshl_add_u64 v[4:5], v[8:9], 0, s[22:23]
	s_mov_b32 m0, s47
	s_nop 0
	global_load_lds_dwordx4 v[4:5], off
	v_lshl_add_u64 v[4:5], v[10:11], 0, s[22:23]
	s_mov_b32 m0, s48
	s_nop 0
	global_load_lds_dwordx4 v[4:5], off
	s_waitcnt vmcnt(8)
	s_waitcnt lgkmcnt(0)
	s_barrier
	s_setprio 1
	s_waitcnt lgkmcnt(0)
	v_mfma_f32_16x16x32_bf16 v[4:7], v[116:119], v[190:193], v[158:161]
	v_mfma_f32_16x16x32_bf16 v[8:11], v[124:127], v[190:193], v[162:165]
	v_mfma_f32_16x16x32_bf16 v[12:15], v[116:119], v[214:217], v[12:15]
	v_mfma_f32_16x16x32_bf16 v[16:19], v[124:127], v[214:217], v[16:19]
	v_mfma_f32_16x16x32_bf16 v[4:7], v[120:123], v[194:197], v[4:7]
	v_mfma_f32_16x16x32_bf16 v[8:11], v[128:131], v[194:197], v[8:11]
	v_mfma_f32_16x16x32_bf16 v[158:161], v[116:119], v[198:201], v[166:169]
	v_mfma_f32_16x16x32_bf16 v[162:165], v[124:127], v[198:201], v[170:173]
	v_mfma_f32_16x16x32_bf16 v[166:169], v[116:119], v[206:209], v[174:177]
	v_mfma_f32_16x16x32_bf16 v[170:173], v[124:127], v[206:209], v[178:181]
	v_mfma_f32_16x16x32_bf16 v[12:15], v[120:123], v[218:221], v[12:15]
	v_mfma_f32_16x16x32_bf16 v[16:19], v[128:131], v[218:221], v[16:19]
	v_mfma_f32_16x16x32_bf16 v[158:161], v[120:123], v[202:205], v[158:161]
	v_mfma_f32_16x16x32_bf16 v[162:165], v[128:131], v[202:205], v[162:165]
	v_mfma_f32_16x16x32_bf16 v[166:169], v[120:123], v[210:213], v[166:169]
	v_mfma_f32_16x16x32_bf16 v[170:173], v[128:131], v[210:213], v[170:173]
	s_setprio 0
	s_setprio 1
	v_mfma_f32_16x16x32_bf16 v[20:23], v[150:153], v[190:193], v[20:23]
	v_mfma_f32_16x16x32_bf16 v[20:23], v[154:157], v[194:197], v[20:23]
	v_mfma_f32_16x16x32_bf16 v[24:27], v[182:185], v[190:193], v[24:27]
	v_mfma_f32_16x16x32_bf16 v[24:27], v[186:189], v[194:197], v[24:27]
	v_mfma_f32_16x16x32_bf16 v[36:39], v[150:153], v[198:201], v[36:39]
	v_mfma_f32_16x16x32_bf16 v[36:39], v[154:157], v[202:205], v[36:39]
	v_mfma_f32_16x16x32_bf16 v[40:43], v[182:185], v[198:201], v[40:43]
	v_mfma_f32_16x16x32_bf16 v[40:43], v[186:189], v[202:205], v[40:43]
	v_mfma_f32_16x16x32_bf16 v[64:67], v[150:153], v[206:209], v[64:67]
	v_mfma_f32_16x16x32_bf16 v[64:67], v[154:157], v[210:213], v[64:67]
	v_mfma_f32_16x16x32_bf16 v[112:115], v[182:185], v[206:209], v[112:115]
	v_mfma_f32_16x16x32_bf16 v[112:115], v[186:189], v[210:213], v[112:115]
	v_mfma_f32_16x16x32_bf16 v[28:31], v[150:153], v[214:217], v[28:31]
	v_mfma_f32_16x16x32_bf16 v[28:31], v[154:157], v[218:221], v[28:31]
	v_mfma_f32_16x16x32_bf16 v[32:35], v[182:185], v[214:217], v[32:35]
	v_mfma_f32_16x16x32_bf16 v[32:35], v[186:189], v[218:221], v[32:35]
	s_setprio 0
	s_barrier
	ds_read_b128 v[116:119], v146
	ds_read_b128 v[120:123], v146 offset:1024
	ds_read_b128 v[124:127], v146 offset:2048
	ds_read_b128 v[128:131], v146 offset:3072
	ds_read_b128 v[150:153], v147
	ds_read_b128 v[154:157], v147 offset:1024
	ds_read_b128 v[174:177], v147 offset:2048
	ds_read_b128 v[178:181], v147 offset:3072
	s_add_u32 s28, s28, 0x18280
	s_addc_u32 s29, s29, 0
	s_mov_b32 m0, s51
	v_lshl_add_u64 v[214:215], s[28:29], 0, v[138:139]
	ds_read_b128 v[182:185], v3
	ds_read_b128 v[186:189], v3 offset:1024
	ds_read_b128 v[190:193], v3 offset:2048
	ds_read_b128 v[194:197], v3 offset:3072
	ds_read_b128 v[198:201], v3 offset:4096
	ds_read_b128 v[202:205], v3 offset:5120
	ds_read_b128 v[206:209], v3 offset:6144
	ds_read_b128 v[210:213], v3 offset:7168
	global_load_lds_dwordx4 v[214:215], off
	v_lshl_add_u64 v[214:215], s[28:29], 0, v[134:135]
	s_mov_b32 m0, s52
	s_nop 0
	global_load_lds_dwordx4 v[214:215], off
	s_waitcnt vmcnt(8)
	s_waitcnt lgkmcnt(0)
	s_barrier
	s_setprio 1
	s_waitcnt lgkmcnt(0)
	v_mfma_f32_16x16x32_bf16 v[68:71], v[116:119], v[182:185], v[68:71]
	v_mfma_f32_16x16x32_bf16 v[72:75], v[124:127], v[182:185], v[72:75]
	v_mfma_f32_16x16x32_bf16 v[76:79], v[116:119], v[190:193], v[76:79]
	v_mfma_f32_16x16x32_bf16 v[80:83], v[124:127], v[190:193], v[80:83]
	v_mfma_f32_16x16x32_bf16 v[84:87], v[116:119], v[198:201], v[84:87]
	v_mfma_f32_16x16x32_bf16 v[88:91], v[124:127], v[198:201], v[88:91]
	v_mfma_f32_16x16x32_bf16 v[92:95], v[116:119], v[206:209], v[92:95]
	v_mfma_f32_16x16x32_bf16 v[68:71], v[120:123], v[186:189], v[68:71]
	v_mfma_f32_16x16x32_bf16 v[72:75], v[128:131], v[186:189], v[72:75]
	v_mfma_f32_16x16x32_bf16 v[76:79], v[120:123], v[194:197], v[76:79]
	v_mfma_f32_16x16x32_bf16 v[80:83], v[128:131], v[194:197], v[80:83]
	v_mfma_f32_16x16x32_bf16 v[84:87], v[120:123], v[202:205], v[84:87]
	v_mfma_f32_16x16x32_bf16 v[88:91], v[128:131], v[202:205], v[88:91]
	v_mfma_f32_16x16x32_bf16 v[214:217], v[120:123], v[210:213], v[92:95]
	v_mfma_f32_16x16x32_bf16 v[92:95], v[124:127], v[206:209], v[96:99]
	v_mfma_f32_16x16x32_bf16 v[218:221], v[128:131], v[210:213], v[92:95]
	s_setprio 0
	s_setprio 1
	v_mfma_f32_16x16x32_bf16 v[92:95], v[150:153], v[182:185], v[100:103]
	v_mfma_f32_16x16x32_bf16 v[100:103], v[154:157], v[186:189], v[92:95]
	v_mfma_f32_16x16x32_bf16 v[92:95], v[174:177], v[182:185], v[104:107]
	v_mfma_f32_16x16x32_bf16 v[44:47], v[174:177], v[190:193], v[44:47]
	v_mfma_f32_16x16x32_bf16 v[48:51], v[150:153], v[198:201], v[48:51]
	v_mfma_f32_16x16x32_bf16 v[52:55], v[174:177], v[198:201], v[52:55]
	v_mfma_f32_16x16x32_bf16 v[56:59], v[150:153], v[206:209], v[56:59]
	v_mfma_f32_16x16x32_bf16 v[60:63], v[174:177], v[206:209], v[60:63]
	v_mfma_f32_16x16x32_bf16 v[104:107], v[178:181], v[186:189], v[92:95]
	v_mfma_f32_16x16x32_bf16 v[92:95], v[150:153], v[190:193], v[108:111]
	v_mfma_f32_16x16x32_bf16 v[44:47], v[178:181], v[194:197], v[44:47]
	v_mfma_f32_16x16x32_bf16 v[48:51], v[154:157], v[202:205], v[48:51]
	v_mfma_f32_16x16x32_bf16 v[52:55], v[178:181], v[202:205], v[52:55]
	v_mfma_f32_16x16x32_bf16 v[56:59], v[154:157], v[210:213], v[56:59]
	v_mfma_f32_16x16x32_bf16 v[60:63], v[178:181], v[210:213], v[60:63]
	v_mfma_f32_16x16x32_bf16 v[182:185], v[154:157], v[194:197], v[92:95]
	s_setprio 0
	s_barrier
; #define PG8_STAGE(bufoff, gbase, voff) do { _Pragma("unroll") for (int _i = 0; _i < 2; ++_i) \
;         __builtin_amdgcn_global_load_lds((const unsigned*)((const char*)(gbase) + (voff)[_i]), (PG8_LAS unsigned*)(lds + (bufoff) + ldsw + _i * 8192), 16, 0, 0); } while (0)
; #define PG8_LDA(dst, b, h) do { _Pragma("unroll") for (int m = 0; m < 4; ++m) _Pragma("unroll") for (int k = 0; k < 2; ++k) dst[m][k] = *(const PG8_LAS bf16x8*)(lds + PG8_SA(b, h) + aoff + m * 2048 + k * 1024); } while (0)
; #define PG8_LDB(dst, b, h) do { _Pragma("unroll") for (int n = 0; n < 2; ++n) _Pragma("unroll") for (int k = 0; k < 2; ++k) dst[n][k] = *(const PG8_LAS bf16x8*)(lds + PG8_SB(b, h) + boff + n * 2048 + k * 1024); } while (0)
; #define PG8_MMA(ai, bj, At, Bt) do { __builtin_amdgcn_s_setprio(1); _Pragma("unroll") for (int m = 0; m < 4; ++m) _Pragma("unroll") for (int n = 0; n < 2; ++n) _Pragma("unroll") for (int k = 0; k < 2; ++k) \
;         acc[ai][bj][m][n] = __builtin_amdgcn_mfma_f32_16x16x32_bf16(Bt[n][k], At[m][k], acc[ai][bj][m][n], 0, 0, 0); __builtin_amdgcn_s_setprio(0); } while (0)
; #define PG8_WAIT_V(n) asm volatile("s_waitcnt vmcnt(" #n ")" ::: "memory")
; #define PG8_WAIT_L(n) asm volatile("s_waitcnt lgkmcnt(" #n ")" ::: "memory")
; #define PG8_BAR __builtin_amdgcn_s_barrier()
; #define PG8_SCHED __builtin_amdgcn_sched_barrier(0)
; template <class Epi, class Sched, bool ALIGN_EPI>
; __device__ __forceinline__ void gemm_phase(PG8_LAS unsigned char* lds, const Gemm g, const Sched& S, const Epi& E) {
;     ...
;             PG8_LDA(At, 0, 1); PG8_STAGE(PG8_SB(0, 0), b2, voffB); PG8_STAGE(PG8_SB(0, 1), b2 + hstepB, voffB); PG8_STAGE(PG8_SA(0, 0), a2, voffA);
;             PG8_WAIT_V(8); PG8_WAIT_L(0); PG8_BAR; PG8_MMA(1, 0, At, B0); PG8_MMA(1, 1, At, B1); PG8_BAR; PG8_SCHED;
;             PG8_LDB(B0, 1, 0); PG8_LDB(B1, 1, 1); PG8_SCHED; PG8_LDA(At, 1, 0); PG8_STAGE(PG8_SA(0, 1), a2 + hstepA, voffA);
	s_mov_b32 m0, s53
	v_lshl_add_u64 v[246:247], s[26:27], 0, v[136:137]
	s_add_u32 s28, s26, 0x18000
	ds_read_b128 v[92:95], v3 offset:16384
	ds_read_b128 v[96:99], v3 offset:17408
	ds_read_b128 v[108:111], v3 offset:18432
	ds_read_b128 v[186:189], v3 offset:19456
	ds_read_b128 v[190:193], v3 offset:20480
	ds_read_b128 v[194:197], v3 offset:21504
	ds_read_b128 v[198:201], v3 offset:22528
	ds_read_b128 v[202:205], v3 offset:23552
	global_load_lds_dwordx4 v[246:247], off
	v_lshl_add_u64 v[248:249], s[26:27], 0, v[132:133]
	s_mov_b32 m0, s57
	s_addc_u32 s29, s27, 0
	global_load_lds_dwordx4 v[248:249], off
	v_lshl_add_u64 v[206:207], s[28:29], 0, v[136:137]
	s_mov_b32 m0, s58
	v_lshl_add_u64 v[250:251], s[24:25], 0, v[138:139]
	global_load_lds_dwordx4 v[206:207], off
	v_lshl_add_u64 v[206:207], s[28:29], 0, v[132:133]
	s_mov_b32 m0, s59
	v_lshl_add_u64 v[252:253], s[24:25], 0, v[134:135]
	global_load_lds_dwordx4 v[206:207], off
	s_mov_b32 m0, s42
	s_nop 0
	global_load_lds_dwordx4 v[250:251], off
	s_mov_b32 m0, s43
	s_nop 0
	global_load_lds_dwordx4 v[252:253], off
	s_waitcnt vmcnt(8)
	s_waitcnt lgkmcnt(0)
	s_barrier
	s_setprio 1
	s_waitcnt lgkmcnt(0)
	v_mfma_f32_16x16x32_bf16 v[4:7], v[116:119], v[92:95], v[4:7]
	v_mfma_f32_16x16x32_bf16 v[8:11], v[124:127], v[92:95], v[8:11]
	v_mfma_f32_16x16x32_bf16 v[12:15], v[116:119], v[198:201], v[12:15]
	v_mfma_f32_16x16x32_bf16 v[4:7], v[120:123], v[96:99], v[4:7]
	v_mfma_f32_16x16x32_bf16 v[8:11], v[128:131], v[96:99], v[8:11]
	v_mfma_f32_16x16x32_bf16 v[158:161], v[116:119], v[108:111], v[158:161]
	v_mfma_f32_16x16x32_bf16 v[162:165], v[124:127], v[108:111], v[162:165]
	v_mfma_f32_16x16x32_bf16 v[166:169], v[116:119], v[190:193], v[166:169]
	v_mfma_f32_16x16x32_bf16 v[170:173], v[124:127], v[190:193], v[170:173]
	v_mfma_f32_16x16x32_bf16 v[12:15], v[120:123], v[202:205], v[12:15]
	v_mfma_f32_16x16x32_bf16 v[16:19], v[124:127], v[198:201], v[16:19]
	v_mfma_f32_16x16x32_bf16 v[158:161], v[120:123], v[186:189], v[158:161]
	v_mfma_f32_16x16x32_bf16 v[162:165], v[128:131], v[186:189], v[162:165]
	v_mfma_f32_16x16x32_bf16 v[166:169], v[120:123], v[194:197], v[166:169]
	v_mfma_f32_16x16x32_bf16 v[170:173], v[128:131], v[194:197], v[170:173]
	v_mfma_f32_16x16x32_bf16 v[206:209], v[128:131], v[202:205], v[16:19]
	s_setprio 0
	s_setprio 1
	v_mfma_f32_16x16x32_bf16 v[16:19], v[150:153], v[92:95], v[20:23]
	v_mfma_f32_16x16x32_bf16 v[20:23], v[154:157], v[96:99], v[16:19]
	v_mfma_f32_16x16x32_bf16 v[16:19], v[174:177], v[92:95], v[24:27]
	v_mfma_f32_16x16x32_bf16 v[24:27], v[178:181], v[96:99], v[16:19]
	v_mfma_f32_16x16x32_bf16 v[16:19], v[150:153], v[108:111], v[36:39]
	v_mfma_f32_16x16x32_bf16 v[36:39], v[154:157], v[186:189], v[16:19]
	v_mfma_f32_16x16x32_bf16 v[16:19], v[174:177], v[108:111], v[40:43]
	v_mfma_f32_16x16x32_bf16 v[186:189], v[178:181], v[186:189], v[16:19]
	v_mfma_f32_16x16x32_bf16 v[16:19], v[150:153], v[190:193], v[64:67]
	v_mfma_f32_16x16x32_bf16 v[210:213], v[154:157], v[194:197], v[16:19]
	v_mfma_f32_16x16x32_bf16 v[16:19], v[174:177], v[190:193], v[112:115]
	v_mfma_f32_16x16x32_bf16 v[190:193], v[178:181], v[194:197], v[16:19]
	v_mfma_f32_16x16x32_bf16 v[16:19], v[150:153], v[198:201], v[28:31]
	v_mfma_f32_16x16x32_bf16 v[150:153], v[154:157], v[202:205], v[16:19]
	v_mfma_f32_16x16x32_bf16 v[16:19], v[174:177], v[198:201], v[32:35]
	v_mfma_f32_16x16x32_bf16 v[154:157], v[178:181], v[202:205], v[16:19]
	s_setprio 0
	s_barrier
	s_nop 4
	ds_read_b128 v[16:19], v148
	ds_read_b128 v[40:43], v148 offset:1024
	ds_read_b128 v[174:177], v148 offset:2048
	ds_read_b128 v[178:181], v148 offset:3072
	ds_read_b128 v[194:197], v149
	ds_read_b128 v[198:201], v149 offset:1024
	ds_read_b128 v[202:205], v149 offset:2048
	ds_read_b128 v[222:225], v149 offset:3072
	s_add_u32 s28, s24, 0x18000
	s_addc_u32 s29, s25, 0
	s_mov_b32 m0, s44
	v_lshl_add_u64 v[92:93], s[28:29], 0, v[138:139]
	ds_read_b128 v[28:31], v3 offset:32768
	ds_read_b128 v[32:35], v3 offset:33792
	ds_read_b128 v[64:67], v3 offset:34816
	ds_read_b128 v[226:229], v3 offset:35840
	ds_read_b128 v[230:233], v3 offset:36864
	ds_read_b128 v[234:237], v3 offset:37888
	ds_read_b128 v[238:241], v3 offset:38912
	ds_read_b128 v[242:245], v3 offset:39936
	global_load_lds_dwordx4 v[92:93], off
	v_lshl_add_u64 v[92:93], s[28:29], 0, v[134:135]
	s_mov_b32 m0, s45
	s_nop 0
	global_load_lds_dwordx4 v[92:93], off
	s_waitcnt vmcnt(8)
	s_waitcnt lgkmcnt(0)
	s_barrier
; #define PG8_STAGE(bufoff, gbase, voff) do { _Pragma("unroll") for (int _i = 0; _i < 2; ++_i) \
;         __builtin_amdgcn_global_load_lds((const unsigned*)((const char*)(gbase) + (voff)[_i]), (PG8_LAS unsigned*)(lds + (bufoff) + ldsw + _i * 8192), 16, 0, 0); } while (0)
; #define PG8_LDA(dst, b, h) do { _Pragma("unroll") for (int m = 0; m < 4; ++m) _Pragma("unroll") for (int k = 0; k < 2; ++k) dst[m][k] = *(const PG8_LAS bf16x8*)(lds + PG8_SA(b, h) + aoff + m * 2048 + k * 1024); } while (0)
; #define PG8_MMA(ai, bj, At, Bt) do { __builtin_amdgcn_s_setprio(1); _Pragma("unroll") for (int m = 0; m < 4; ++m) _Pragma("unroll") for (int n = 0; n < 2; ++n) _Pragma("unroll") for (int k = 0; k < 2; ++k) \
;         acc[ai][bj][m][n] = __builtin_amdgcn_mfma_f32_16x16x32_bf16(Bt[n][k], At[m][k], acc[ai][bj][m][n], 0, 0, 0); __builtin_amdgcn_s_setprio(0); } while (0)
; #define PG8_WAIT_V(n) asm volatile("s_waitcnt vmcnt(" #n ")" ::: "memory")
; #define PG8_WAIT_L(n) asm volatile("s_waitcnt lgkmcnt(" #n ")" ::: "memory")
; #define PG8_BAR __builtin_amdgcn_s_barrier()
; #define PG8_SCHED __builtin_amdgcn_sched_barrier(0)
; template <class Epi, class Sched, bool ALIGN_EPI>
; __device__ __forceinline__ void gemm_phase(PG8_LAS unsigned char* lds, const Gemm g, const Sched& S, const Epi& E) {
;     ...
;             PG8_WAIT_V(8); PG8_WAIT_L(0); PG8_BAR; PG8_MMA(0, 0, At, B0); PG8_MMA(0, 1, At, B1); PG8_BAR; PG8_SCHED;
;             PG8_LDA(At, 1, 1); PG8_STAGE(PG8_SB(1, 0), b3, voffB); PG8_STAGE(PG8_SB(1, 1), b3 + hstepB, voffB); PG8_STAGE(PG8_SA(1, 0), a3, voffA);
;             PG8_WAIT_V(8); PG8_WAIT_L(0); PG8_BAR; PG8_MMA(1, 0, At, B0); PG8_MMA(1, 1, At, B1); PG8_BAR; PG8_SCHED;
;         }
;         if constexpr (ALIGN_EPI) { if (wr == 0) PG8_BAR; }
	s_setprio 1
	s_waitcnt lgkmcnt(0)
	v_mfma_f32_16x16x32_bf16 v[68:71], v[16:19], v[28:31], v[68:71]
	v_mfma_f32_16x16x32_bf16 v[128:131], v[40:43], v[32:35], v[68:71]
	v_mfma_f32_16x16x32_bf16 v[68:71], v[174:177], v[28:31], v[72:75]
	v_mfma_f32_16x16x32_bf16 v[124:127], v[178:181], v[32:35], v[68:71]
	v_mfma_f32_16x16x32_bf16 v[68:71], v[16:19], v[64:67], v[76:79]
	v_mfma_f32_16x16x32_bf16 v[112:115], v[40:43], v[226:229], v[68:71]
	v_mfma_f32_16x16x32_bf16 v[68:71], v[174:177], v[64:67], v[80:83]
	v_mfma_f32_16x16x32_bf16 v[108:111], v[178:181], v[226:229], v[68:71]
	v_mfma_f32_16x16x32_bf16 v[68:71], v[16:19], v[230:233], v[84:87]
	v_mfma_f32_16x16x32_bf16 v[96:99], v[40:43], v[234:237], v[68:71]
	v_mfma_f32_16x16x32_bf16 v[68:71], v[174:177], v[230:233], v[88:91]
	v_mfma_f32_16x16x32_bf16 v[92:95], v[178:181], v[234:237], v[68:71]
	v_mfma_f32_16x16x32_bf16 v[68:71], v[16:19], v[238:241], v[214:217]
	v_mfma_f32_16x16x32_bf16 v[80:83], v[40:43], v[242:245], v[68:71]
	v_mfma_f32_16x16x32_bf16 v[68:71], v[174:177], v[238:241], v[218:221]
	v_mfma_f32_16x16x32_bf16 v[76:79], v[178:181], v[242:245], v[68:71]
	s_setprio 0
	s_setprio 1
	v_mfma_f32_16x16x32_bf16 v[68:71], v[194:197], v[28:31], v[100:103]
	v_mfma_f32_16x16x32_bf16 v[28:31], v[202:205], v[28:31], v[104:107]
	v_mfma_f32_16x16x32_bf16 v[116:119], v[222:225], v[32:35], v[28:31]
	v_mfma_f32_16x16x32_bf16 v[28:31], v[194:197], v[64:67], v[182:185]
	v_mfma_f32_16x16x32_bf16 v[104:107], v[198:201], v[226:229], v[28:31]
	v_mfma_f32_16x16x32_bf16 v[28:31], v[202:205], v[64:67], v[44:47]
	v_mfma_f32_16x16x32_bf16 v[100:103], v[222:225], v[226:229], v[28:31]
	v_mfma_f32_16x16x32_bf16 v[28:31], v[194:197], v[230:233], v[48:51]
	v_mfma_f32_16x16x32_bf16 v[88:91], v[198:201], v[234:237], v[28:31]
	v_mfma_f32_16x16x32_bf16 v[28:31], v[202:205], v[230:233], v[52:55]
	v_mfma_f32_16x16x32_bf16 v[84:87], v[222:225], v[234:237], v[28:31]
	v_mfma_f32_16x16x32_bf16 v[28:31], v[194:197], v[238:241], v[56:59]
	v_mfma_f32_16x16x32_bf16 v[72:75], v[198:201], v[242:245], v[28:31]
	v_mfma_f32_16x16x32_bf16 v[28:31], v[202:205], v[238:241], v[60:63]
	v_mfma_f32_16x16x32_bf16 v[120:123], v[198:201], v[32:35], v[68:71]
	v_mfma_f32_16x16x32_bf16 v[68:71], v[222:225], v[242:245], v[28:31]
	s_setprio 0
	s_barrier
	s_mov_b32 m0, s61
	s_nop 2
	v_lshl_add_u64 v[28:29], v[246:247], 0, s[10:11]
	s_add_u32 s28, s26, 0x18080
	ds_read_b128 v[52:55], v3 offset:49152
	ds_read_b128 v[182:185], v3 offset:50176
	ds_read_b128 v[214:217], v3 offset:51200
	ds_read_b128 v[218:221], v3 offset:52224
	ds_read_b128 v[226:229], v3 offset:53248
	ds_read_b128 v[230:233], v3 offset:54272
	ds_read_b128 v[234:237], v3 offset:55296
	ds_read_b128 v[238:241], v3 offset:56320
	global_load_lds_dwordx4 v[28:29], off
	v_lshl_add_u64 v[28:29], v[248:249], 0, s[10:11]
	s_mov_b32 m0, s4
	s_addc_u32 s29, s27, 0
	global_load_lds_dwordx4 v[28:29], off
	v_lshl_add_u64 v[28:29], s[28:29], 0, v[136:137]
	s_mov_b32 m0, s5
	s_nop 0
	global_load_lds_dwordx4 v[28:29], off
	v_lshl_add_u64 v[28:29], s[28:29], 0, v[132:133]
	s_mov_b32 m0, s7
	s_nop 0
	global_load_lds_dwordx4 v[28:29], off
	v_lshl_add_u64 v[28:29], v[250:251], 0, s[10:11]
	s_mov_b32 m0, s47
	s_nop 0
	global_load_lds_dwordx4 v[28:29], off
	v_lshl_add_u64 v[28:29], v[252:253], 0, s[10:11]
	s_mov_b32 m0, s48
	s_nop 0
	global_load_lds_dwordx4 v[28:29], off
	s_waitcnt vmcnt(8)
	s_waitcnt lgkmcnt(0)
	s_barrier
	s_setprio 1
	s_waitcnt lgkmcnt(0)
	v_mfma_f32_16x16x32_bf16 v[4:7], v[16:19], v[52:55], v[4:7]
	v_mfma_f32_16x16x32_bf16 v[64:67], v[40:43], v[182:185], v[4:7]
	v_mfma_f32_16x16x32_bf16 v[4:7], v[174:177], v[52:55], v[8:11]
	v_mfma_f32_16x16x32_bf16 v[60:63], v[178:181], v[182:185], v[4:7]
	v_mfma_f32_16x16x32_bf16 v[4:7], v[16:19], v[214:217], v[158:161]
	v_mfma_f32_16x16x32_bf16 v[48:51], v[40:43], v[218:221], v[4:7]
	v_mfma_f32_16x16x32_bf16 v[4:7], v[174:177], v[214:217], v[162:165]
	v_mfma_f32_16x16x32_bf16 v[44:47], v[178:181], v[218:221], v[4:7]
	v_mfma_f32_16x16x32_bf16 v[4:7], v[16:19], v[226:229], v[166:169]
	v_mfma_f32_16x16x32_bf16 v[32:35], v[40:43], v[230:233], v[4:7]
	v_mfma_f32_16x16x32_bf16 v[4:7], v[174:177], v[226:229], v[170:173]
	v_mfma_f32_16x16x32_bf16 v[28:31], v[178:181], v[230:233], v[4:7]
	v_mfma_f32_16x16x32_bf16 v[4:7], v[16:19], v[234:237], v[12:15]
	v_mfma_f32_16x16x32_bf16 v[16:19], v[40:43], v[238:241], v[4:7]
	v_mfma_f32_16x16x32_bf16 v[4:7], v[174:177], v[234:237], v[206:209]
	v_mfma_f32_16x16x32_bf16 v[12:15], v[178:181], v[238:241], v[4:7]
	s_setprio 0
	s_setprio 1
	v_mfma_f32_16x16x32_bf16 v[4:7], v[194:197], v[52:55], v[20:23]
	v_mfma_f32_16x16x32_bf16 v[56:59], v[198:201], v[182:185], v[4:7]
	v_mfma_f32_16x16x32_bf16 v[4:7], v[202:205], v[52:55], v[24:27]
	v_mfma_f32_16x16x32_bf16 v[52:55], v[222:225], v[182:185], v[4:7]
	v_mfma_f32_16x16x32_bf16 v[4:7], v[194:197], v[214:217], v[36:39]
	v_mfma_f32_16x16x32_bf16 v[40:43], v[198:201], v[218:221], v[4:7]
	v_mfma_f32_16x16x32_bf16 v[4:7], v[202:205], v[214:217], v[186:189]
	v_mfma_f32_16x16x32_bf16 v[36:39], v[222:225], v[218:221], v[4:7]
	v_mfma_f32_16x16x32_bf16 v[4:7], v[194:197], v[226:229], v[210:213]
	v_mfma_f32_16x16x32_bf16 v[24:27], v[198:201], v[230:233], v[4:7]
	v_mfma_f32_16x16x32_bf16 v[4:7], v[202:205], v[226:229], v[190:193]
	v_mfma_f32_16x16x32_bf16 v[20:23], v[222:225], v[230:233], v[4:7]
	v_mfma_f32_16x16x32_bf16 v[4:7], v[194:197], v[234:237], v[150:153]
	v_mfma_f32_16x16x32_bf16 v[8:11], v[198:201], v[238:241], v[4:7]
	v_mfma_f32_16x16x32_bf16 v[4:7], v[202:205], v[234:237], v[154:157]
	v_mfma_f32_16x16x32_bf16 v[4:7], v[222:225], v[238:241], v[4:7]
	s_setprio 0
	s_barrier
	s_andn2_b64 vcc, exec, s[12:13]
	s_cbranch_vccnz .LBB0_650
	s_barrier

; #define PG8_STAGE(bufoff, gbase, voff) do { _Pragma("unroll") for (int _i = 0; _i < 2; ++_i) \
;         __builtin_amdgcn_global_load_lds((const unsigned*)((const char*)(gbase) + (voff)[_i]), (PG8_LAS unsigned*)(lds + (bufoff) + ldsw + _i * 8192), 16, 0, 0); } while (0)
; #define PG8_LDA(dst, b, h) do { _Pragma("unroll") for (int m = 0; m < 4; ++m) _Pragma("unroll") for (int k = 0; k < 2; ++k) dst[m][k] = *(const PG8_LAS bf16x8*)(lds + PG8_SA(b, h) + aoff + m * 2048 + k * 1024); } while (0)
; #define PG8_LDB(dst, b, h) do { _Pragma("unroll") for (int n = 0; n < 2; ++n) _Pragma("unroll") for (int k = 0; k < 2; ++k) dst[n][k] = *(const PG8_LAS bf16x8*)(lds + PG8_SB(b, h) + boff + n * 2048 + k * 1024); } while (0)
; #define PG8_MMA(ai, bj, At, Bt) do { __builtin_amdgcn_s_setprio(1); _Pragma("unroll") for (int m = 0; m < 4; ++m) _Pragma("unroll") for (int n = 0; n < 2; ++n) _Pragma("unroll") for (int k = 0; k < 2; ++k) \
;         acc[ai][bj][m][n] = __builtin_amdgcn_mfma_f32_16x16x32_bf16(Bt[n][k], At[m][k], acc[ai][bj][m][n], 0, 0, 0); __builtin_amdgcn_s_setprio(0); } while (0)
; #define PG8_WAIT_V(n) asm volatile("s_waitcnt vmcnt(" #n ")" ::: "memory")
; #define PG8_WAIT_L(n) asm volatile("s_waitcnt lgkmcnt(" #n ")" ::: "memory")
; #define PG8_BAR __builtin_amdgcn_s_barrier()
; #define PG8_SCHED __builtin_amdgcn_sched_barrier(0)
; template <class Epi, class Sched, bool ALIGN_EPI>
; __device__ __forceinline__ void gemm_phase(PG8_LAS unsigned char* lds, const Gemm g, const Sched& S, const Epi& E) {
;     ...
;             const bool last = (t == nt - 2);
;             const char* a1 = cA + (size_t)(t + 1) * kstepA;
;             const char* a2 = last ? nA : cA + (size_t)(t + 2) * kstepA; const char* b2 = last ? nB : cB + (size_t)(t + 2) * kstep;
;             const char* a3 = a2 + kstepA; const char* b3 = b2 + kstep;
;             PG8_LDB(B0, 0, 0); PG8_LDB(B1, 0, 1); PG8_SCHED; PG8_LDA(At, 0, 0); PG8_STAGE(PG8_SA(1, 1), a1 + hstepA, voffA);
;             PG8_WAIT_V(8); PG8_WAIT_L(0); PG8_BAR; PG8_MMA(0, 0, At, B0); PG8_MMA(0, 1, At, B1); PG8_BAR; PG8_SCHED;
;             PG8_LDA(At, 0, 1); PG8_STAGE(PG8_SB(0, 0), b2, voffB); PG8_STAGE(PG8_SB(0, 1), b2 + hstepB, voffB); PG8_STAGE(PG8_SA(0, 0), a2, voffA);
;             PG8_WAIT_V(8); PG8_WAIT_L(0); PG8_BAR; PG8_MMA(1, 0, At, B0); PG8_MMA(1, 1, At, B1); PG8_BAR; PG8_SCHED;
.LBB0_778:
	ds_read_b128 v[114:117], v178
	ds_read_b128 v[118:121], v178 offset:1024
	ds_read_b128 v[156:159], v178 offset:2048
	ds_read_b128 v[160:163], v178 offset:3072
	ds_read_b128 v[164:167], v179
	ds_read_b128 v[168:171], v179 offset:1024
	ds_read_b128 v[182:185], v179 offset:2048
	ds_read_b128 v[186:189], v179 offset:3072
	s_add_u32 s36, s34, 0x400000
	s_addc_u32 s37, s35, 0
	s_cmp_eq_u32 s21, 12
	s_cselect_b32 s42, s24, s36
	s_cselect_b32 s43, s25, s37
	s_cselect_b32 s40, s26, s4
	s_cselect_b32 s41, s27, s5
	s_add_u32 s38, s42, 0x200000
	s_addc_u32 s39, s43, 0
	v_lshl_add_u64 v[222:223], s[34:35], 0, v[148:149]
	s_add_i32 m0, s31, 0xc000
	ds_read_b128 v[190:193], v180
	ds_read_b128 v[194:197], v180 offset:1024
	ds_read_b128 v[198:201], v180 offset:2048
	ds_read_b128 v[202:205], v180 offset:3072
	ds_read_b128 v[206:209], v180 offset:4096
	ds_read_b128 v[210:213], v180 offset:5120
	ds_read_b128 v[214:217], v180 offset:6144
	ds_read_b128 v[218:221], v180 offset:7168
	global_load_lds_dwordx4 v[222:223], off
	v_lshl_add_u64 v[222:223], s[34:35], 0, v[150:151]
	s_add_i32 m0, s31, 0xe000
	s_nop 0
	global_load_lds_dwordx4 v[222:223], off
	s_waitcnt vmcnt(8)
	s_waitcnt lgkmcnt(0)
	s_barrier
	s_setprio 1
	s_waitcnt lgkmcnt(0)
	v_mfma_f32_16x16x32_bf16 v[134:137], v[114:117], v[190:193], v[134:137]
	v_mfma_f32_16x16x32_bf16 v[134:137], v[118:121], v[194:197], v[134:137]
	v_mfma_f32_16x16x32_bf16 v[130:133], v[156:159], v[190:193], v[130:133]
	v_mfma_f32_16x16x32_bf16 v[130:133], v[160:163], v[194:197], v[130:133]
	v_mfma_f32_16x16x32_bf16 v[126:129], v[114:117], v[198:201], v[126:129]
	v_mfma_f32_16x16x32_bf16 v[126:129], v[118:121], v[202:205], v[126:129]
	v_mfma_f32_16x16x32_bf16 v[122:125], v[156:159], v[198:201], v[122:125]
	v_mfma_f32_16x16x32_bf16 v[122:125], v[160:163], v[202:205], v[122:125]
	v_mfma_f32_16x16x32_bf16 v[110:113], v[114:117], v[206:209], v[110:113]
	v_mfma_f32_16x16x32_bf16 v[110:113], v[118:121], v[210:213], v[110:113]
	v_mfma_f32_16x16x32_bf16 v[106:109], v[156:159], v[206:209], v[106:109]
	v_mfma_f32_16x16x32_bf16 v[106:109], v[160:163], v[210:213], v[106:109]
	v_mfma_f32_16x16x32_bf16 v[102:105], v[114:117], v[214:217], v[102:105]
	v_mfma_f32_16x16x32_bf16 v[102:105], v[118:121], v[218:221], v[102:105]
	v_mfma_f32_16x16x32_bf16 v[98:101], v[156:159], v[214:217], v[98:101]
	v_mfma_f32_16x16x32_bf16 v[98:101], v[160:163], v[218:221], v[98:101]
	s_setprio 0
	s_setprio 1
	v_mfma_f32_16x16x32_bf16 v[62:65], v[164:167], v[190:193], v[62:65]
	v_mfma_f32_16x16x32_bf16 v[62:65], v[168:171], v[194:197], v[62:65]
	v_mfma_f32_16x16x32_bf16 v[58:61], v[182:185], v[190:193], v[58:61]
	v_mfma_f32_16x16x32_bf16 v[58:61], v[186:189], v[194:197], v[58:61]
	v_mfma_f32_16x16x32_bf16 v[54:57], v[164:167], v[198:201], v[54:57]
	v_mfma_f32_16x16x32_bf16 v[54:57], v[168:171], v[202:205], v[54:57]
	v_mfma_f32_16x16x32_bf16 v[50:53], v[182:185], v[198:201], v[50:53]
	v_mfma_f32_16x16x32_bf16 v[50:53], v[186:189], v[202:205], v[50:53]
	v_mfma_f32_16x16x32_bf16 v[46:49], v[164:167], v[206:209], v[46:49]
	v_mfma_f32_16x16x32_bf16 v[46:49], v[168:171], v[210:213], v[46:49]
	v_mfma_f32_16x16x32_bf16 v[42:45], v[182:185], v[206:209], v[42:45]
	v_mfma_f32_16x16x32_bf16 v[42:45], v[186:189], v[210:213], v[42:45]
	v_mfma_f32_16x16x32_bf16 v[38:41], v[164:167], v[214:217], v[38:41]
	v_mfma_f32_16x16x32_bf16 v[38:41], v[168:171], v[218:221], v[38:41]
	v_mfma_f32_16x16x32_bf16 v[34:37], v[182:185], v[214:217], v[34:37]
	v_mfma_f32_16x16x32_bf16 v[34:37], v[186:189], v[218:221], v[34:37]
	s_setprio 0
	s_barrier
	s_add_i32 s2, s52, s3
	v_lshl_add_u64 v[222:223], s[40:41], 0, v[140:141]
	s_mov_b32 m0, s2
	ds_read_b128 v[190:193], v180 offset:16384
	ds_read_b128 v[194:197], v180 offset:17408
	ds_read_b128 v[198:201], v180 offset:18432
	ds_read_b128 v[202:205], v180 offset:19456
	ds_read_b128 v[206:209], v180 offset:20480
	ds_read_b128 v[210:213], v180 offset:21504
	ds_read_b128 v[214:217], v180 offset:22528
	ds_read_b128 v[218:221], v180 offset:23552
	global_load_lds_dwordx4 v[222:223], off
	s_add_i32 m0, s2, 0x2000
	s_add_u32 s34, s40, 0x40000
	v_lshl_add_u64 v[224:225], s[40:41], 0, v[144:145]
	s_addc_u32 s35, s41, 0
	s_add_i32 s2, s53, s3
	global_load_lds_dwordx4 v[224:225], off
	v_lshl_add_u64 v[226:227], s[34:35], 0, v[140:141]
	s_mov_b32 m0, s2
	s_nop 0
	global_load_lds_dwordx4 v[226:227], off
	v_lshl_add_u64 v[226:227], s[34:35], 0, v[144:145]
	s_add_i32 m0, s2, 0x2000
	s_nop 0
	global_load_lds_dwordx4 v[226:227], off
	v_lshl_add_u64 v[226:227], s[42:43], 0, v[138:139]
	s_mov_b32 m0, s31
	s_nop 0
	global_load_lds_dwordx4 v[226:227], off
	v_lshl_add_u64 v[226:227], s[42:43], 0, v[142:143]
	s_mov_b32 m0, s44
	s_nop 0
	global_load_lds_dwordx4 v[226:227], off
	s_waitcnt vmcnt(8)
	s_waitcnt lgkmcnt(0)
	s_barrier
; #define PG8_STAGE(bufoff, gbase, voff) do { _Pragma("unroll") for (int _i = 0; _i < 2; ++_i) \
;         __builtin_amdgcn_global_load_lds((const unsigned*)((const char*)(gbase) + (voff)[_i]), (PG8_LAS unsigned*)(lds + (bufoff) + ldsw + _i * 8192), 16, 0, 0); } while (0)
; #define PG8_LDA(dst, b, h) do { _Pragma("unroll") for (int m = 0; m < 4; ++m) _Pragma("unroll") for (int k = 0; k < 2; ++k) dst[m][k] = *(const PG8_LAS bf16x8*)(lds + PG8_SA(b, h) + aoff + m * 2048 + k * 1024); } while (0)
; #define PG8_LDB(dst, b, h) do { _Pragma("unroll") for (int n = 0; n < 2; ++n) _Pragma("unroll") for (int k = 0; k < 2; ++k) dst[n][k] = *(const PG8_LAS bf16x8*)(lds + PG8_SB(b, h) + boff + n * 2048 + k * 1024); } while (0)
; #define PG8_MMA(ai, bj, At, Bt) do { __builtin_amdgcn_s_setprio(1); _Pragma("unroll") for (int m = 0; m < 4; ++m) _Pragma("unroll") for (int n = 0; n < 2; ++n) _Pragma("unroll") for (int k = 0; k < 2; ++k) \
;         acc[ai][bj][m][n] = __builtin_amdgcn_mfma_f32_16x16x32_bf16(Bt[n][k], At[m][k], acc[ai][bj][m][n], 0, 0, 0); __builtin_amdgcn_s_setprio(0); } while (0)
; #define PG8_WAIT_V(n) asm volatile("s_waitcnt vmcnt(" #n ")" ::: "memory")
; #define PG8_WAIT_L(n) asm volatile("s_waitcnt lgkmcnt(" #n ")" ::: "memory")
; #define PG8_BAR __builtin_amdgcn_s_barrier()
; #define PG8_SCHED __builtin_amdgcn_sched_barrier(0)
; template <class Epi, class Sched, bool ALIGN_EPI>
; __device__ __forceinline__ void gemm_phase(PG8_LAS unsigned char* lds, const Gemm g, const Sched& S, const Epi& E) {
;     ...
;             PG8_WAIT_V(8); PG8_WAIT_L(0); PG8_BAR; PG8_MMA(1, 0, At, B0); PG8_MMA(1, 1, At, B1); PG8_BAR; PG8_SCHED;
;             PG8_LDB(B0, 1, 0); PG8_LDB(B1, 1, 1); PG8_SCHED; PG8_LDA(At, 1, 0); PG8_STAGE(PG8_SA(0, 1), a2 + hstepA, voffA);
;             PG8_WAIT_V(8); PG8_WAIT_L(0); PG8_BAR; PG8_MMA(0, 0, At, B0); PG8_MMA(0, 1, At, B1); PG8_BAR; PG8_SCHED;
	s_setprio 1
	s_waitcnt lgkmcnt(0)
	v_mfma_f32_16x16x32_bf16 v[94:97], v[114:117], v[190:193], v[94:97]
	v_mfma_f32_16x16x32_bf16 v[94:97], v[118:121], v[194:197], v[94:97]
	v_mfma_f32_16x16x32_bf16 v[90:93], v[156:159], v[190:193], v[90:93]
	v_mfma_f32_16x16x32_bf16 v[90:93], v[160:163], v[194:197], v[90:93]
	v_mfma_f32_16x16x32_bf16 v[86:89], v[114:117], v[198:201], v[86:89]
	v_mfma_f32_16x16x32_bf16 v[86:89], v[118:121], v[202:205], v[86:89]
	v_mfma_f32_16x16x32_bf16 v[82:85], v[156:159], v[198:201], v[82:85]
	v_mfma_f32_16x16x32_bf16 v[82:85], v[160:163], v[202:205], v[82:85]
	v_mfma_f32_16x16x32_bf16 v[78:81], v[114:117], v[206:209], v[78:81]
	v_mfma_f32_16x16x32_bf16 v[78:81], v[118:121], v[210:213], v[78:81]
	v_mfma_f32_16x16x32_bf16 v[74:77], v[156:159], v[206:209], v[74:77]
	v_mfma_f32_16x16x32_bf16 v[74:77], v[160:163], v[210:213], v[74:77]
	v_mfma_f32_16x16x32_bf16 v[70:73], v[114:117], v[214:217], v[70:73]
	v_mfma_f32_16x16x32_bf16 v[70:73], v[118:121], v[218:221], v[70:73]
	v_mfma_f32_16x16x32_bf16 v[66:69], v[156:159], v[214:217], v[66:69]
	v_mfma_f32_16x16x32_bf16 v[66:69], v[160:163], v[218:221], v[66:69]
	s_setprio 0
	s_setprio 1
	v_mfma_f32_16x16x32_bf16 v[30:33], v[164:167], v[190:193], v[30:33]
	v_mfma_f32_16x16x32_bf16 v[30:33], v[168:171], v[194:197], v[30:33]
	v_mfma_f32_16x16x32_bf16 v[26:29], v[182:185], v[190:193], v[26:29]
	v_mfma_f32_16x16x32_bf16 v[26:29], v[186:189], v[194:197], v[26:29]
	v_mfma_f32_16x16x32_bf16 v[22:25], v[164:167], v[198:201], v[22:25]
	v_mfma_f32_16x16x32_bf16 v[22:25], v[168:171], v[202:205], v[22:25]
	v_mfma_f32_16x16x32_bf16 v[18:21], v[182:185], v[198:201], v[18:21]
	v_mfma_f32_16x16x32_bf16 v[18:21], v[186:189], v[202:205], v[18:21]
	v_mfma_f32_16x16x32_bf16 v[14:17], v[164:167], v[206:209], v[14:17]
	v_mfma_f32_16x16x32_bf16 v[14:17], v[168:171], v[210:213], v[14:17]
	v_mfma_f32_16x16x32_bf16 v[10:13], v[182:185], v[206:209], v[10:13]
	v_mfma_f32_16x16x32_bf16 v[10:13], v[186:189], v[210:213], v[10:13]
	v_mfma_f32_16x16x32_bf16 v[6:9], v[164:167], v[214:217], v[6:9]
	v_mfma_f32_16x16x32_bf16 v[6:9], v[168:171], v[218:221], v[6:9]
	v_mfma_f32_16x16x32_bf16 v[2:5], v[182:185], v[214:217], v[2:5]
	v_mfma_f32_16x16x32_bf16 v[2:5], v[186:189], v[218:221], v[2:5]
	s_setprio 0
	s_barrier
	s_add_i32 s2, 0, 0x18000
	s_add_i32 s23, 0, 0x1c000
	v_add_u32_e32 v160, s2, v175
	v_add_u32_e32 v181, s23, v175
	ds_read_b128 v[114:117], v160
	ds_read_b128 v[118:121], v160 offset:1024
	ds_read_b128 v[156:159], v160 offset:2048
	ds_read_b128 v[160:163], v160 offset:3072
	ds_read_b128 v[164:167], v181
	ds_read_b128 v[168:171], v181 offset:1024
	ds_read_b128 v[182:185], v181 offset:2048
	ds_read_b128 v[186:189], v181 offset:3072
	s_add_u32 s34, s42, 0x1000
	s_addc_u32 s35, s43, 0
	s_mov_b32 m0, s45
	v_lshl_add_u64 v[226:227], s[34:35], 0, v[138:139]
	ds_read_b128 v[190:193], v180 offset:32768
	ds_read_b128 v[194:197], v180 offset:33792
	ds_read_b128 v[198:201], v180 offset:34816
	ds_read_b128 v[202:205], v180 offset:35840
	ds_read_b128 v[206:209], v180 offset:36864
	ds_read_b128 v[210:213], v180 offset:37888
	ds_read_b128 v[214:217], v180 offset:38912
	ds_read_b128 v[218:221], v180 offset:39936
	global_load_lds_dwordx4 v[226:227], off
	v_lshl_add_u64 v[226:227], s[34:35], 0, v[142:143]
	s_mov_b32 m0, s46
	s_nop 0
	global_load_lds_dwordx4 v[226:227], off
	s_waitcnt vmcnt(8)
	s_waitcnt lgkmcnt(0)
	s_barrier
	s_setprio 1
	s_waitcnt lgkmcnt(0)
	v_mfma_f32_16x16x32_bf16 v[134:137], v[114:117], v[190:193], v[134:137]
	v_mfma_f32_16x16x32_bf16 v[134:137], v[118:121], v[194:197], v[134:137]
	v_mfma_f32_16x16x32_bf16 v[130:133], v[156:159], v[190:193], v[130:133]
	v_mfma_f32_16x16x32_bf16 v[130:133], v[160:163], v[194:197], v[130:133]
	v_mfma_f32_16x16x32_bf16 v[126:129], v[114:117], v[198:201], v[126:129]
	v_mfma_f32_16x16x32_bf16 v[126:129], v[118:121], v[202:205], v[126:129]
	v_mfma_f32_16x16x32_bf16 v[122:125], v[156:159], v[198:201], v[122:125]
	v_mfma_f32_16x16x32_bf16 v[122:125], v[160:163], v[202:205], v[122:125]
	v_mfma_f32_16x16x32_bf16 v[110:113], v[114:117], v[206:209], v[110:113]
	v_mfma_f32_16x16x32_bf16 v[110:113], v[118:121], v[210:213], v[110:113]
	v_mfma_f32_16x16x32_bf16 v[106:109], v[156:159], v[206:209], v[106:109]
	v_mfma_f32_16x16x32_bf16 v[106:109], v[160:163], v[210:213], v[106:109]
	v_mfma_f32_16x16x32_bf16 v[102:105], v[114:117], v[214:217], v[102:105]
	v_mfma_f32_16x16x32_bf16 v[102:105], v[118:121], v[218:221], v[102:105]
	v_mfma_f32_16x16x32_bf16 v[98:101], v[156:159], v[214:217], v[98:101]
	v_mfma_f32_16x16x32_bf16 v[98:101], v[160:163], v[218:221], v[98:101]
	s_setprio 0
	s_setprio 1
	v_mfma_f32_16x16x32_bf16 v[62:65], v[164:167], v[190:193], v[62:65]
	v_mfma_f32_16x16x32_bf16 v[62:65], v[168:171], v[194:197], v[62:65]
	v_mfma_f32_16x16x32_bf16 v[58:61], v[182:185], v[190:193], v[58:61]
	v_mfma_f32_16x16x32_bf16 v[58:61], v[186:189], v[194:197], v[58:61]
	v_mfma_f32_16x16x32_bf16 v[54:57], v[164:167], v[198:201], v[54:57]
	v_mfma_f32_16x16x32_bf16 v[54:57], v[168:171], v[202:205], v[54:57]
	v_mfma_f32_16x16x32_bf16 v[50:53], v[182:185], v[198:201], v[50:53]
	v_mfma_f32_16x16x32_bf16 v[50:53], v[186:189], v[202:205], v[50:53]
	v_mfma_f32_16x16x32_bf16 v[46:49], v[164:167], v[206:209], v[46:49]
	v_mfma_f32_16x16x32_bf16 v[46:49], v[168:171], v[210:213], v[46:49]
	v_mfma_f32_16x16x32_bf16 v[42:45], v[182:185], v[206:209], v[42:45]
	v_mfma_f32_16x16x32_bf16 v[42:45], v[186:189], v[210:213], v[42:45]
	v_mfma_f32_16x16x32_bf16 v[38:41], v[164:167], v[214:217], v[38:41]
	v_mfma_f32_16x16x32_bf16 v[38:41], v[168:171], v[218:221], v[38:41]
	v_mfma_f32_16x16x32_bf16 v[34:37], v[182:185], v[214:217], v[34:37]
	v_mfma_f32_16x16x32_bf16 v[34:37], v[186:189], v[218:221], v[34:37]
	s_setprio 0
	s_barrier
; #define PG8_STAGE(bufoff, gbase, voff) do { _Pragma("unroll") for (int _i = 0; _i < 2; ++_i) \
;         __builtin_amdgcn_global_load_lds((const unsigned*)((const char*)(gbase) + (voff)[_i]), (PG8_LAS unsigned*)(lds + (bufoff) + ldsw + _i * 8192), 16, 0, 0); } while (0)
; #define PG8_LDA(dst, b, h) do { _Pragma("unroll") for (int m = 0; m < 4; ++m) _Pragma("unroll") for (int k = 0; k < 2; ++k) dst[m][k] = *(const PG8_LAS bf16x8*)(lds + PG8_SA(b, h) + aoff + m * 2048 + k * 1024); } while (0)
; #define PG8_MMA(ai, bj, At, Bt) do { __builtin_amdgcn_s_setprio(1); _Pragma("unroll") for (int m = 0; m < 4; ++m) _Pragma("unroll") for (int n = 0; n < 2; ++n) _Pragma("unroll") for (int k = 0; k < 2; ++k) \
;         acc[ai][bj][m][n] = __builtin_amdgcn_mfma_f32_16x16x32_bf16(Bt[n][k], At[m][k], acc[ai][bj][m][n], 0, 0, 0); __builtin_amdgcn_s_setprio(0); } while (0)
; #define PG8_WAIT_V(n) asm volatile("s_waitcnt vmcnt(" #n ")" ::: "memory")
; #define PG8_WAIT_L(n) asm volatile("s_waitcnt lgkmcnt(" #n ")" ::: "memory")
; #define PG8_BAR __builtin_amdgcn_s_barrier()
; #define PG8_SCHED __builtin_amdgcn_sched_barrier(0)
; template <class Epi, class Sched, bool ALIGN_EPI>
; __device__ __forceinline__ void gemm_phase(PG8_LAS unsigned char* lds, const Gemm g, const Sched& S, const Epi& E) {
;     ...
;             PG8_LDA(At, 1, 1); PG8_STAGE(PG8_SB(1, 0), b3, voffB); PG8_STAGE(PG8_SB(1, 1), b3 + hstepB, voffB); PG8_STAGE(PG8_SA(1, 0), a3, voffA);
;             PG8_WAIT_V(8); PG8_WAIT_L(0); PG8_BAR; PG8_MMA(1, 0, At, B0); PG8_MMA(1, 1, At, B1); PG8_BAR; PG8_SCHED;
;         }
;         if constexpr (ALIGN_EPI) { if (wr == 0) PG8_BAR; }
	s_add_i32 s2, s2, s3
	v_lshl_add_u64 v[222:223], v[222:223], 0, s[16:17]
	s_mov_b32 m0, s2
	ds_read_b128 v[190:193], v180 offset:49152
	ds_read_b128 v[194:197], v180 offset:50176
	ds_read_b128 v[198:201], v180 offset:51200
	ds_read_b128 v[202:205], v180 offset:52224
	ds_read_b128 v[206:209], v180 offset:53248
	ds_read_b128 v[210:213], v180 offset:54272
	ds_read_b128 v[214:217], v180 offset:55296
	ds_read_b128 v[218:221], v180 offset:56320
	global_load_lds_dwordx4 v[222:223], off
	s_add_i32 m0, s2, 0x2000
	s_add_u32 s34, s40, 0x40080
	v_lshl_add_u64 v[222:223], v[224:225], 0, s[16:17]
	s_addc_u32 s35, s41, 0
	s_add_i32 s2, s23, s3
	global_load_lds_dwordx4 v[222:223], off
	v_lshl_add_u64 v[222:223], s[34:35], 0, v[140:141]
	s_mov_b32 m0, s2
	s_nop 0
	global_load_lds_dwordx4 v[222:223], off
	v_lshl_add_u64 v[222:223], s[34:35], 0, v[144:145]
	s_add_i32 m0, s2, 0x2000
	s_nop 0
	global_load_lds_dwordx4 v[222:223], off
	v_lshl_add_u64 v[222:223], s[38:39], 0, v[138:139]
	s_mov_b32 m0, s48
	s_nop 0
	global_load_lds_dwordx4 v[222:223], off
	v_lshl_add_u64 v[222:223], s[38:39], 0, v[142:143]
	s_mov_b32 m0, s49
	s_nop 0
	global_load_lds_dwordx4 v[222:223], off
	s_waitcnt vmcnt(8)
	s_waitcnt lgkmcnt(0)
	s_barrier
	s_setprio 1
	s_waitcnt lgkmcnt(0)
	v_mfma_f32_16x16x32_bf16 v[94:97], v[114:117], v[190:193], v[94:97]
	v_mfma_f32_16x16x32_bf16 v[94:97], v[118:121], v[194:197], v[94:97]
	v_mfma_f32_16x16x32_bf16 v[90:93], v[156:159], v[190:193], v[90:93]
	v_mfma_f32_16x16x32_bf16 v[90:93], v[160:163], v[194:197], v[90:93]
	v_mfma_f32_16x16x32_bf16 v[86:89], v[114:117], v[198:201], v[86:89]
	v_mfma_f32_16x16x32_bf16 v[86:89], v[118:121], v[202:205], v[86:89]
	v_mfma_f32_16x16x32_bf16 v[82:85], v[156:159], v[198:201], v[82:85]
	v_mfma_f32_16x16x32_bf16 v[82:85], v[160:163], v[202:205], v[82:85]
	v_mfma_f32_16x16x32_bf16 v[78:81], v[114:117], v[206:209], v[78:81]
	v_mfma_f32_16x16x32_bf16 v[78:81], v[118:121], v[210:213], v[78:81]
	v_mfma_f32_16x16x32_bf16 v[74:77], v[156:159], v[206:209], v[74:77]
	v_mfma_f32_16x16x32_bf16 v[74:77], v[160:163], v[210:213], v[74:77]
	v_mfma_f32_16x16x32_bf16 v[70:73], v[114:117], v[214:217], v[70:73]
	v_mfma_f32_16x16x32_bf16 v[70:73], v[118:121], v[218:221], v[70:73]
	v_mfma_f32_16x16x32_bf16 v[66:69], v[156:159], v[214:217], v[66:69]
	v_mfma_f32_16x16x32_bf16 v[66:69], v[160:163], v[218:221], v[66:69]
	s_setprio 0
	s_setprio 1
	v_mfma_f32_16x16x32_bf16 v[30:33], v[164:167], v[190:193], v[30:33]
	v_mfma_f32_16x16x32_bf16 v[30:33], v[168:171], v[194:197], v[30:33]
	v_mfma_f32_16x16x32_bf16 v[26:29], v[182:185], v[190:193], v[26:29]
	v_mfma_f32_16x16x32_bf16 v[26:29], v[186:189], v[194:197], v[26:29]
	v_mfma_f32_16x16x32_bf16 v[22:25], v[164:167], v[198:201], v[22:25]
	v_mfma_f32_16x16x32_bf16 v[22:25], v[168:171], v[202:205], v[22:25]
	v_mfma_f32_16x16x32_bf16 v[18:21], v[182:185], v[198:201], v[18:21]
	v_mfma_f32_16x16x32_bf16 v[18:21], v[186:189], v[202:205], v[18:21]
	v_mfma_f32_16x16x32_bf16 v[14:17], v[164:167], v[206:209], v[14:17]
	v_mfma_f32_16x16x32_bf16 v[14:17], v[168:171], v[210:213], v[14:17]
	v_mfma_f32_16x16x32_bf16 v[10:13], v[182:185], v[206:209], v[10:13]
	v_mfma_f32_16x16x32_bf16 v[10:13], v[186:189], v[210:213], v[10:13]
	v_mfma_f32_16x16x32_bf16 v[6:9], v[164:167], v[214:217], v[6:9]
	v_mfma_f32_16x16x32_bf16 v[6:9], v[168:171], v[218:221], v[6:9]
	v_mfma_f32_16x16x32_bf16 v[2:5], v[182:185], v[214:217], v[2:5]
	v_mfma_f32_16x16x32_bf16 v[2:5], v[186:189], v[218:221], v[2:5]
	s_setprio 0
	s_barrier
	s_add_i32 s21, s21, 2
	s_add_u32 s4, s4, 0x100
	s_addc_u32 s5, s5, 0
	s_cmp_gt_u32 s21, 13
	s_mov_b64 s[34:35], s[36:37]
	s_cbranch_scc0 .LBB0_778
	s_and_b64 vcc, exec, s[18:19]
	s_cbranch_vccz .LBB0_781
	s_barrier

; #define PG8_STAGE(bufoff, gbase, voff) do { _Pragma("unroll") for (int _i = 0; _i < 2; ++_i) \
;         __builtin_amdgcn_global_load_lds((const unsigned*)((const char*)(gbase) + (voff)[_i]), (PG8_LAS unsigned*)(lds + (bufoff) + ldsw + _i * 8192), 16, 0, 0); } while (0)
; #define PG8_LDA(dst, b, h) do { _Pragma("unroll") for (int m = 0; m < 4; ++m) _Pragma("unroll") for (int k = 0; k < 2; ++k) dst[m][k] = *(const PG8_LAS bf16x8*)(lds + PG8_SA(b, h) + aoff + m * 2048 + k * 1024); } while (0)
; #define PG8_LDB(dst, b, h) do { _Pragma("unroll") for (int n = 0; n < 2; ++n) _Pragma("unroll") for (int k = 0; k < 2; ++k) dst[n][k] = *(const PG8_LAS bf16x8*)(lds + PG8_SB(b, h) + boff + n * 2048 + k * 1024); } while (0)
; #define PG8_MMA(ai, bj, At, Bt) do { __builtin_amdgcn_s_setprio(1); _Pragma("unroll") for (int m = 0; m < 4; ++m) _Pragma("unroll") for (int n = 0; n < 2; ++n) _Pragma("unroll") for (int k = 0; k < 2; ++k) \
;         acc[ai][bj][m][n] = __builtin_amdgcn_mfma_f32_16x16x32_bf16(Bt[n][k], At[m][k], acc[ai][bj][m][n], 0, 0, 0); __builtin_amdgcn_s_setprio(0); } while (0)
; #define PG8_WAIT_V(n) asm volatile("s_waitcnt vmcnt(" #n ")" ::: "memory")
; #define PG8_WAIT_L(n) asm volatile("s_waitcnt lgkmcnt(" #n ")" ::: "memory")
; #define PG8_BAR __builtin_amdgcn_s_barrier()
; #define PG8_SCHED __builtin_amdgcn_sched_barrier(0)
; template <class Epi, class Sched, bool ALIGN_EPI>
; __device__ __forceinline__ void gemm_phase(PG8_LAS unsigned char* lds, const Gemm g, const Sched& S, const Epi& E) {
;     ...
;             const bool last = (t == nt - 2);
;             const char* a1 = cA + (size_t)(t + 1) * kstepA;
;             const char* a2 = last ? nA : cA + (size_t)(t + 2) * kstepA; const char* b2 = last ? nB : cB + (size_t)(t + 2) * kstep;
;             const char* a3 = a2 + kstepA; const char* b3 = b2 + kstep;
;             PG8_LDB(B0, 0, 0); PG8_LDB(B1, 0, 1); PG8_SCHED; PG8_LDA(At, 0, 0); PG8_STAGE(PG8_SA(1, 1), a1 + hstepA, voffA);
;             PG8_WAIT_V(8); PG8_WAIT_L(0); PG8_BAR; PG8_MMA(0, 0, At, B0); PG8_MMA(0, 1, At, B1); PG8_BAR; PG8_SCHED;
;             PG8_LDA(At, 0, 1); PG8_STAGE(PG8_SB(0, 0), b2, voffB); PG8_STAGE(PG8_SB(0, 1), b2 + hstepB, voffB); PG8_STAGE(PG8_SA(0, 0), a2, voffA);
;             PG8_WAIT_V(8); PG8_WAIT_L(0); PG8_BAR; PG8_MMA(1, 0, At, B0); PG8_MMA(1, 1, At, B1); PG8_BAR; PG8_SCHED;
.LBB0_839:
	v_add_u32_e32 v3, s55, v155
	ds_read_b128 v[160:163], v3
	ds_read_b128 v[164:167], v3 offset:1024
	ds_read_b128 v[168:171], v3 offset:2048
	ds_read_b128 v[174:177], v3 offset:3072
	v_add_u32_e32 v3, s56, v155
	s_add_u32 s2, s38, s40
	ds_read_b128 v[178:181], v3
	ds_read_b128 v[182:185], v3 offset:1024
	ds_read_b128 v[186:189], v3 offset:2048
	ds_read_b128 v[190:193], v3 offset:3072
	s_addc_u32 s42, s39, s41
	s_add_u32 s2, s2, 0x100
	s_addc_u32 s42, s42, 0
	s_add_u32 s63, s27, s40
	s_addc_u32 s43, s29, s41
	s_cmpk_eq_i32 s40, 0xf00
	s_cselect_b32 s45, s31, s42
	s_cselect_b32 s44, s30, s2
	s_cselect_b32 s43, s35, s43
	s_cselect_b32 s42, s34, s63
	v_lshl_add_u64 v[4:5], v[150:151], 0, s[40:41]
	s_add_i32 m0, s37, 0xc000
	ds_read_b128 v[194:197], v159
	ds_read_b128 v[198:201], v159 offset:1024
	ds_read_b128 v[202:205], v159 offset:2048
	ds_read_b128 v[206:209], v159 offset:3072
	ds_read_b128 v[210:213], v159 offset:4096
	ds_read_b128 v[214:217], v159 offset:5120
	ds_read_b128 v[218:221], v159 offset:6144
	ds_read_b128 v[222:225], v159 offset:7168
	global_load_lds_dwordx4 v[4:5], off
	v_lshl_add_u64 v[4:5], v[152:153], 0, s[40:41]
	s_add_i32 m0, s37, 0xe000
	s_nop 0
	global_load_lds_dwordx4 v[4:5], off
	s_waitcnt vmcnt(8)
	s_waitcnt lgkmcnt(0)
	s_barrier
	s_setprio 1
	s_waitcnt lgkmcnt(0)
	v_mfma_f32_16x16x32_bf16 v[130:133], v[160:163], v[194:197], v[130:133]
	v_mfma_f32_16x16x32_bf16 v[130:133], v[164:167], v[198:201], v[130:133]
	v_mfma_f32_16x16x32_bf16 v[126:129], v[168:171], v[194:197], v[126:129]
	v_mfma_f32_16x16x32_bf16 v[126:129], v[174:177], v[198:201], v[126:129]
	v_mfma_f32_16x16x32_bf16 v[114:117], v[160:163], v[202:205], v[114:117]
	v_mfma_f32_16x16x32_bf16 v[114:117], v[164:167], v[206:209], v[114:117]
	v_mfma_f32_16x16x32_bf16 v[110:113], v[168:171], v[202:205], v[110:113]
	v_mfma_f32_16x16x32_bf16 v[110:113], v[174:177], v[206:209], v[110:113]
	v_mfma_f32_16x16x32_bf16 v[98:101], v[160:163], v[210:213], v[98:101]
	v_mfma_f32_16x16x32_bf16 v[98:101], v[164:167], v[214:217], v[98:101]
	v_mfma_f32_16x16x32_bf16 v[94:97], v[168:171], v[210:213], v[94:97]
	v_mfma_f32_16x16x32_bf16 v[94:97], v[174:177], v[214:217], v[94:97]
	v_mfma_f32_16x16x32_bf16 v[82:85], v[160:163], v[218:221], v[82:85]
	v_mfma_f32_16x16x32_bf16 v[82:85], v[164:167], v[222:225], v[82:85]
	v_mfma_f32_16x16x32_bf16 v[78:81], v[168:171], v[218:221], v[78:81]
	v_mfma_f32_16x16x32_bf16 v[78:81], v[174:177], v[222:225], v[78:81]
	s_setprio 0
	s_setprio 1
	v_mfma_f32_16x16x32_bf16 v[122:125], v[178:181], v[194:197], v[122:125]
	v_mfma_f32_16x16x32_bf16 v[122:125], v[182:185], v[198:201], v[122:125]
	v_mfma_f32_16x16x32_bf16 v[118:121], v[186:189], v[194:197], v[118:121]
	v_mfma_f32_16x16x32_bf16 v[118:121], v[190:193], v[198:201], v[118:121]
	v_mfma_f32_16x16x32_bf16 v[106:109], v[178:181], v[202:205], v[106:109]
	v_mfma_f32_16x16x32_bf16 v[106:109], v[182:185], v[206:209], v[106:109]
	v_mfma_f32_16x16x32_bf16 v[102:105], v[186:189], v[202:205], v[102:105]
	v_mfma_f32_16x16x32_bf16 v[102:105], v[190:193], v[206:209], v[102:105]
	v_mfma_f32_16x16x32_bf16 v[90:93], v[178:181], v[210:213], v[90:93]
	v_mfma_f32_16x16x32_bf16 v[90:93], v[182:185], v[214:217], v[90:93]
	v_mfma_f32_16x16x32_bf16 v[86:89], v[186:189], v[210:213], v[86:89]
	v_mfma_f32_16x16x32_bf16 v[86:89], v[190:193], v[214:217], v[86:89]
	v_mfma_f32_16x16x32_bf16 v[74:77], v[178:181], v[218:221], v[74:77]
	v_mfma_f32_16x16x32_bf16 v[74:77], v[182:185], v[222:225], v[74:77]
	v_mfma_f32_16x16x32_bf16 v[70:73], v[186:189], v[218:221], v[70:73]
	v_mfma_f32_16x16x32_bf16 v[70:73], v[190:193], v[222:225], v[70:73]
	s_setprio 0
	s_barrier
	s_add_i32 s2, s55, s4
	v_lshl_add_u64 v[226:227], s[42:43], 0, v[136:137]
	s_mov_b32 m0, s2
	ds_read_b128 v[194:197], v159 offset:16384
	ds_read_b128 v[198:201], v159 offset:17408
	ds_read_b128 v[202:205], v159 offset:18432
	ds_read_b128 v[206:209], v159 offset:19456
	ds_read_b128 v[210:213], v159 offset:20480
	ds_read_b128 v[214:217], v159 offset:21504
	ds_read_b128 v[218:221], v159 offset:22528
	ds_read_b128 v[222:225], v159 offset:23552
	global_load_lds_dwordx4 v[226:227], off
	s_add_i32 m0, s2, 0x2000
	s_add_u32 s64, s42, 0x80000
	v_lshl_add_u64 v[228:229], s[42:43], 0, v[140:141]
	s_addc_u32 s65, s43, 0
	s_add_i32 s2, s56, s4
	global_load_lds_dwordx4 v[228:229], off
	v_lshl_add_u64 v[4:5], s[64:65], 0, v[136:137]
	s_mov_b32 m0, s2
	v_lshl_add_u64 v[230:231], s[44:45], 0, v[134:135]
	global_load_lds_dwordx4 v[4:5], off
	v_lshl_add_u64 v[4:5], s[64:65], 0, v[140:141]
	s_add_i32 m0, s2, 0x2000
	v_lshl_add_u64 v[232:233], s[44:45], 0, v[138:139]
	global_load_lds_dwordx4 v[4:5], off
	s_mov_b32 m0, s37
	s_nop 0
	global_load_lds_dwordx4 v[230:231], off
	s_mov_b32 m0, s48
	s_nop 0
	global_load_lds_dwordx4 v[232:233], off
	s_waitcnt vmcnt(8)
	s_waitcnt lgkmcnt(0)
	s_barrier
; #define PG8_STAGE(bufoff, gbase, voff) do { _Pragma("unroll") for (int _i = 0; _i < 2; ++_i) \
;         __builtin_amdgcn_global_load_lds((const unsigned*)((const char*)(gbase) + (voff)[_i]), (PG8_LAS unsigned*)(lds + (bufoff) + ldsw + _i * 8192), 16, 0, 0); } while (0)
; #define PG8_LDA(dst, b, h) do { _Pragma("unroll") for (int m = 0; m < 4; ++m) _Pragma("unroll") for (int k = 0; k < 2; ++k) dst[m][k] = *(const PG8_LAS bf16x8*)(lds + PG8_SA(b, h) + aoff + m * 2048 + k * 1024); } while (0)
; #define PG8_LDB(dst, b, h) do { _Pragma("unroll") for (int n = 0; n < 2; ++n) _Pragma("unroll") for (int k = 0; k < 2; ++k) dst[n][k] = *(const PG8_LAS bf16x8*)(lds + PG8_SB(b, h) + boff + n * 2048 + k * 1024); } while (0)
; #define PG8_MMA(ai, bj, At, Bt) do { __builtin_amdgcn_s_setprio(1); _Pragma("unroll") for (int m = 0; m < 4; ++m) _Pragma("unroll") for (int n = 0; n < 2; ++n) _Pragma("unroll") for (int k = 0; k < 2; ++k) \
;         acc[ai][bj][m][n] = __builtin_amdgcn_mfma_f32_16x16x32_bf16(Bt[n][k], At[m][k], acc[ai][bj][m][n], 0, 0, 0); __builtin_amdgcn_s_setprio(0); } while (0)
; #define PG8_WAIT_V(n) asm volatile("s_waitcnt vmcnt(" #n ")" ::: "memory")
; #define PG8_WAIT_L(n) asm volatile("s_waitcnt lgkmcnt(" #n ")" ::: "memory")
; #define PG8_BAR __builtin_amdgcn_s_barrier()
; #define PG8_SCHED __builtin_amdgcn_sched_barrier(0)
; template <class Epi, class Sched, bool ALIGN_EPI>
; __device__ __forceinline__ void gemm_phase(PG8_LAS unsigned char* lds, const Gemm g, const Sched& S, const Epi& E) {
;     ...
;             PG8_WAIT_V(8); PG8_WAIT_L(0); PG8_BAR; PG8_MMA(1, 0, At, B0); PG8_MMA(1, 1, At, B1); PG8_BAR; PG8_SCHED;
;             PG8_LDB(B0, 1, 0); PG8_LDB(B1, 1, 1); PG8_SCHED; PG8_LDA(At, 1, 0); PG8_STAGE(PG8_SA(0, 1), a2 + hstepA, voffA);
;             PG8_WAIT_V(8); PG8_WAIT_L(0); PG8_BAR; PG8_MMA(0, 0, At, B0); PG8_MMA(0, 1, At, B1); PG8_BAR; PG8_SCHED;
	s_setprio 1
	s_waitcnt lgkmcnt(0)
	v_mfma_f32_16x16x32_bf16 v[66:69], v[160:163], v[194:197], v[66:69]
	v_mfma_f32_16x16x32_bf16 v[66:69], v[164:167], v[198:201], v[66:69]
	v_mfma_f32_16x16x32_bf16 v[62:65], v[168:171], v[194:197], v[62:65]
	v_mfma_f32_16x16x32_bf16 v[62:65], v[174:177], v[198:201], v[62:65]
	v_mfma_f32_16x16x32_bf16 v[50:53], v[160:163], v[202:205], v[50:53]
	v_mfma_f32_16x16x32_bf16 v[50:53], v[164:167], v[206:209], v[50:53]
	v_mfma_f32_16x16x32_bf16 v[46:49], v[168:171], v[202:205], v[46:49]
	v_mfma_f32_16x16x32_bf16 v[46:49], v[174:177], v[206:209], v[46:49]
	v_mfma_f32_16x16x32_bf16 v[34:37], v[160:163], v[210:213], v[34:37]
	v_mfma_f32_16x16x32_bf16 v[34:37], v[164:167], v[214:217], v[34:37]
	v_mfma_f32_16x16x32_bf16 v[30:33], v[168:171], v[210:213], v[30:33]
	v_mfma_f32_16x16x32_bf16 v[30:33], v[174:177], v[214:217], v[30:33]
	v_mfma_f32_16x16x32_bf16 v[18:21], v[160:163], v[218:221], v[18:21]
	v_mfma_f32_16x16x32_bf16 v[18:21], v[164:167], v[222:225], v[18:21]
	v_mfma_f32_16x16x32_bf16 v[14:17], v[168:171], v[218:221], v[14:17]
	v_mfma_f32_16x16x32_bf16 v[14:17], v[174:177], v[222:225], v[14:17]
	s_setprio 0
	s_setprio 1
	v_mfma_f32_16x16x32_bf16 v[58:61], v[178:181], v[194:197], v[58:61]
	v_mfma_f32_16x16x32_bf16 v[54:57], v[186:189], v[194:197], v[54:57]
	v_mfma_f32_16x16x32_bf16 v[42:45], v[178:181], v[202:205], v[42:45]
	v_mfma_f32_16x16x32_bf16 v[38:41], v[186:189], v[202:205], v[38:41]
	v_mfma_f32_16x16x32_bf16 v[26:29], v[178:181], v[210:213], v[26:29]
	v_mfma_f32_16x16x32_bf16 v[22:25], v[186:189], v[210:213], v[22:25]
	v_mfma_f32_16x16x32_bf16 v[10:13], v[178:181], v[218:221], v[10:13]
	v_mfma_f32_16x16x32_bf16 v[4:7], v[186:189], v[218:221], v[6:9]
	v_mfma_f32_16x16x32_bf16 v[58:61], v[182:185], v[198:201], v[58:61]
	v_mfma_f32_16x16x32_bf16 v[54:57], v[190:193], v[198:201], v[54:57]
	v_mfma_f32_16x16x32_bf16 v[42:45], v[182:185], v[206:209], v[42:45]
	v_mfma_f32_16x16x32_bf16 v[38:41], v[190:193], v[206:209], v[38:41]
	v_mfma_f32_16x16x32_bf16 v[26:29], v[182:185], v[214:217], v[26:29]
	v_mfma_f32_16x16x32_bf16 v[22:25], v[190:193], v[214:217], v[22:25]
	v_mfma_f32_16x16x32_bf16 v[10:13], v[182:185], v[222:225], v[10:13]
	v_mfma_f32_16x16x32_bf16 v[4:7], v[190:193], v[222:225], v[4:7]
	s_setprio 0
	s_barrier
	s_add_i32 s2, 0, 0x18000
	v_add_u32_e32 v3, s2, v155
	s_add_i32 s63, 0, 0x1c000
	ds_read_b128 v[160:163], v3
	ds_read_b128 v[164:167], v3 offset:1024
	ds_read_b128 v[168:171], v3 offset:2048
	ds_read_b128 v[174:177], v3 offset:3072
	v_add_u32_e32 v3, s63, v155
	ds_read_b128 v[178:181], v3
	ds_read_b128 v[182:185], v3 offset:1024
	ds_read_b128 v[186:189], v3 offset:2048
	ds_read_b128 v[190:193], v3 offset:3072
	s_add_u32 s44, s44, 0x80000
	s_addc_u32 s45, s45, 0
	s_mov_b32 m0, s49
	v_lshl_add_u64 v[8:9], s[44:45], 0, v[134:135]
	ds_read_b128 v[194:197], v159 offset:32768
	ds_read_b128 v[198:201], v159 offset:33792
	ds_read_b128 v[202:205], v159 offset:34816
	ds_read_b128 v[206:209], v159 offset:35840
	ds_read_b128 v[210:213], v159 offset:36864
	ds_read_b128 v[214:217], v159 offset:37888
	ds_read_b128 v[218:221], v159 offset:38912
	ds_read_b128 v[222:225], v159 offset:39936
	global_load_lds_dwordx4 v[8:9], off
	v_lshl_add_u64 v[8:9], s[44:45], 0, v[138:139]
	s_mov_b32 m0, s50
	s_nop 0
	global_load_lds_dwordx4 v[8:9], off
	s_waitcnt vmcnt(8)
	s_waitcnt lgkmcnt(0)
	s_barrier
	s_setprio 1
	s_waitcnt lgkmcnt(0)
	v_mfma_f32_16x16x32_bf16 v[130:133], v[160:163], v[194:197], v[130:133]
	v_mfma_f32_16x16x32_bf16 v[130:133], v[164:167], v[198:201], v[130:133]
	v_mfma_f32_16x16x32_bf16 v[126:129], v[168:171], v[194:197], v[126:129]
	v_mfma_f32_16x16x32_bf16 v[126:129], v[174:177], v[198:201], v[126:129]
	v_mfma_f32_16x16x32_bf16 v[114:117], v[160:163], v[202:205], v[114:117]
	v_mfma_f32_16x16x32_bf16 v[114:117], v[164:167], v[206:209], v[114:117]
	v_mfma_f32_16x16x32_bf16 v[110:113], v[168:171], v[202:205], v[110:113]
	v_mfma_f32_16x16x32_bf16 v[110:113], v[174:177], v[206:209], v[110:113]
	v_mfma_f32_16x16x32_bf16 v[98:101], v[160:163], v[210:213], v[98:101]
	v_mfma_f32_16x16x32_bf16 v[98:101], v[164:167], v[214:217], v[98:101]
	v_mfma_f32_16x16x32_bf16 v[94:97], v[168:171], v[210:213], v[94:97]
	v_mfma_f32_16x16x32_bf16 v[94:97], v[174:177], v[214:217], v[94:97]
	v_mfma_f32_16x16x32_bf16 v[82:85], v[160:163], v[218:221], v[82:85]
	v_mfma_f32_16x16x32_bf16 v[82:85], v[164:167], v[222:225], v[82:85]
	v_mfma_f32_16x16x32_bf16 v[78:81], v[168:171], v[218:221], v[78:81]
	v_mfma_f32_16x16x32_bf16 v[78:81], v[174:177], v[222:225], v[78:81]
	s_setprio 0
	s_setprio 1
	v_mfma_f32_16x16x32_bf16 v[122:125], v[178:181], v[194:197], v[122:125]
	v_mfma_f32_16x16x32_bf16 v[122:125], v[182:185], v[198:201], v[122:125]
	v_mfma_f32_16x16x32_bf16 v[118:121], v[186:189], v[194:197], v[118:121]
	v_mfma_f32_16x16x32_bf16 v[118:121], v[190:193], v[198:201], v[118:121]
	v_mfma_f32_16x16x32_bf16 v[106:109], v[178:181], v[202:205], v[106:109]
	v_mfma_f32_16x16x32_bf16 v[106:109], v[182:185], v[206:209], v[106:109]
	v_mfma_f32_16x16x32_bf16 v[102:105], v[186:189], v[202:205], v[102:105]
	v_mfma_f32_16x16x32_bf16 v[102:105], v[190:193], v[206:209], v[102:105]
	v_mfma_f32_16x16x32_bf16 v[90:93], v[178:181], v[210:213], v[90:93]
	v_mfma_f32_16x16x32_bf16 v[90:93], v[182:185], v[214:217], v[90:93]
	v_mfma_f32_16x16x32_bf16 v[86:89], v[186:189], v[210:213], v[86:89]
	v_mfma_f32_16x16x32_bf16 v[86:89], v[190:193], v[214:217], v[86:89]
	v_mfma_f32_16x16x32_bf16 v[74:77], v[178:181], v[218:221], v[74:77]
	v_mfma_f32_16x16x32_bf16 v[74:77], v[182:185], v[222:225], v[74:77]
	v_mfma_f32_16x16x32_bf16 v[70:73], v[186:189], v[218:221], v[70:73]
	v_mfma_f32_16x16x32_bf16 v[70:73], v[190:193], v[222:225], v[70:73]
	s_setprio 0
	s_barrier
; #define PG8_STAGE(bufoff, gbase, voff) do { _Pragma("unroll") for (int _i = 0; _i < 2; ++_i) \
;         __builtin_amdgcn_global_load_lds((const unsigned*)((const char*)(gbase) + (voff)[_i]), (PG8_LAS unsigned*)(lds + (bufoff) + ldsw + _i * 8192), 16, 0, 0); } while (0)
; #define PG8_LDA(dst, b, h) do { _Pragma("unroll") for (int m = 0; m < 4; ++m) _Pragma("unroll") for (int k = 0; k < 2; ++k) dst[m][k] = *(const PG8_LAS bf16x8*)(lds + PG8_SA(b, h) + aoff + m * 2048 + k * 1024); } while (0)
; #define PG8_MMA(ai, bj, At, Bt) do { __builtin_amdgcn_s_setprio(1); _Pragma("unroll") for (int m = 0; m < 4; ++m) _Pragma("unroll") for (int n = 0; n < 2; ++n) _Pragma("unroll") for (int k = 0; k < 2; ++k) \
;         acc[ai][bj][m][n] = __builtin_amdgcn_mfma_f32_16x16x32_bf16(Bt[n][k], At[m][k], acc[ai][bj][m][n], 0, 0, 0); __builtin_amdgcn_s_setprio(0); } while (0)
; #define PG8_WAIT_V(n) asm volatile("s_waitcnt vmcnt(" #n ")" ::: "memory")
; #define PG8_WAIT_L(n) asm volatile("s_waitcnt lgkmcnt(" #n ")" ::: "memory")
; #define PG8_BAR __builtin_amdgcn_s_barrier()
; #define PG8_SCHED __builtin_amdgcn_sched_barrier(0)
; template <class Epi, class Sched, bool ALIGN_EPI>
; __device__ __forceinline__ void gemm_phase(PG8_LAS unsigned char* lds, const Gemm g, const Sched& S, const Epi& E) {
;     ...
;             if constexpr (Epi::MIDK) { if (t == (nt >> 1)) E.midk(acc, cur, wr, fr); }
;     ...
;             PG8_LDA(At, 1, 1); PG8_STAGE(PG8_SB(1, 0), b3, voffB); PG8_STAGE(PG8_SB(1, 1), b3 + hstepB, voffB); PG8_STAGE(PG8_SA(1, 0), a3, voffA);
;             PG8_WAIT_V(8); PG8_WAIT_L(0); PG8_BAR; PG8_MMA(1, 0, At, B0); PG8_MMA(1, 1, At, B1); PG8_BAR; PG8_SCHED;
;         }
	s_add_i32 s2, s2, s4
	v_lshl_add_u64 v[8:9], v[226:227], 0, s[16:17]
	s_mov_b32 m0, s2
	ds_read_b128 v[194:197], v159 offset:49152
	ds_read_b128 v[198:201], v159 offset:50176
	ds_read_b128 v[202:205], v159 offset:51200
	ds_read_b128 v[206:209], v159 offset:52224
	ds_read_b128 v[210:213], v159 offset:53248
	ds_read_b128 v[214:217], v159 offset:54272
	ds_read_b128 v[218:221], v159 offset:55296
	ds_read_b128 v[222:225], v159 offset:56320
	global_load_lds_dwordx4 v[8:9], off
	s_add_i32 m0, s2, 0x2000
	s_add_u32 s42, s42, 0x80080
	v_lshl_add_u64 v[8:9], v[228:229], 0, s[16:17]
	s_addc_u32 s43, s43, 0
	s_add_i32 s2, s63, s4
	global_load_lds_dwordx4 v[8:9], off
	v_lshl_add_u64 v[8:9], s[42:43], 0, v[136:137]
	s_mov_b32 m0, s2
	s_nop 0
	global_load_lds_dwordx4 v[8:9], off
	v_lshl_add_u64 v[8:9], s[42:43], 0, v[140:141]
	s_add_i32 m0, s2, 0x2000
	s_nop 0
	global_load_lds_dwordx4 v[8:9], off
	v_lshl_add_u64 v[8:9], v[230:231], 0, s[16:17]
	s_mov_b32 m0, s52
	s_nop 0
	global_load_lds_dwordx4 v[8:9], off
	v_lshl_add_u64 v[8:9], v[232:233], 0, s[16:17]
	s_mov_b32 m0, s53
	s_nop 0
	global_load_lds_dwordx4 v[8:9], off
	s_waitcnt vmcnt(8)
	s_waitcnt lgkmcnt(0)
	s_barrier
	s_setprio 1
	s_waitcnt lgkmcnt(0)
	v_mfma_f32_16x16x32_bf16 v[66:69], v[160:163], v[194:197], v[66:69]
	v_mfma_f32_16x16x32_bf16 v[66:69], v[164:167], v[198:201], v[66:69]
	v_mfma_f32_16x16x32_bf16 v[62:65], v[168:171], v[194:197], v[62:65]
	v_mfma_f32_16x16x32_bf16 v[62:65], v[174:177], v[198:201], v[62:65]
	v_mfma_f32_16x16x32_bf16 v[50:53], v[160:163], v[202:205], v[50:53]
	v_mfma_f32_16x16x32_bf16 v[50:53], v[164:167], v[206:209], v[50:53]
	v_mfma_f32_16x16x32_bf16 v[46:49], v[168:171], v[202:205], v[46:49]
	v_mfma_f32_16x16x32_bf16 v[46:49], v[174:177], v[206:209], v[46:49]
	v_mfma_f32_16x16x32_bf16 v[34:37], v[160:163], v[210:213], v[34:37]
	v_mfma_f32_16x16x32_bf16 v[34:37], v[164:167], v[214:217], v[34:37]
	v_mfma_f32_16x16x32_bf16 v[30:33], v[168:171], v[210:213], v[30:33]
	v_mfma_f32_16x16x32_bf16 v[30:33], v[174:177], v[214:217], v[30:33]
	v_mfma_f32_16x16x32_bf16 v[18:21], v[160:163], v[218:221], v[18:21]
	v_mfma_f32_16x16x32_bf16 v[18:21], v[164:167], v[222:225], v[18:21]
	v_mfma_f32_16x16x32_bf16 v[14:17], v[168:171], v[218:221], v[14:17]
	v_mfma_f32_16x16x32_bf16 v[14:17], v[174:177], v[222:225], v[14:17]
	s_setprio 0
	s_setprio 1
	v_mfma_f32_16x16x32_bf16 v[58:61], v[178:181], v[194:197], v[58:61]
	v_mfma_f32_16x16x32_bf16 v[54:57], v[186:189], v[194:197], v[54:57]
	v_mfma_f32_16x16x32_bf16 v[42:45], v[178:181], v[202:205], v[42:45]
	v_mfma_f32_16x16x32_bf16 v[38:41], v[186:189], v[202:205], v[38:41]
	v_mfma_f32_16x16x32_bf16 v[26:29], v[178:181], v[210:213], v[26:29]
	v_mfma_f32_16x16x32_bf16 v[22:25], v[186:189], v[210:213], v[22:25]
	v_mfma_f32_16x16x32_bf16 v[8:11], v[178:181], v[218:221], v[10:13]
	v_mfma_f32_16x16x32_bf16 v[4:7], v[186:189], v[218:221], v[4:7]
	v_mfma_f32_16x16x32_bf16 v[58:61], v[182:185], v[198:201], v[58:61]
	v_mfma_f32_16x16x32_bf16 v[54:57], v[190:193], v[198:201], v[54:57]
	v_mfma_f32_16x16x32_bf16 v[42:45], v[182:185], v[206:209], v[42:45]
	v_mfma_f32_16x16x32_bf16 v[38:41], v[190:193], v[206:209], v[38:41]
	v_mfma_f32_16x16x32_bf16 v[26:29], v[182:185], v[214:217], v[26:29]
	v_mfma_f32_16x16x32_bf16 v[22:25], v[190:193], v[214:217], v[22:25]
	v_mfma_f32_16x16x32_bf16 v[10:13], v[182:185], v[222:225], v[8:11]
	v_mfma_f32_16x16x32_bf16 v[6:9], v[190:193], v[222:225], v[4:7]
	s_setprio 0
	s_barrier
	s_add_i32 s62, s62, 2
	s_add_u32 s40, s40, 0x100
	s_addc_u32 s41, s41, 0
	s_cmp_gt_u32 s62, 29
	s_cbranch_scc1 .LBB0_842

; #define PG8_STAGE(bufoff, gbase, voff) do { _Pragma("unroll") for (int _i = 0; _i < 2; ++_i) \
;         __builtin_amdgcn_global_load_lds((const unsigned*)((const char*)(gbase) + (voff)[_i]), (PG8_LAS unsigned*)(lds + (bufoff) + ldsw + _i * 8192), 16, 0, 0); } while (0)
; #define PG8_LDA(dst, b, h) do { _Pragma("unroll") for (int m = 0; m < 4; ++m) _Pragma("unroll") for (int k = 0; k < 2; ++k) dst[m][k] = *(const PG8_LAS bf16x8*)(lds + PG8_SA(b, h) + aoff + m * 2048 + k * 1024); } while (0)
; #define PG8_LDB(dst, b, h) do { _Pragma("unroll") for (int n = 0; n < 2; ++n) _Pragma("unroll") for (int k = 0; k < 2; ++k) dst[n][k] = *(const PG8_LAS bf16x8*)(lds + PG8_SB(b, h) + boff + n * 2048 + k * 1024); } while (0)
; #define PG8_MMA(ai, bj, At, Bt) do { __builtin_amdgcn_s_setprio(1); _Pragma("unroll") for (int m = 0; m < 4; ++m) _Pragma("unroll") for (int n = 0; n < 2; ++n) _Pragma("unroll") for (int k = 0; k < 2; ++k) \
;         acc[ai][bj][m][n] = __builtin_amdgcn_mfma_f32_16x16x32_bf16(Bt[n][k], At[m][k], acc[ai][bj][m][n], 0, 0, 0); __builtin_amdgcn_s_setprio(0); } while (0)
; #define PG8_WAIT_V(n) asm volatile("s_waitcnt vmcnt(" #n ")" ::: "memory")
; #define PG8_WAIT_L(n) asm volatile("s_waitcnt lgkmcnt(" #n ")" ::: "memory")
; template <class Epi, class Sched, bool ALIGN_EPI>
; __device__ __forceinline__ void gemm_phase(PG8_LAS unsigned char* lds, const Gemm g, const Sched& S, const Epi& E) {
;     ...
;         for (int t = 0; t < nt; t += 2) {
;             if constexpr (Epi::MIDK) { if (t == (nt >> 1)) E.midk(acc, cur, wr, fr); }
;             const bool last = (t == nt - 2);
;             const char* a1 = cA + (size_t)(t + 1) * kstepA;
;             const char* a2 = last ? nA : cA + (size_t)(t + 2) * kstepA; const char* b2 = last ? nB : cB + (size_t)(t + 2) * kstep;
;             const char* a3 = a2 + kstepA; const char* b3 = b2 + kstep;
;             PG8_LDB(B0, 0, 0); PG8_LDB(B1, 0, 1); PG8_SCHED; PG8_LDA(At, 0, 0); PG8_STAGE(PG8_SA(1, 1), a1 + hstepA, voffA);
;             PG8_WAIT_V(8); PG8_WAIT_L(0); PG8_BAR; PG8_MMA(0, 0, At, B0); PG8_MMA(0, 1, At, B1); PG8_BAR; PG8_SCHED;
;             PG8_LDA(At, 0, 1); PG8_STAGE(PG8_SB(0, 0), b2, voffB); PG8_STAGE(PG8_SB(0, 1), b2 + hstepB, voffB); PG8_STAGE(PG8_SA(0, 0), a2, voffA);
;             PG8_WAIT_V(8); PG8_WAIT_L(0); PG8_BAR; PG8_MMA(1, 0, At, B0); PG8_MMA(1, 1, At, B1); PG8_BAR; PG8_SCHED;
.LBB0_901:
	ds_read_b128 v[156:159], v153
	ds_read_b128 v[160:163], v153 offset:1024
	ds_read_b128 v[164:167], v153 offset:2048
	ds_read_b128 v[168:171], v153 offset:3072
	ds_read_b128 v[174:177], v154
	ds_read_b128 v[178:181], v154 offset:1024
	ds_read_b128 v[182:185], v154 offset:2048
	ds_read_b128 v[186:189], v154 offset:3072
	s_add_u32 s2, s28, 0xfff80080
	s_addc_u32 s30, s29, -1
	s_cmp_eq_u32 s49, 28
	s_cselect_b32 s35, s23, s30
	s_cselect_b32 s34, s22, s2
	s_cselect_b32 s31, s25, s21
	s_cselect_b32 s30, s24, s19
	v_lshl_add_u64 v[222:223], s[28:29], 0, v[138:139]
	s_add_i32 m0, s27, 0xc000
	ds_read_b128 v[190:193], v155
	ds_read_b128 v[194:197], v155 offset:1024
	ds_read_b128 v[198:201], v155 offset:2048
	ds_read_b128 v[202:205], v155 offset:3072
	ds_read_b128 v[206:209], v155 offset:4096
	ds_read_b128 v[210:213], v155 offset:5120
	ds_read_b128 v[214:217], v155 offset:6144
	ds_read_b128 v[218:221], v155 offset:7168
	global_load_lds_dwordx4 v[222:223], off
	v_lshl_add_u64 v[222:223], s[28:29], 0, v[140:141]
	s_add_i32 m0, s27, 0xe000
	s_nop 0
	global_load_lds_dwordx4 v[222:223], off
	s_waitcnt vmcnt(8)
	s_waitcnt lgkmcnt(0)
	s_barrier
	s_setprio 1
	s_waitcnt lgkmcnt(0)
	v_mfma_f32_16x16x32_bf16 v[126:129], v[156:159], v[190:193], v[126:129]
	v_mfma_f32_16x16x32_bf16 v[126:129], v[160:163], v[194:197], v[126:129]
	v_mfma_f32_16x16x32_bf16 v[122:125], v[164:167], v[190:193], v[122:125]
	v_mfma_f32_16x16x32_bf16 v[122:125], v[168:171], v[194:197], v[122:125]
	v_mfma_f32_16x16x32_bf16 v[110:113], v[156:159], v[198:201], v[110:113]
	v_mfma_f32_16x16x32_bf16 v[110:113], v[160:163], v[202:205], v[110:113]
	v_mfma_f32_16x16x32_bf16 v[106:109], v[164:167], v[198:201], v[106:109]
	v_mfma_f32_16x16x32_bf16 v[106:109], v[168:171], v[202:205], v[106:109]
	v_mfma_f32_16x16x32_bf16 v[94:97], v[156:159], v[206:209], v[94:97]
	v_mfma_f32_16x16x32_bf16 v[94:97], v[160:163], v[210:213], v[94:97]
	v_mfma_f32_16x16x32_bf16 v[90:93], v[164:167], v[206:209], v[90:93]
	v_mfma_f32_16x16x32_bf16 v[90:93], v[168:171], v[210:213], v[90:93]
	v_mfma_f32_16x16x32_bf16 v[78:81], v[156:159], v[214:217], v[78:81]
	v_mfma_f32_16x16x32_bf16 v[78:81], v[160:163], v[218:221], v[78:81]
	v_mfma_f32_16x16x32_bf16 v[74:77], v[164:167], v[214:217], v[74:77]
	v_mfma_f32_16x16x32_bf16 v[74:77], v[168:171], v[218:221], v[74:77]
	s_setprio 0
	s_setprio 1
	v_mfma_f32_16x16x32_bf16 v[118:121], v[174:177], v[190:193], v[118:121]
	v_mfma_f32_16x16x32_bf16 v[118:121], v[178:181], v[194:197], v[118:121]
	v_mfma_f32_16x16x32_bf16 v[114:117], v[182:185], v[190:193], v[114:117]
	v_mfma_f32_16x16x32_bf16 v[114:117], v[186:189], v[194:197], v[114:117]
	v_mfma_f32_16x16x32_bf16 v[102:105], v[174:177], v[198:201], v[102:105]
	v_mfma_f32_16x16x32_bf16 v[102:105], v[178:181], v[202:205], v[102:105]
	v_mfma_f32_16x16x32_bf16 v[98:101], v[182:185], v[198:201], v[98:101]
	v_mfma_f32_16x16x32_bf16 v[98:101], v[186:189], v[202:205], v[98:101]
	v_mfma_f32_16x16x32_bf16 v[86:89], v[174:177], v[206:209], v[86:89]
	v_mfma_f32_16x16x32_bf16 v[86:89], v[178:181], v[210:213], v[86:89]
	v_mfma_f32_16x16x32_bf16 v[82:85], v[182:185], v[206:209], v[82:85]
	v_mfma_f32_16x16x32_bf16 v[82:85], v[186:189], v[210:213], v[82:85]
	v_mfma_f32_16x16x32_bf16 v[70:73], v[174:177], v[214:217], v[70:73]
	v_mfma_f32_16x16x32_bf16 v[70:73], v[178:181], v[218:221], v[70:73]
	v_mfma_f32_16x16x32_bf16 v[66:69], v[182:185], v[214:217], v[66:69]
	v_mfma_f32_16x16x32_bf16 v[66:69], v[186:189], v[218:221], v[66:69]
	s_setprio 0
	s_barrier
	s_add_i32 s2, s5, s3
	v_lshl_add_u64 v[222:223], s[30:31], 0, v[134:135]
	s_mov_b32 m0, s2
	ds_read_b128 v[190:193], v155 offset:16384
	ds_read_b128 v[194:197], v155 offset:17408
	ds_read_b128 v[198:201], v155 offset:18432
	ds_read_b128 v[202:205], v155 offset:19456
	ds_read_b128 v[206:209], v155 offset:20480
	ds_read_b128 v[210:213], v155 offset:21504
	ds_read_b128 v[214:217], v155 offset:22528
	ds_read_b128 v[218:221], v155 offset:23552
	global_load_lds_dwordx4 v[222:223], off
	s_add_i32 m0, s2, 0x2000
	s_add_u32 s50, s30, 0x80000
	v_lshl_add_u64 v[224:225], s[30:31], 0, v[130:131]
	s_addc_u32 s51, s31, 0
	s_add_i32 s2, s45, s3
	global_load_lds_dwordx4 v[224:225], off
	v_lshl_add_u64 v[226:227], s[50:51], 0, v[134:135]
	s_mov_b32 m0, s2
	v_lshl_add_u64 v[228:229], s[34:35], 0, v[132:133]
	global_load_lds_dwordx4 v[226:227], off
	v_lshl_add_u64 v[226:227], s[50:51], 0, v[130:131]
	s_add_i32 m0, s2, 0x2000
	s_nop 0
	global_load_lds_dwordx4 v[226:227], off
	v_lshl_add_u64 v[226:227], s[34:35], 0, v[136:137]
	s_mov_b32 m0, s27
	s_nop 0
	global_load_lds_dwordx4 v[226:227], off
	s_mov_b32 m0, s39
	s_nop 0
	global_load_lds_dwordx4 v[228:229], off
	s_waitcnt vmcnt(8)
	s_waitcnt lgkmcnt(0)
	s_barrier
; #define PG8_STAGE(bufoff, gbase, voff) do { _Pragma("unroll") for (int _i = 0; _i < 2; ++_i) \
;         __builtin_amdgcn_global_load_lds((const unsigned*)((const char*)(gbase) + (voff)[_i]), (PG8_LAS unsigned*)(lds + (bufoff) + ldsw + _i * 8192), 16, 0, 0); } while (0)
; #define PG8_LDA(dst, b, h) do { _Pragma("unroll") for (int m = 0; m < 4; ++m) _Pragma("unroll") for (int k = 0; k < 2; ++k) dst[m][k] = *(const PG8_LAS bf16x8*)(lds + PG8_SA(b, h) + aoff + m * 2048 + k * 1024); } while (0)
; #define PG8_LDB(dst, b, h) do { _Pragma("unroll") for (int n = 0; n < 2; ++n) _Pragma("unroll") for (int k = 0; k < 2; ++k) dst[n][k] = *(const PG8_LAS bf16x8*)(lds + PG8_SB(b, h) + boff + n * 2048 + k * 1024); } while (0)
; #define PG8_MMA(ai, bj, At, Bt) do { __builtin_amdgcn_s_setprio(1); _Pragma("unroll") for (int m = 0; m < 4; ++m) _Pragma("unroll") for (int n = 0; n < 2; ++n) _Pragma("unroll") for (int k = 0; k < 2; ++k) \
;         acc[ai][bj][m][n] = __builtin_amdgcn_mfma_f32_16x16x32_bf16(Bt[n][k], At[m][k], acc[ai][bj][m][n], 0, 0, 0); __builtin_amdgcn_s_setprio(0); } while (0)
; #define PG8_WAIT_V(n) asm volatile("s_waitcnt vmcnt(" #n ")" ::: "memory")
; #define PG8_WAIT_L(n) asm volatile("s_waitcnt lgkmcnt(" #n ")" ::: "memory")
; #define PG8_BAR __builtin_amdgcn_s_barrier()
; #define PG8_SCHED __builtin_amdgcn_sched_barrier(0)
; template <class Epi, class Sched, bool ALIGN_EPI>
; __device__ __forceinline__ void gemm_phase(PG8_LAS unsigned char* lds, const Gemm g, const Sched& S, const Epi& E) {
;     ...
;             PG8_WAIT_V(8); PG8_WAIT_L(0); PG8_BAR; PG8_MMA(1, 0, At, B0); PG8_MMA(1, 1, At, B1); PG8_BAR; PG8_SCHED;
;             PG8_LDB(B0, 1, 0); PG8_LDB(B1, 1, 1); PG8_SCHED; PG8_LDA(At, 1, 0); PG8_STAGE(PG8_SA(0, 1), a2 + hstepA, voffA);
;             PG8_WAIT_V(8); PG8_WAIT_L(0); PG8_BAR; PG8_MMA(0, 0, At, B0); PG8_MMA(0, 1, At, B1); PG8_BAR; PG8_SCHED;
	s_setprio 1
	s_waitcnt lgkmcnt(0)
	v_mfma_f32_16x16x32_bf16 v[62:65], v[156:159], v[190:193], v[62:65]
	v_mfma_f32_16x16x32_bf16 v[62:65], v[160:163], v[194:197], v[62:65]
	v_mfma_f32_16x16x32_bf16 v[58:61], v[164:167], v[190:193], v[58:61]
	v_mfma_f32_16x16x32_bf16 v[58:61], v[168:171], v[194:197], v[58:61]
	v_mfma_f32_16x16x32_bf16 v[46:49], v[156:159], v[198:201], v[46:49]
	v_mfma_f32_16x16x32_bf16 v[46:49], v[160:163], v[202:205], v[46:49]
	v_mfma_f32_16x16x32_bf16 v[42:45], v[164:167], v[198:201], v[42:45]
	v_mfma_f32_16x16x32_bf16 v[42:45], v[168:171], v[202:205], v[42:45]
	v_mfma_f32_16x16x32_bf16 v[30:33], v[156:159], v[206:209], v[30:33]
	v_mfma_f32_16x16x32_bf16 v[30:33], v[160:163], v[210:213], v[30:33]
	v_mfma_f32_16x16x32_bf16 v[26:29], v[164:167], v[206:209], v[26:29]
	v_mfma_f32_16x16x32_bf16 v[26:29], v[168:171], v[210:213], v[26:29]
	v_mfma_f32_16x16x32_bf16 v[14:17], v[156:159], v[214:217], v[14:17]
	v_mfma_f32_16x16x32_bf16 v[14:17], v[160:163], v[218:221], v[14:17]
	v_mfma_f32_16x16x32_bf16 v[10:13], v[164:167], v[214:217], v[10:13]
	v_mfma_f32_16x16x32_bf16 v[10:13], v[168:171], v[218:221], v[10:13]
	s_setprio 0
	s_setprio 1
	v_mfma_f32_16x16x32_bf16 v[54:57], v[174:177], v[190:193], v[54:57]
	v_mfma_f32_16x16x32_bf16 v[54:57], v[178:181], v[194:197], v[54:57]
	v_mfma_f32_16x16x32_bf16 v[50:53], v[182:185], v[190:193], v[50:53]
	v_mfma_f32_16x16x32_bf16 v[50:53], v[186:189], v[194:197], v[50:53]
	v_mfma_f32_16x16x32_bf16 v[38:41], v[174:177], v[198:201], v[38:41]
	v_mfma_f32_16x16x32_bf16 v[38:41], v[178:181], v[202:205], v[38:41]
	v_mfma_f32_16x16x32_bf16 v[34:37], v[182:185], v[198:201], v[34:37]
	v_mfma_f32_16x16x32_bf16 v[34:37], v[186:189], v[202:205], v[34:37]
	v_mfma_f32_16x16x32_bf16 v[22:25], v[174:177], v[206:209], v[22:25]
	v_mfma_f32_16x16x32_bf16 v[22:25], v[178:181], v[210:213], v[22:25]
	v_mfma_f32_16x16x32_bf16 v[18:21], v[182:185], v[206:209], v[18:21]
	v_mfma_f32_16x16x32_bf16 v[18:21], v[186:189], v[210:213], v[18:21]
	v_mfma_f32_16x16x32_bf16 v[6:9], v[174:177], v[214:217], v[6:9]
	v_mfma_f32_16x16x32_bf16 v[6:9], v[178:181], v[218:221], v[6:9]
	v_mfma_f32_16x16x32_bf16 v[2:5], v[182:185], v[214:217], v[2:5]
	v_mfma_f32_16x16x32_bf16 v[2:5], v[186:189], v[218:221], v[2:5]
	s_setprio 0
	s_barrier
	s_add_i32 s2, 0, 0x18000
	s_add_i32 s50, 0, 0x1c000
	v_add_u32_e32 v168, s2, v146
	v_add_u32_e32 v173, s50, v146
	ds_read_b128 v[156:159], v168
	ds_read_b128 v[160:163], v168 offset:1024
	ds_read_b128 v[164:167], v168 offset:2048
	ds_read_b128 v[168:171], v168 offset:3072
	ds_read_b128 v[174:177], v173
	ds_read_b128 v[178:181], v173 offset:1024
	ds_read_b128 v[182:185], v173 offset:2048
	ds_read_b128 v[186:189], v173 offset:3072
	s_add_u32 s34, s34, 0x80000
	s_addc_u32 s35, s35, 0
	s_mov_b32 m0, s40
	v_lshl_add_u64 v[230:231], s[34:35], 0, v[136:137]
	ds_read_b128 v[190:193], v155 offset:32768
	ds_read_b128 v[194:197], v155 offset:33792
	ds_read_b128 v[198:201], v155 offset:34816
	ds_read_b128 v[202:205], v155 offset:35840
	ds_read_b128 v[206:209], v155 offset:36864
	ds_read_b128 v[210:213], v155 offset:37888
	ds_read_b128 v[214:217], v155 offset:38912
	ds_read_b128 v[218:221], v155 offset:39936
	global_load_lds_dwordx4 v[230:231], off
	v_lshl_add_u64 v[230:231], s[34:35], 0, v[132:133]
	s_mov_b32 m0, s41
	s_nop 0
	global_load_lds_dwordx4 v[230:231], off
	s_waitcnt vmcnt(8)
	s_waitcnt lgkmcnt(0)
	s_barrier
	s_setprio 1
	s_waitcnt lgkmcnt(0)
	v_mfma_f32_16x16x32_bf16 v[126:129], v[156:159], v[190:193], v[126:129]
	v_mfma_f32_16x16x32_bf16 v[126:129], v[160:163], v[194:197], v[126:129]
	v_mfma_f32_16x16x32_bf16 v[122:125], v[164:167], v[190:193], v[122:125]
	v_mfma_f32_16x16x32_bf16 v[122:125], v[168:171], v[194:197], v[122:125]
	v_mfma_f32_16x16x32_bf16 v[110:113], v[156:159], v[198:201], v[110:113]
	v_mfma_f32_16x16x32_bf16 v[110:113], v[160:163], v[202:205], v[110:113]
	v_mfma_f32_16x16x32_bf16 v[106:109], v[164:167], v[198:201], v[106:109]
	v_mfma_f32_16x16x32_bf16 v[106:109], v[168:171], v[202:205], v[106:109]
	v_mfma_f32_16x16x32_bf16 v[94:97], v[156:159], v[206:209], v[94:97]
	v_mfma_f32_16x16x32_bf16 v[94:97], v[160:163], v[210:213], v[94:97]
	v_mfma_f32_16x16x32_bf16 v[90:93], v[164:167], v[206:209], v[90:93]
	v_mfma_f32_16x16x32_bf16 v[90:93], v[168:171], v[210:213], v[90:93]
	v_mfma_f32_16x16x32_bf16 v[78:81], v[156:159], v[214:217], v[78:81]
	v_mfma_f32_16x16x32_bf16 v[78:81], v[160:163], v[218:221], v[78:81]
	v_mfma_f32_16x16x32_bf16 v[74:77], v[164:167], v[214:217], v[74:77]
	v_mfma_f32_16x16x32_bf16 v[74:77], v[168:171], v[218:221], v[74:77]
	s_setprio 0
	s_setprio 1
	v_mfma_f32_16x16x32_bf16 v[118:121], v[174:177], v[190:193], v[118:121]
	v_mfma_f32_16x16x32_bf16 v[118:121], v[178:181], v[194:197], v[118:121]
	v_mfma_f32_16x16x32_bf16 v[114:117], v[182:185], v[190:193], v[114:117]
	v_mfma_f32_16x16x32_bf16 v[114:117], v[186:189], v[194:197], v[114:117]
	v_mfma_f32_16x16x32_bf16 v[102:105], v[174:177], v[198:201], v[102:105]
	v_mfma_f32_16x16x32_bf16 v[102:105], v[178:181], v[202:205], v[102:105]
	v_mfma_f32_16x16x32_bf16 v[98:101], v[182:185], v[198:201], v[98:101]
	v_mfma_f32_16x16x32_bf16 v[98:101], v[186:189], v[202:205], v[98:101]
	v_mfma_f32_16x16x32_bf16 v[86:89], v[174:177], v[206:209], v[86:89]
	v_mfma_f32_16x16x32_bf16 v[86:89], v[178:181], v[210:213], v[86:89]
	v_mfma_f32_16x16x32_bf16 v[82:85], v[182:185], v[206:209], v[82:85]
	v_mfma_f32_16x16x32_bf16 v[82:85], v[186:189], v[210:213], v[82:85]
	v_mfma_f32_16x16x32_bf16 v[70:73], v[174:177], v[214:217], v[70:73]
	v_mfma_f32_16x16x32_bf16 v[70:73], v[178:181], v[218:221], v[70:73]
	v_mfma_f32_16x16x32_bf16 v[66:69], v[182:185], v[214:217], v[66:69]
	v_mfma_f32_16x16x32_bf16 v[66:69], v[186:189], v[218:221], v[66:69]
	s_setprio 0
	s_barrier
; #define PG8_STAGE(bufoff, gbase, voff) do { _Pragma("unroll") for (int _i = 0; _i < 2; ++_i) \
;         __builtin_amdgcn_global_load_lds((const unsigned*)((const char*)(gbase) + (voff)[_i]), (PG8_LAS unsigned*)(lds + (bufoff) + ldsw + _i * 8192), 16, 0, 0); } while (0)
; #define PG8_LDA(dst, b, h) do { _Pragma("unroll") for (int m = 0; m < 4; ++m) _Pragma("unroll") for (int k = 0; k < 2; ++k) dst[m][k] = *(const PG8_LAS bf16x8*)(lds + PG8_SA(b, h) + aoff + m * 2048 + k * 1024); } while (0)
; #define PG8_MMA(ai, bj, At, Bt) do { __builtin_amdgcn_s_setprio(1); _Pragma("unroll") for (int m = 0; m < 4; ++m) _Pragma("unroll") for (int n = 0; n < 2; ++n) _Pragma("unroll") for (int k = 0; k < 2; ++k) \
;         acc[ai][bj][m][n] = __builtin_amdgcn_mfma_f32_16x16x32_bf16(Bt[n][k], At[m][k], acc[ai][bj][m][n], 0, 0, 0); __builtin_amdgcn_s_setprio(0); } while (0)
; #define PG8_WAIT_V(n) asm volatile("s_waitcnt vmcnt(" #n ")" ::: "memory")
; #define PG8_WAIT_L(n) asm volatile("s_waitcnt lgkmcnt(" #n ")" ::: "memory")
; #define PG8_BAR __builtin_amdgcn_s_barrier()
; #define PG8_SCHED __builtin_amdgcn_sched_barrier(0)
; template <class Epi, class Sched, bool ALIGN_EPI>
; __device__ __forceinline__ void gemm_phase(PG8_LAS unsigned char* lds, const Gemm g, const Sched& S, const Epi& E) {
;     ...
;             PG8_LDA(At, 1, 1); PG8_STAGE(PG8_SB(1, 0), b3, voffB); PG8_STAGE(PG8_SB(1, 1), b3 + hstepB, voffB); PG8_STAGE(PG8_SA(1, 0), a3, voffA);
;             PG8_WAIT_V(8); PG8_WAIT_L(0); PG8_BAR; PG8_MMA(1, 0, At, B0); PG8_MMA(1, 1, At, B1); PG8_BAR; PG8_SCHED;
;         }
;         if constexpr (ALIGN_EPI) { if (wr == 0) PG8_BAR; }
	s_add_i32 s2, s2, s3
	v_lshl_add_u64 v[222:223], v[222:223], 0, s[14:15]
	s_mov_b32 m0, s2
	ds_read_b128 v[190:193], v155 offset:49152
	ds_read_b128 v[194:197], v155 offset:50176
	ds_read_b128 v[198:201], v155 offset:51200
	ds_read_b128 v[202:205], v155 offset:52224
	ds_read_b128 v[206:209], v155 offset:53248
	ds_read_b128 v[210:213], v155 offset:54272
	ds_read_b128 v[214:217], v155 offset:55296
	ds_read_b128 v[218:221], v155 offset:56320
	global_load_lds_dwordx4 v[222:223], off
	s_add_i32 m0, s2, 0x2000
	s_add_u32 s30, s30, 0x80080
	v_lshl_add_u64 v[222:223], v[224:225], 0, s[14:15]
	s_addc_u32 s31, s31, 0
	s_add_i32 s2, s50, s3
	global_load_lds_dwordx4 v[222:223], off
	v_lshl_add_u64 v[222:223], s[30:31], 0, v[134:135]
	s_mov_b32 m0, s2
	s_nop 0
	global_load_lds_dwordx4 v[222:223], off
	v_lshl_add_u64 v[222:223], s[30:31], 0, v[130:131]
	s_add_i32 m0, s2, 0x2000
	s_nop 0
	global_load_lds_dwordx4 v[222:223], off
	v_lshl_add_u64 v[222:223], v[226:227], 0, s[14:15]
	s_mov_b32 m0, s43
	s_nop 0
	global_load_lds_dwordx4 v[222:223], off
	v_lshl_add_u64 v[222:223], v[228:229], 0, s[14:15]
	s_mov_b32 m0, s44
	s_nop 0
	global_load_lds_dwordx4 v[222:223], off
	s_waitcnt vmcnt(8)
	s_waitcnt lgkmcnt(0)
	s_barrier
	s_setprio 1
	s_waitcnt lgkmcnt(0)
	v_mfma_f32_16x16x32_bf16 v[62:65], v[156:159], v[190:193], v[62:65]
	v_mfma_f32_16x16x32_bf16 v[62:65], v[160:163], v[194:197], v[62:65]
	v_mfma_f32_16x16x32_bf16 v[58:61], v[164:167], v[190:193], v[58:61]
	v_mfma_f32_16x16x32_bf16 v[58:61], v[168:171], v[194:197], v[58:61]
	v_mfma_f32_16x16x32_bf16 v[46:49], v[156:159], v[198:201], v[46:49]
	v_mfma_f32_16x16x32_bf16 v[46:49], v[160:163], v[202:205], v[46:49]
	v_mfma_f32_16x16x32_bf16 v[42:45], v[164:167], v[198:201], v[42:45]
	v_mfma_f32_16x16x32_bf16 v[42:45], v[168:171], v[202:205], v[42:45]
	v_mfma_f32_16x16x32_bf16 v[30:33], v[156:159], v[206:209], v[30:33]
	v_mfma_f32_16x16x32_bf16 v[30:33], v[160:163], v[210:213], v[30:33]
	v_mfma_f32_16x16x32_bf16 v[26:29], v[164:167], v[206:209], v[26:29]
	v_mfma_f32_16x16x32_bf16 v[26:29], v[168:171], v[210:213], v[26:29]
	v_mfma_f32_16x16x32_bf16 v[14:17], v[156:159], v[214:217], v[14:17]
	v_mfma_f32_16x16x32_bf16 v[14:17], v[160:163], v[218:221], v[14:17]
	v_mfma_f32_16x16x32_bf16 v[10:13], v[164:167], v[214:217], v[10:13]
	v_mfma_f32_16x16x32_bf16 v[10:13], v[168:171], v[218:221], v[10:13]
	s_setprio 0
	s_setprio 1
	v_mfma_f32_16x16x32_bf16 v[54:57], v[174:177], v[190:193], v[54:57]
	v_mfma_f32_16x16x32_bf16 v[54:57], v[178:181], v[194:197], v[54:57]
	v_mfma_f32_16x16x32_bf16 v[50:53], v[182:185], v[190:193], v[50:53]
	v_mfma_f32_16x16x32_bf16 v[50:53], v[186:189], v[194:197], v[50:53]
	v_mfma_f32_16x16x32_bf16 v[38:41], v[174:177], v[198:201], v[38:41]
	v_mfma_f32_16x16x32_bf16 v[38:41], v[178:181], v[202:205], v[38:41]
	v_mfma_f32_16x16x32_bf16 v[34:37], v[182:185], v[198:201], v[34:37]
	v_mfma_f32_16x16x32_bf16 v[34:37], v[186:189], v[202:205], v[34:37]
	v_mfma_f32_16x16x32_bf16 v[22:25], v[174:177], v[206:209], v[22:25]
	v_mfma_f32_16x16x32_bf16 v[22:25], v[178:181], v[210:213], v[22:25]
	v_mfma_f32_16x16x32_bf16 v[18:21], v[182:185], v[206:209], v[18:21]
	v_mfma_f32_16x16x32_bf16 v[18:21], v[186:189], v[210:213], v[18:21]
	v_mfma_f32_16x16x32_bf16 v[6:9], v[174:177], v[214:217], v[6:9]
	v_mfma_f32_16x16x32_bf16 v[6:9], v[178:181], v[218:221], v[6:9]
	v_mfma_f32_16x16x32_bf16 v[2:5], v[182:185], v[214:217], v[2:5]
	v_mfma_f32_16x16x32_bf16 v[2:5], v[186:189], v[218:221], v[2:5]
	s_setprio 0
	s_barrier
	s_add_i32 s49, s49, 2
	s_add_u32 s28, s28, 0x100
	s_addc_u32 s29, s29, 0
	s_add_u32 s19, s19, 0x100
	s_addc_u32 s21, s21, 0
	s_cmp_gt_u32 s49, 29
	s_cbranch_scc0 .LBB0_901
	s_and_b64 vcc, exec, s[16:17]
	s_cbranch_vccz .LBB0_904
	s_barrier

; #define PG8_STAGE(bufoff, gbase, voff) do { _Pragma("unroll") for (int _i = 0; _i < 2; ++_i) \
;         __builtin_amdgcn_global_load_lds((const unsigned*)((const char*)(gbase) + (voff)[_i]), (PG8_LAS unsigned*)(lds + (bufoff) + ldsw + _i * 8192), 16, 0, 0); } while (0)
; #define PG8_LDA(dst, b, h) do { _Pragma("unroll") for (int m = 0; m < 4; ++m) _Pragma("unroll") for (int k = 0; k < 2; ++k) dst[m][k] = *(const PG8_LAS bf16x8*)(lds + PG8_SA(b, h) + aoff + m * 2048 + k * 1024); } while (0)
; #define PG8_LDB(dst, b, h) do { _Pragma("unroll") for (int n = 0; n < 2; ++n) _Pragma("unroll") for (int k = 0; k < 2; ++k) dst[n][k] = *(const PG8_LAS bf16x8*)(lds + PG8_SB(b, h) + boff + n * 2048 + k * 1024); } while (0)
; #define PG8_MMA(ai, bj, At, Bt) do { __builtin_amdgcn_s_setprio(1); _Pragma("unroll") for (int m = 0; m < 4; ++m) _Pragma("unroll") for (int n = 0; n < 2; ++n) _Pragma("unroll") for (int k = 0; k < 2; ++k) \
;         acc[ai][bj][m][n] = __builtin_amdgcn_mfma_f32_16x16x32_bf16(Bt[n][k], At[m][k], acc[ai][bj][m][n], 0, 0, 0); __builtin_amdgcn_s_setprio(0); } while (0)
; #define PG8_WAIT_V(n) asm volatile("s_waitcnt vmcnt(" #n ")" ::: "memory")
; #define PG8_WAIT_L(n) asm volatile("s_waitcnt lgkmcnt(" #n ")" ::: "memory")
; #define PG8_BAR __builtin_amdgcn_s_barrier()
; #define PG8_SCHED __builtin_amdgcn_sched_barrier(0)
; template <class Epi, class Sched, bool ALIGN_EPI>
; __device__ __forceinline__ void gemm_phase(PG8_LAS unsigned char* lds, const Gemm g, const Sched& S, const Epi& E) {
;     ...
;             PG8_LDB(B0, 0, 0); PG8_LDB(B1, 0, 1); PG8_SCHED; PG8_LDA(At, 0, 0); PG8_STAGE(PG8_SA(1, 1), a1 + hstepA, voffA);
;             PG8_WAIT_V(8); PG8_WAIT_L(0); PG8_BAR; PG8_MMA(0, 0, At, B0); PG8_MMA(0, 1, At, B1); PG8_BAR; PG8_SCHED;
;             PG8_LDA(At, 0, 1); PG8_STAGE(PG8_SB(0, 0), b2, voffB); PG8_STAGE(PG8_SB(0, 1), b2 + hstepB, voffB); PG8_STAGE(PG8_SA(0, 0), a2, voffA);
;             PG8_WAIT_V(8); PG8_WAIT_L(0); PG8_BAR; PG8_MMA(1, 0, At, B0); PG8_MMA(1, 1, At, B1); PG8_BAR; PG8_SCHED;
.LBB0_948:
	ds_read_b128 v[158:161], v155
	ds_read_b128 v[162:165], v155 offset:1024
	ds_read_b128 v[166:169], v155 offset:2048
	ds_read_b128 v[174:177], v155 offset:3072
	ds_read_b128 v[178:181], v156
	ds_read_b128 v[182:185], v156 offset:1024
	ds_read_b128 v[186:189], v156 offset:2048
	ds_read_b128 v[190:193], v156 offset:3072
	s_add_u32 s28, s26, 0x100
	s_addc_u32 s29, s27, 0
	s_cmpk_eq_i32 s59, 0x54
	s_cselect_b32 s35, s7, s29
	s_cselect_b32 s34, s6, s28
	s_cselect_b32 s31, s25, s58
	s_cselect_b32 s30, s24, s57
	v_lshl_add_u64 v[146:147], s[26:27], 0, v[138:139]
	s_add_i32 m0, s37, 0xc000
	ds_read_b128 v[194:197], v157
	ds_read_b128 v[198:201], v157 offset:1024
	ds_read_b128 v[202:205], v157 offset:2048
	ds_read_b128 v[206:209], v157 offset:3072
	ds_read_b128 v[210:213], v157 offset:4096
	ds_read_b128 v[214:217], v157 offset:5120
	ds_read_b128 v[218:221], v157 offset:6144
	ds_read_b128 v[222:225], v157 offset:7168
	global_load_lds_dwordx4 v[146:147], off
	v_lshl_add_u64 v[146:147], s[26:27], 0, v[140:141]
	s_add_i32 m0, s37, 0xe000
	s_nop 0
	global_load_lds_dwordx4 v[146:147], off
	s_waitcnt vmcnt(8)
	s_waitcnt lgkmcnt(0)
	s_barrier
	s_setprio 1
	s_waitcnt lgkmcnt(0)
	v_mfma_f32_16x16x32_bf16 v[126:129], v[158:161], v[194:197], v[126:129]
	v_mfma_f32_16x16x32_bf16 v[126:129], v[162:165], v[198:201], v[126:129]
	v_mfma_f32_16x16x32_bf16 v[122:125], v[166:169], v[194:197], v[122:125]
	v_mfma_f32_16x16x32_bf16 v[122:125], v[174:177], v[198:201], v[122:125]
	v_mfma_f32_16x16x32_bf16 v[118:121], v[158:161], v[202:205], v[118:121]
	v_mfma_f32_16x16x32_bf16 v[118:121], v[162:165], v[206:209], v[118:121]
	v_mfma_f32_16x16x32_bf16 v[110:113], v[166:169], v[202:205], v[110:113]
	v_mfma_f32_16x16x32_bf16 v[110:113], v[174:177], v[206:209], v[110:113]
	v_mfma_f32_16x16x32_bf16 v[102:105], v[158:161], v[210:213], v[102:105]
	v_mfma_f32_16x16x32_bf16 v[102:105], v[162:165], v[214:217], v[102:105]
	v_mfma_f32_16x16x32_bf16 v[94:97], v[166:169], v[210:213], v[94:97]
	v_mfma_f32_16x16x32_bf16 v[94:97], v[174:177], v[214:217], v[94:97]
	v_mfma_f32_16x16x32_bf16 v[86:89], v[158:161], v[218:221], v[86:89]
	v_mfma_f32_16x16x32_bf16 v[86:89], v[162:165], v[222:225], v[86:89]
	v_mfma_f32_16x16x32_bf16 v[78:81], v[166:169], v[218:221], v[78:81]
	v_mfma_f32_16x16x32_bf16 v[78:81], v[174:177], v[222:225], v[78:81]
	s_setprio 0
	s_setprio 1
	v_mfma_f32_16x16x32_bf16 v[114:117], v[178:181], v[194:197], v[114:117]
	v_mfma_f32_16x16x32_bf16 v[114:117], v[182:185], v[198:201], v[114:117]
	v_mfma_f32_16x16x32_bf16 v[106:109], v[186:189], v[194:197], v[106:109]
	v_mfma_f32_16x16x32_bf16 v[106:109], v[190:193], v[198:201], v[106:109]
	v_mfma_f32_16x16x32_bf16 v[98:101], v[178:181], v[202:205], v[98:101]
	v_mfma_f32_16x16x32_bf16 v[98:101], v[182:185], v[206:209], v[98:101]
	v_mfma_f32_16x16x32_bf16 v[90:93], v[186:189], v[202:205], v[90:93]
	v_mfma_f32_16x16x32_bf16 v[90:93], v[190:193], v[206:209], v[90:93]
	v_mfma_f32_16x16x32_bf16 v[82:85], v[178:181], v[210:213], v[82:85]
	v_mfma_f32_16x16x32_bf16 v[82:85], v[182:185], v[214:217], v[82:85]
	v_mfma_f32_16x16x32_bf16 v[74:77], v[186:189], v[210:213], v[74:77]
	v_mfma_f32_16x16x32_bf16 v[74:77], v[190:193], v[214:217], v[74:77]
	v_mfma_f32_16x16x32_bf16 v[70:73], v[178:181], v[218:221], v[70:73]
	v_mfma_f32_16x16x32_bf16 v[70:73], v[182:185], v[222:225], v[70:73]
	v_mfma_f32_16x16x32_bf16 v[66:69], v[186:189], v[218:221], v[66:69]
	v_mfma_f32_16x16x32_bf16 v[66:69], v[190:193], v[222:225], v[66:69]
	s_setprio 0
	s_barrier
	s_add_i32 s2, s47, s36
	v_lshl_add_u64 v[146:147], s[30:31], 0, v[132:133]
	s_mov_b32 m0, s2
	ds_read_b128 v[194:197], v157 offset:16384
	ds_read_b128 v[198:201], v157 offset:17408
	ds_read_b128 v[202:205], v157 offset:18432
	ds_read_b128 v[206:209], v157 offset:19456
	ds_read_b128 v[210:213], v157 offset:20480
	ds_read_b128 v[214:217], v157 offset:21504
	ds_read_b128 v[218:221], v157 offset:22528
	ds_read_b128 v[222:225], v157 offset:23552
	global_load_lds_dwordx4 v[146:147], off
	s_add_i32 m0, s2, 0x2000
	s_add_u32 s26, s30, 0x160000
	v_lshl_add_u64 v[170:171], s[30:31], 0, v[136:137]
	s_addc_u32 s27, s31, 0
	s_add_i32 s2, s48, s36
	global_load_lds_dwordx4 v[170:171], off
	v_lshl_add_u64 v[226:227], s[26:27], 0, v[132:133]
	s_mov_b32 m0, s2
	v_lshl_add_u64 v[228:229], s[34:35], 0, v[134:135]
	global_load_lds_dwordx4 v[226:227], off
	v_lshl_add_u64 v[226:227], s[26:27], 0, v[136:137]
	s_add_i32 m0, s2, 0x2000
	s_nop 0
	global_load_lds_dwordx4 v[226:227], off
	v_lshl_add_u64 v[226:227], s[34:35], 0, v[130:131]
	s_mov_b32 m0, s37
	s_nop 0
	global_load_lds_dwordx4 v[226:227], off
	s_mov_b32 m0, s39
	s_nop 0
	global_load_lds_dwordx4 v[228:229], off
	s_waitcnt vmcnt(8)
	s_waitcnt lgkmcnt(0)
	s_barrier
; #define PG8_STAGE(bufoff, gbase, voff) do { _Pragma("unroll") for (int _i = 0; _i < 2; ++_i) \
;         __builtin_amdgcn_global_load_lds((const unsigned*)((const char*)(gbase) + (voff)[_i]), (PG8_LAS unsigned*)(lds + (bufoff) + ldsw + _i * 8192), 16, 0, 0); } while (0)
; #define PG8_LDA(dst, b, h) do { _Pragma("unroll") for (int m = 0; m < 4; ++m) _Pragma("unroll") for (int k = 0; k < 2; ++k) dst[m][k] = *(const PG8_LAS bf16x8*)(lds + PG8_SA(b, h) + aoff + m * 2048 + k * 1024); } while (0)
; #define PG8_LDB(dst, b, h) do { _Pragma("unroll") for (int n = 0; n < 2; ++n) _Pragma("unroll") for (int k = 0; k < 2; ++k) dst[n][k] = *(const PG8_LAS bf16x8*)(lds + PG8_SB(b, h) + boff + n * 2048 + k * 1024); } while (0)
; #define PG8_MMA(ai, bj, At, Bt) do { __builtin_amdgcn_s_setprio(1); _Pragma("unroll") for (int m = 0; m < 4; ++m) _Pragma("unroll") for (int n = 0; n < 2; ++n) _Pragma("unroll") for (int k = 0; k < 2; ++k) \
;         acc[ai][bj][m][n] = __builtin_amdgcn_mfma_f32_16x16x32_bf16(Bt[n][k], At[m][k], acc[ai][bj][m][n], 0, 0, 0); __builtin_amdgcn_s_setprio(0); } while (0)
; #define PG8_WAIT_V(n) asm volatile("s_waitcnt vmcnt(" #n ")" ::: "memory")
; #define PG8_WAIT_L(n) asm volatile("s_waitcnt lgkmcnt(" #n ")" ::: "memory")
; #define PG8_BAR __builtin_amdgcn_s_barrier()
; #define PG8_SCHED __builtin_amdgcn_sched_barrier(0)
; template <class Epi, class Sched, bool ALIGN_EPI>
; __device__ __forceinline__ void gemm_phase(PG8_LAS unsigned char* lds, const Gemm g, const Sched& S, const Epi& E) {
;     ...
;             PG8_WAIT_V(8); PG8_WAIT_L(0); PG8_BAR; PG8_MMA(1, 0, At, B0); PG8_MMA(1, 1, At, B1); PG8_BAR; PG8_SCHED;
;             PG8_LDB(B0, 1, 0); PG8_LDB(B1, 1, 1); PG8_SCHED; PG8_LDA(At, 1, 0); PG8_STAGE(PG8_SA(0, 1), a2 + hstepA, voffA);
;             PG8_WAIT_V(8); PG8_WAIT_L(0); PG8_BAR; PG8_MMA(0, 0, At, B0); PG8_MMA(0, 1, At, B1); PG8_BAR; PG8_SCHED;
	s_setprio 1
	s_waitcnt lgkmcnt(0)
	v_mfma_f32_16x16x32_bf16 v[62:65], v[158:161], v[194:197], v[62:65]
	v_mfma_f32_16x16x32_bf16 v[62:65], v[162:165], v[198:201], v[62:65]
	v_mfma_f32_16x16x32_bf16 v[58:61], v[166:169], v[194:197], v[58:61]
	v_mfma_f32_16x16x32_bf16 v[58:61], v[174:177], v[198:201], v[58:61]
	v_mfma_f32_16x16x32_bf16 v[54:57], v[158:161], v[202:205], v[54:57]
	v_mfma_f32_16x16x32_bf16 v[54:57], v[162:165], v[206:209], v[54:57]
	v_mfma_f32_16x16x32_bf16 v[46:49], v[166:169], v[202:205], v[46:49]
	v_mfma_f32_16x16x32_bf16 v[46:49], v[174:177], v[206:209], v[46:49]
	v_mfma_f32_16x16x32_bf16 v[38:41], v[158:161], v[210:213], v[38:41]
	v_mfma_f32_16x16x32_bf16 v[38:41], v[162:165], v[214:217], v[38:41]
	v_mfma_f32_16x16x32_bf16 v[30:33], v[166:169], v[210:213], v[30:33]
	v_mfma_f32_16x16x32_bf16 v[30:33], v[174:177], v[214:217], v[30:33]
	v_mfma_f32_16x16x32_bf16 v[22:25], v[158:161], v[218:221], v[22:25]
	v_mfma_f32_16x16x32_bf16 v[22:25], v[162:165], v[222:225], v[22:25]
	v_mfma_f32_16x16x32_bf16 v[14:17], v[166:169], v[218:221], v[14:17]
	v_mfma_f32_16x16x32_bf16 v[14:17], v[174:177], v[222:225], v[14:17]
	s_setprio 0
	s_setprio 1
	v_mfma_f32_16x16x32_bf16 v[50:53], v[178:181], v[194:197], v[50:53]
	v_mfma_f32_16x16x32_bf16 v[50:53], v[182:185], v[198:201], v[50:53]
	v_mfma_f32_16x16x32_bf16 v[42:45], v[186:189], v[194:197], v[42:45]
	v_mfma_f32_16x16x32_bf16 v[42:45], v[190:193], v[198:201], v[42:45]
	v_mfma_f32_16x16x32_bf16 v[34:37], v[178:181], v[202:205], v[34:37]
	v_mfma_f32_16x16x32_bf16 v[34:37], v[182:185], v[206:209], v[34:37]
	v_mfma_f32_16x16x32_bf16 v[26:29], v[186:189], v[202:205], v[26:29]
	v_mfma_f32_16x16x32_bf16 v[26:29], v[190:193], v[206:209], v[26:29]
	v_mfma_f32_16x16x32_bf16 v[18:21], v[178:181], v[210:213], v[18:21]
	v_mfma_f32_16x16x32_bf16 v[18:21], v[182:185], v[214:217], v[18:21]
	v_mfma_f32_16x16x32_bf16 v[10:13], v[186:189], v[210:213], v[10:13]
	v_mfma_f32_16x16x32_bf16 v[10:13], v[190:193], v[214:217], v[10:13]
	v_mfma_f32_16x16x32_bf16 v[6:9], v[178:181], v[218:221], v[6:9]
	v_mfma_f32_16x16x32_bf16 v[6:9], v[182:185], v[222:225], v[6:9]
	v_mfma_f32_16x16x32_bf16 v[2:5], v[186:189], v[218:221], v[2:5]
	v_mfma_f32_16x16x32_bf16 v[2:5], v[190:193], v[222:225], v[2:5]
	s_setprio 0
	s_barrier
	s_add_i32 s2, 0, 0x18000
	v_add_u32_e32 v173, s2, v153
	s_add_i32 s60, 0, 0x1c000
	ds_read_b128 v[158:161], v173
	ds_read_b128 v[162:165], v173 offset:1024
	ds_read_b128 v[166:169], v173 offset:2048
	ds_read_b128 v[174:177], v173 offset:3072
	v_add_u32_e32 v173, s60, v153
	ds_read_b128 v[178:181], v173
	ds_read_b128 v[182:185], v173 offset:1024
	ds_read_b128 v[186:189], v173 offset:2048
	ds_read_b128 v[190:193], v173 offset:3072
	s_add_u32 s26, s34, 0x160000
	s_addc_u32 s27, s35, 0
	s_mov_b32 m0, s40
	v_lshl_add_u64 v[230:231], s[26:27], 0, v[130:131]
	ds_read_b128 v[194:197], v157 offset:32768
	ds_read_b128 v[198:201], v157 offset:33792
	ds_read_b128 v[202:205], v157 offset:34816
	ds_read_b128 v[206:209], v157 offset:35840
	ds_read_b128 v[210:213], v157 offset:36864
	ds_read_b128 v[214:217], v157 offset:37888
	ds_read_b128 v[218:221], v157 offset:38912
	ds_read_b128 v[222:225], v157 offset:39936
	global_load_lds_dwordx4 v[230:231], off
	v_lshl_add_u64 v[230:231], s[26:27], 0, v[134:135]
	s_mov_b32 m0, s41
	s_nop 0
	global_load_lds_dwordx4 v[230:231], off
	s_waitcnt vmcnt(8)
	s_waitcnt lgkmcnt(0)
	s_barrier
	s_setprio 1
	s_waitcnt lgkmcnt(0)
	v_mfma_f32_16x16x32_bf16 v[126:129], v[158:161], v[194:197], v[126:129]
	v_mfma_f32_16x16x32_bf16 v[126:129], v[162:165], v[198:201], v[126:129]
	v_mfma_f32_16x16x32_bf16 v[122:125], v[166:169], v[194:197], v[122:125]
	v_mfma_f32_16x16x32_bf16 v[122:125], v[174:177], v[198:201], v[122:125]
	v_mfma_f32_16x16x32_bf16 v[118:121], v[158:161], v[202:205], v[118:121]
	v_mfma_f32_16x16x32_bf16 v[118:121], v[162:165], v[206:209], v[118:121]
	v_mfma_f32_16x16x32_bf16 v[110:113], v[166:169], v[202:205], v[110:113]
	v_mfma_f32_16x16x32_bf16 v[110:113], v[174:177], v[206:209], v[110:113]
	v_mfma_f32_16x16x32_bf16 v[102:105], v[158:161], v[210:213], v[102:105]
	v_mfma_f32_16x16x32_bf16 v[102:105], v[162:165], v[214:217], v[102:105]
	v_mfma_f32_16x16x32_bf16 v[94:97], v[166:169], v[210:213], v[94:97]
	v_mfma_f32_16x16x32_bf16 v[94:97], v[174:177], v[214:217], v[94:97]
	v_mfma_f32_16x16x32_bf16 v[86:89], v[158:161], v[218:221], v[86:89]
	v_mfma_f32_16x16x32_bf16 v[86:89], v[162:165], v[222:225], v[86:89]
	v_mfma_f32_16x16x32_bf16 v[78:81], v[166:169], v[218:221], v[78:81]
	v_mfma_f32_16x16x32_bf16 v[78:81], v[174:177], v[222:225], v[78:81]
	s_setprio 0
	s_setprio 1
	v_mfma_f32_16x16x32_bf16 v[114:117], v[178:181], v[194:197], v[114:117]
	v_mfma_f32_16x16x32_bf16 v[114:117], v[182:185], v[198:201], v[114:117]
	v_mfma_f32_16x16x32_bf16 v[106:109], v[186:189], v[194:197], v[106:109]
	v_mfma_f32_16x16x32_bf16 v[106:109], v[190:193], v[198:201], v[106:109]
	v_mfma_f32_16x16x32_bf16 v[98:101], v[178:181], v[202:205], v[98:101]
	v_mfma_f32_16x16x32_bf16 v[98:101], v[182:185], v[206:209], v[98:101]
	v_mfma_f32_16x16x32_bf16 v[90:93], v[186:189], v[202:205], v[90:93]
	v_mfma_f32_16x16x32_bf16 v[90:93], v[190:193], v[206:209], v[90:93]
	v_mfma_f32_16x16x32_bf16 v[82:85], v[178:181], v[210:213], v[82:85]
	v_mfma_f32_16x16x32_bf16 v[82:85], v[182:185], v[214:217], v[82:85]
	v_mfma_f32_16x16x32_bf16 v[74:77], v[186:189], v[210:213], v[74:77]
	v_mfma_f32_16x16x32_bf16 v[74:77], v[190:193], v[214:217], v[74:77]
	v_mfma_f32_16x16x32_bf16 v[70:73], v[178:181], v[218:221], v[70:73]
	v_mfma_f32_16x16x32_bf16 v[70:73], v[182:185], v[222:225], v[70:73]
	v_mfma_f32_16x16x32_bf16 v[66:69], v[186:189], v[218:221], v[66:69]
	v_mfma_f32_16x16x32_bf16 v[66:69], v[190:193], v[222:225], v[66:69]
	s_setprio 0
	s_barrier
; #define PG8_STAGE(bufoff, gbase, voff) do { _Pragma("unroll") for (int _i = 0; _i < 2; ++_i) \
;         __builtin_amdgcn_global_load_lds((const unsigned*)((const char*)(gbase) + (voff)[_i]), (PG8_LAS unsigned*)(lds + (bufoff) + ldsw + _i * 8192), 16, 0, 0); } while (0)
; #define PG8_LDA(dst, b, h) do { _Pragma("unroll") for (int m = 0; m < 4; ++m) _Pragma("unroll") for (int k = 0; k < 2; ++k) dst[m][k] = *(const PG8_LAS bf16x8*)(lds + PG8_SA(b, h) + aoff + m * 2048 + k * 1024); } while (0)
; #define PG8_MMA(ai, bj, At, Bt) do { __builtin_amdgcn_s_setprio(1); _Pragma("unroll") for (int m = 0; m < 4; ++m) _Pragma("unroll") for (int n = 0; n < 2; ++n) _Pragma("unroll") for (int k = 0; k < 2; ++k) \
;         acc[ai][bj][m][n] = __builtin_amdgcn_mfma_f32_16x16x32_bf16(Bt[n][k], At[m][k], acc[ai][bj][m][n], 0, 0, 0); __builtin_amdgcn_s_setprio(0); } while (0)
; #define PG8_WAIT_V(n) asm volatile("s_waitcnt vmcnt(" #n ")" ::: "memory")
; #define PG8_WAIT_L(n) asm volatile("s_waitcnt lgkmcnt(" #n ")" ::: "memory")
; #define PG8_BAR __builtin_amdgcn_s_barrier()
; #define PG8_SCHED __builtin_amdgcn_sched_barrier(0)
; template <class Epi, class Sched, bool ALIGN_EPI>
; __device__ __forceinline__ void gemm_phase(PG8_LAS unsigned char* lds, const Gemm g, const Sched& S, const Epi& E) {
;     ...
;             PG8_LDA(At, 1, 1); PG8_STAGE(PG8_SB(1, 0), b3, voffB); PG8_STAGE(PG8_SB(1, 1), b3 + hstepB, voffB); PG8_STAGE(PG8_SA(1, 0), a3, voffA);
;             PG8_WAIT_V(8); PG8_WAIT_L(0); PG8_BAR; PG8_MMA(1, 0, At, B0); PG8_MMA(1, 1, At, B1); PG8_BAR; PG8_SCHED;
;         }
;         if constexpr (ALIGN_EPI) { if (wr == 0) PG8_BAR; }
	s_add_i32 s2, s2, s36
	v_lshl_add_u64 v[146:147], v[146:147], 0, s[12:13]
	s_mov_b32 m0, s2
	ds_read_b128 v[194:197], v157 offset:49152
	ds_read_b128 v[198:201], v157 offset:50176
	ds_read_b128 v[202:205], v157 offset:51200
	ds_read_b128 v[206:209], v157 offset:52224
	ds_read_b128 v[210:213], v157 offset:53248
	ds_read_b128 v[214:217], v157 offset:54272
	ds_read_b128 v[218:221], v157 offset:55296
	ds_read_b128 v[222:225], v157 offset:56320
	global_load_lds_dwordx4 v[146:147], off
	s_add_i32 m0, s2, 0x2000
	s_add_u32 s26, s30, 0x160080
	v_lshl_add_u64 v[146:147], v[170:171], 0, s[12:13]
	s_addc_u32 s27, s31, 0
	s_add_i32 s2, s60, s36
	global_load_lds_dwordx4 v[146:147], off
	v_lshl_add_u64 v[146:147], s[26:27], 0, v[132:133]
	s_mov_b32 m0, s2
	s_nop 0
	global_load_lds_dwordx4 v[146:147], off
	v_lshl_add_u64 v[146:147], s[26:27], 0, v[136:137]
	s_add_i32 m0, s2, 0x2000
	s_nop 0
	global_load_lds_dwordx4 v[146:147], off
	v_lshl_add_u64 v[146:147], v[226:227], 0, s[12:13]
	s_mov_b32 m0, s43
	s_nop 0
	global_load_lds_dwordx4 v[146:147], off
	v_lshl_add_u64 v[146:147], v[228:229], 0, s[12:13]
	s_mov_b32 m0, s44
	s_nop 0
	global_load_lds_dwordx4 v[146:147], off
	s_waitcnt vmcnt(8)
	s_waitcnt lgkmcnt(0)
	s_barrier
	s_setprio 1
	s_waitcnt lgkmcnt(0)
	v_mfma_f32_16x16x32_bf16 v[62:65], v[158:161], v[194:197], v[62:65]
	v_mfma_f32_16x16x32_bf16 v[62:65], v[162:165], v[198:201], v[62:65]
	v_mfma_f32_16x16x32_bf16 v[58:61], v[166:169], v[194:197], v[58:61]
	v_mfma_f32_16x16x32_bf16 v[58:61], v[174:177], v[198:201], v[58:61]
	v_mfma_f32_16x16x32_bf16 v[54:57], v[158:161], v[202:205], v[54:57]
	v_mfma_f32_16x16x32_bf16 v[54:57], v[162:165], v[206:209], v[54:57]
	v_mfma_f32_16x16x32_bf16 v[46:49], v[166:169], v[202:205], v[46:49]
	v_mfma_f32_16x16x32_bf16 v[46:49], v[174:177], v[206:209], v[46:49]
	v_mfma_f32_16x16x32_bf16 v[38:41], v[158:161], v[210:213], v[38:41]
	v_mfma_f32_16x16x32_bf16 v[38:41], v[162:165], v[214:217], v[38:41]
	v_mfma_f32_16x16x32_bf16 v[30:33], v[166:169], v[210:213], v[30:33]
	v_mfma_f32_16x16x32_bf16 v[30:33], v[174:177], v[214:217], v[30:33]
	v_mfma_f32_16x16x32_bf16 v[22:25], v[158:161], v[218:221], v[22:25]
	v_mfma_f32_16x16x32_bf16 v[22:25], v[162:165], v[222:225], v[22:25]
	v_mfma_f32_16x16x32_bf16 v[14:17], v[166:169], v[218:221], v[14:17]
	v_mfma_f32_16x16x32_bf16 v[14:17], v[174:177], v[222:225], v[14:17]
	s_setprio 0
	s_setprio 1
	v_mfma_f32_16x16x32_bf16 v[50:53], v[178:181], v[194:197], v[50:53]
	v_mfma_f32_16x16x32_bf16 v[50:53], v[182:185], v[198:201], v[50:53]
	v_mfma_f32_16x16x32_bf16 v[42:45], v[186:189], v[194:197], v[42:45]
	v_mfma_f32_16x16x32_bf16 v[42:45], v[190:193], v[198:201], v[42:45]
	v_mfma_f32_16x16x32_bf16 v[34:37], v[178:181], v[202:205], v[34:37]
	v_mfma_f32_16x16x32_bf16 v[34:37], v[182:185], v[206:209], v[34:37]
	v_mfma_f32_16x16x32_bf16 v[26:29], v[186:189], v[202:205], v[26:29]
	v_mfma_f32_16x16x32_bf16 v[26:29], v[190:193], v[206:209], v[26:29]
	v_mfma_f32_16x16x32_bf16 v[18:21], v[178:181], v[210:213], v[18:21]
	v_mfma_f32_16x16x32_bf16 v[18:21], v[182:185], v[214:217], v[18:21]
	v_mfma_f32_16x16x32_bf16 v[10:13], v[186:189], v[210:213], v[10:13]
	v_mfma_f32_16x16x32_bf16 v[10:13], v[190:193], v[214:217], v[10:13]
	v_mfma_f32_16x16x32_bf16 v[6:9], v[178:181], v[218:221], v[6:9]
	v_mfma_f32_16x16x32_bf16 v[6:9], v[182:185], v[222:225], v[6:9]
	v_mfma_f32_16x16x32_bf16 v[2:5], v[186:189], v[218:221], v[2:5]
	v_mfma_f32_16x16x32_bf16 v[2:5], v[190:193], v[222:225], v[2:5]
	s_setprio 0
	s_barrier
	s_add_i32 s59, s59, 2
	s_add_u32 s57, s57, 0x100
	s_addc_u32 s58, s58, 0
	s_cmpk_gt_u32 s59, 0x55
	s_mov_b64 s[26:27], s[28:29]
	s_cbranch_scc0 .LBB0_948
	s_and_b64 vcc, exec, s[14:15]
	s_cbranch_vccz .LBB0_951
	s_barrier
